# forward substitution of chunk prep rewritten on all 8 waves (one f32 column per thread), ada and pool GEMM epilogues load row-independent vectors once
# speedup vs baseline: 1.0545x; 1.0026x over previous
; #define PG8_STAGE(bufoff, gbase, voff) do { _Pragma("unroll") for (int _i = 0; _i < 2; ++_i) \
;         __builtin_amdgcn_global_load_lds((const unsigned*)((const char*)(gbase) + (voff)[_i]), (LAS unsigned*)(lds + (bufoff) + ldsw + _i * 8192), 16, 0, 0); } while (0)
; #define PG8_LDA(dst, b, h) do { _Pragma("unroll") for (int m = 0; m < 4; ++m) _Pragma("unroll") for (int k = 0; k < 2; ++k) dst[m][k] = *(const LAS bf16x8*)(lds + PG8_SA(b, h) + aoff + m * 2048 + k * 1024); } while (0)
; #define PG8_BAR __builtin_amdgcn_s_barrier()
; template <class Epi, class Sched>
; __device__ __forceinline__ void gemm_phase(LAS unsigned char* lds, const Gemm g, const Sched& S, const Epi& E) {
;     ...
;         for (int t = 0; t < nt; t += 2) {
;             const bool last = (t == nt - 2);
;             const char* a1 = cA + (size_t)(t + 1) * kstep;
;             const char* a2 = last ? nA : cA + (size_t)(t + 2) * kstep; const char* b2 = last ? nB : cB + (size_t)(t + 2) * kstep;
;             const char* a3 = a2 + kstep; const char* b3 = b2 + kstep;
;             PG8_LDB(B0, 0, 0); PG8_SCHED; PG8_LDA(At, 0, 0); PG8_STAGE(PG8_SA(1, 1), a1 + hstepA, voffA);
;             PG8_WAIT_L(8); PG8_BAR; PG8_WAIT_L(0); PG8_MMA(0, 0, At, B0); PG8_BAR; PG8_SCHED;
;             PG8_LDB(B1, 0, 1); PG8_STAGE(PG8_SB(0, 0), b2, voffB);
;             PG8_BAR; PG8_WAIT_L(0); if constexpr (!Epi::DIAG) PG8_MMA(0, 1, At, B1); PG8_BAR;
;             PG8_LDA(At, 0, 1); PG8_STAGE(PG8_SA(0, 0), a2, voffA);
;             PG8_BAR; PG8_WAIT_L(0); if constexpr (!Epi::DIAG) PG8_MMA(1, 0, At, B0); PG8_BAR; PG8_SCHED;
;             PG8_STAGE(PG8_SB(0, 1), b2 + hstepB, voffB);
;             PG8_WAIT_V(6); PG8_BAR; PG8_MMA(1, 1, At, B1); PG8_BAR;
;             PG8_LDB(B0, 1, 0); PG8_SCHED; PG8_LDA(At, 1, 0); PG8_STAGE(PG8_SA(0, 1), a2 + hstepA, voffA);
;             PG8_WAIT_L(8); PG8_BAR; PG8_WAIT_L(0); PG8_MMA(0, 0, At, B0); PG8_BAR; PG8_SCHED;
;             PG8_LDB(B1, 1, 1); PG8_STAGE(PG8_SB(1, 0), b3, voffB);
;             PG8_BAR; PG8_WAIT_L(0); if constexpr (!Epi::DIAG) PG8_MMA(0, 1, At, B1); PG8_BAR;
;             PG8_LDA(At, 1, 1); PG8_STAGE(PG8_SA(1, 0), a3, voffA);
;             PG8_BAR; PG8_WAIT_L(0); if constexpr (!Epi::DIAG) PG8_MMA(1, 0, At, B0); PG8_BAR; PG8_SCHED;
;             PG8_STAGE(PG8_SB(1, 1), b3 + hstepB, voffB);
;             PG8_WAIT_V(6); PG8_BAR; PG8_MMA(1, 1, At, B1); PG8_BAR;
.LBB0_299:
	s_add_u32 s16, s14, 0xf8800080
	ds_read_b128 v[96:99], v91
	ds_read_b128 v[100:103], v91 offset:1024
	ds_read_b128 v[104:107], v91 offset:2048
	ds_read_b128 v[108:111], v91 offset:3072
	s_addc_u32 s17, s15, -1
	s_cmp_lg_u32 s27, 28
	s_cselect_b32 s16, s16, 0
	s_cselect_b32 s17, s17, 0
	s_add_u32 s18, s8, s16
	s_addc_u32 s19, s9, s17
	s_add_u32 s16, s10, s16
	s_addc_u32 s17, s11, s17
	s_mov_b32 m0, s28
	v_lshl_add_u64 v[144:145], v[84:85], 0, s[14:15]
	ds_read_b128 v[112:115], v92
	ds_read_b128 v[116:119], v92 offset:1024
	ds_read_b128 v[120:123], v92 offset:2048
	ds_read_b128 v[124:127], v92 offset:3072
	ds_read_b128 v[128:131], v92 offset:4096
	ds_read_b128 v[132:135], v92 offset:5120
	ds_read_b128 v[136:139], v92 offset:6144
	ds_read_b128 v[140:143], v92 offset:7168
	global_load_lds_dwordx4 v[144:145], off
	v_lshl_add_u64 v[144:145], v[86:87], 0, s[14:15]
	s_mov_b32 m0, s29
	s_nop 0
	global_load_lds_dwordx4 v[144:145], off
	s_waitcnt lgkmcnt(8)
	s_barrier
	s_waitcnt lgkmcnt(0)
	s_setprio 1
	s_waitcnt lgkmcnt(0)
	v_mfma_f32_16x16x32_bf16 v[76:79], v[96:99], v[112:115], v[76:79]
	v_mfma_f32_16x16x32_bf16 v[72:75], v[104:107], v[112:115], v[72:75]
	v_mfma_f32_16x16x32_bf16 v[60:63], v[96:99], v[120:123], v[60:63]
	v_mfma_f32_16x16x32_bf16 v[56:59], v[104:107], v[120:123], v[56:59]
	v_mfma_f32_16x16x32_bf16 v[44:47], v[96:99], v[128:131], v[44:47]
	v_mfma_f32_16x16x32_bf16 v[40:43], v[104:107], v[128:131], v[40:43]
	v_mfma_f32_16x16x32_bf16 v[28:31], v[96:99], v[136:139], v[28:31]
	v_mfma_f32_16x16x32_bf16 v[24:27], v[104:107], v[136:139], v[24:27]
	v_mfma_f32_16x16x32_bf16 v[76:79], v[100:103], v[116:119], v[76:79]
	v_mfma_f32_16x16x32_bf16 v[72:75], v[108:111], v[116:119], v[72:75]
	v_mfma_f32_16x16x32_bf16 v[60:63], v[100:103], v[124:127], v[60:63]
	v_mfma_f32_16x16x32_bf16 v[56:59], v[108:111], v[124:127], v[56:59]
	v_mfma_f32_16x16x32_bf16 v[44:47], v[100:103], v[132:135], v[44:47]
	v_mfma_f32_16x16x32_bf16 v[40:43], v[108:111], v[132:135], v[40:43]
	v_mfma_f32_16x16x32_bf16 v[28:31], v[100:103], v[140:143], v[28:31]
	v_mfma_f32_16x16x32_bf16 v[24:27], v[108:111], v[140:143], v[24:27]
	s_setprio 0
	s_barrier
	s_mov_b32 m0, s30
	v_lshl_add_u64 v[162:163], s[16:17], 0, v[82:83]
	ds_read_b128 v[144:147], v93
	ds_read_b128 v[148:151], v93 offset:1024
	ds_read_b128 v[152:155], v93 offset:2048
	ds_read_b128 v[156:159], v93 offset:3072
	global_load_lds_dwordx4 v[162:163], off
	v_lshl_add_u64 v[164:165], s[16:17], 0, v[80:81]
	s_mov_b32 m0, s31
	s_nop 0
	global_load_lds_dwordx4 v[164:165], off
	s_barrier
	s_waitcnt lgkmcnt(0)
	s_setprio 1
	s_waitcnt lgkmcnt(0)
	v_mfma_f32_16x16x32_bf16 v[68:71], v[144:147], v[112:115], v[68:71]
	v_mfma_f32_16x16x32_bf16 v[64:67], v[152:155], v[112:115], v[64:67]
	v_mfma_f32_16x16x32_bf16 v[52:55], v[144:147], v[120:123], v[52:55]
	v_mfma_f32_16x16x32_bf16 v[48:51], v[152:155], v[120:123], v[48:51]
	v_mfma_f32_16x16x32_bf16 v[36:39], v[144:147], v[128:131], v[36:39]
	v_mfma_f32_16x16x32_bf16 v[32:35], v[152:155], v[128:131], v[32:35]
	v_mfma_f32_16x16x32_bf16 v[20:23], v[144:147], v[136:139], v[20:23]
	v_mfma_f32_16x16x32_bf16 v[16:19], v[152:155], v[136:139], v[16:19]
	v_mfma_f32_16x16x32_bf16 v[68:71], v[148:151], v[116:119], v[68:71]
	v_mfma_f32_16x16x32_bf16 v[64:67], v[156:159], v[116:119], v[64:67]
	v_mfma_f32_16x16x32_bf16 v[52:55], v[148:151], v[124:127], v[52:55]
	v_mfma_f32_16x16x32_bf16 v[48:51], v[156:159], v[124:127], v[48:51]
	v_mfma_f32_16x16x32_bf16 v[36:39], v[148:151], v[132:135], v[36:39]
	v_mfma_f32_16x16x32_bf16 v[32:35], v[156:159], v[132:135], v[32:35]
	v_mfma_f32_16x16x32_bf16 v[20:23], v[148:151], v[140:143], v[20:23]
	v_mfma_f32_16x16x32_bf16 v[16:19], v[156:159], v[140:143], v[16:19]
	s_setprio 0
	s_mov_b32 m0, s20
	v_lshl_add_u64 v[168:169], s[18:19], 0, v[82:83]
	s_barrier
	ds_read_b128 v[112:115], v92 offset:16384
	ds_read_b128 v[116:119], v92 offset:17408
	global_load_lds_dwordx4 v[168:169], off
	v_lshl_add_u64 v[170:171], s[18:19], 0, v[80:81]
	s_mov_b32 m0, s21
	s_nop 0
	global_load_lds_dwordx4 v[170:171], off
	s_barrier
	s_waitcnt lgkmcnt(0)
	s_setprio 1
	s_waitcnt lgkmcnt(0)
	v_mfma_f32_16x16x32_bf16 v[12:15], v[96:99], v[112:115], v[12:15]
	v_mfma_f32_16x16x32_bf16 v[8:11], v[104:107], v[112:115], v[8:11]
	v_mfma_f32_16x16x32_bf16 v[12:15], v[100:103], v[116:119], v[12:15]
	v_mfma_f32_16x16x32_bf16 v[8:11], v[108:111], v[116:119], v[8:11]
	s_setprio 0
	s_barrier
	s_add_u32 s40, s16, 0x80000
	s_addc_u32 s41, s17, 0
	s_mov_b32 m0, s34
	v_lshl_add_u64 v[96:97], s[40:41], 0, v[82:83]
	global_load_lds_dwordx4 v[96:97], off
	v_lshl_add_u64 v[96:97], s[40:41], 0, v[80:81]
	s_mov_b32 m0, s35
	s_nop 0
	global_load_lds_dwordx4 v[96:97], off
	s_waitcnt vmcnt(6)
	s_barrier
	s_setprio 1
	v_mfma_f32_16x16x32_bf16 v[4:7], v[144:147], v[112:115], v[4:7]
	v_mfma_f32_16x16x32_bf16 v[0:3], v[152:155], v[112:115], v[0:3]
	v_mfma_f32_16x16x32_bf16 v[4:7], v[148:151], v[116:119], v[4:7]
	v_mfma_f32_16x16x32_bf16 v[0:3], v[156:159], v[116:119], v[0:3]
	s_setprio 0
	s_barrier
	ds_read_b128 v[96:99], v94
	ds_read_b128 v[100:103], v94 offset:1024
	ds_read_b128 v[104:107], v94 offset:2048
	ds_read_b128 v[108:111], v94 offset:3072
	s_add_u32 s18, s18, 0x80000
	s_addc_u32 s19, s19, 0
	s_mov_b32 m0, s22
	v_lshl_add_u64 v[144:145], s[18:19], 0, v[82:83]
	ds_read_b128 v[112:115], v92 offset:32768
	ds_read_b128 v[116:119], v92 offset:33792
	ds_read_b128 v[120:123], v92 offset:34816
	ds_read_b128 v[124:127], v92 offset:35840
	ds_read_b128 v[128:131], v92 offset:36864
	ds_read_b128 v[132:135], v92 offset:37888
	ds_read_b128 v[136:139], v92 offset:38912
	ds_read_b128 v[140:143], v92 offset:39936
	global_load_lds_dwordx4 v[144:145], off
	v_lshl_add_u64 v[144:145], s[18:19], 0, v[80:81]
	s_mov_b32 m0, s23
	s_nop 0
	global_load_lds_dwordx4 v[144:145], off
	s_waitcnt lgkmcnt(8)
	s_barrier
; #define PG8_LDA(dst, b, h) do { _Pragma("unroll") for (int m = 0; m < 4; ++m) _Pragma("unroll") for (int k = 0; k < 2; ++k) dst[m][k] = *(const LAS bf16x8*)(lds + PG8_SA(b, h) + aoff + m * 2048 + k * 1024); } while (0)
; template <class Epi, class Sched>
; __device__ __forceinline__ void gemm_phase(LAS unsigned char* lds, const Gemm g, const Sched& S, const Epi& E) {
;     ...
;             PG8_LDB(B0, 0, 0); PG8_SCHED; PG8_LDA(At, 0, 0); PG8_STAGE(PG8_SA(1, 1), a1 + hstepA, voffA);
;             PG8_WAIT_L(8); PG8_BAR; PG8_WAIT_L(0); PG8_MMA(0, 0, At, B0); PG8_BAR; PG8_SCHED;
;             PG8_LDB(B1, 0, 1); PG8_STAGE(PG8_SB(0, 0), b2, voffB);
;             PG8_BAR; PG8_WAIT_L(0); if constexpr (!Epi::DIAG) PG8_MMA(0, 1, At, B1); PG8_BAR;
;             PG8_LDA(At, 0, 1); PG8_STAGE(PG8_SA(0, 0), a2, voffA);
;             PG8_BAR; PG8_WAIT_L(0); if constexpr (!Epi::DIAG) PG8_MMA(1, 0, At, B0); PG8_BAR; PG8_SCHED;
;             PG8_STAGE(PG8_SB(0, 1), b2 + hstepB, voffB);
;             PG8_WAIT_V(6); PG8_BAR; PG8_MMA(1, 1, At, B1); PG8_BAR;
;             PG8_LDB(B0, 1, 0); PG8_SCHED; PG8_LDA(At, 1, 0); PG8_STAGE(PG8_SA(0, 1), a2 + hstepA, voffA);
;             PG8_WAIT_L(8); PG8_BAR; PG8_WAIT_L(0); PG8_MMA(0, 0, At, B0); PG8_BAR; PG8_SCHED;
;             PG8_LDB(B1, 1, 1); PG8_STAGE(PG8_SB(1, 0), b3, voffB);
;             PG8_BAR; PG8_WAIT_L(0); if constexpr (!Epi::DIAG) PG8_MMA(0, 1, At, B1); PG8_BAR;
;             PG8_LDA(At, 1, 1); PG8_STAGE(PG8_SA(1, 0), a3, voffA);
;             PG8_BAR; PG8_WAIT_L(0); if constexpr (!Epi::DIAG) PG8_MMA(1, 0, At, B0); PG8_BAR; PG8_SCHED;
;             PG8_STAGE(PG8_SB(1, 1), b3 + hstepB, voffB);
;             PG8_WAIT_V(6); PG8_BAR; PG8_MMA(1, 1, At, B1); PG8_BAR;
;     __device__ __forceinline__ void operator()(const Acc& acc, const Unit& u, int wr, int wc, int fr, int fq) const {
;         const int row0 = wr * 64 + fr, col0 = u.pn * BM + wc * 32 + 4 * fq;
; #pragma unroll
;         for (int ai = 0; ai < 2; ++ai)
; #pragma unroll
;             for (int m = 0; m < 4; ++m) { const int row = row0 + ai * HALF + m * 16; if (row < NB) {
; #pragma unroll
;                 for (int bj = 0; bj < 2; ++bj)
; #pragma unroll
;                     for (int n = 0; n < 2; ++n) { const int c = col0 + bj * HALF + n * 16; *(f32x4*)(C + (size_t)row * MODW + c) = acc[ai][bj][m][n] + *(const f32x4*)(bias + c); } } }
	s_waitcnt lgkmcnt(0)
	s_setprio 1
	s_waitcnt lgkmcnt(0)
	v_mfma_f32_16x16x32_bf16 v[76:79], v[96:99], v[112:115], v[76:79]
	v_mfma_f32_16x16x32_bf16 v[72:75], v[104:107], v[112:115], v[72:75]
	v_mfma_f32_16x16x32_bf16 v[60:63], v[96:99], v[120:123], v[60:63]
	v_mfma_f32_16x16x32_bf16 v[56:59], v[104:107], v[120:123], v[56:59]
	v_mfma_f32_16x16x32_bf16 v[44:47], v[96:99], v[128:131], v[44:47]
	v_mfma_f32_16x16x32_bf16 v[40:43], v[104:107], v[128:131], v[40:43]
	v_mfma_f32_16x16x32_bf16 v[28:31], v[96:99], v[136:139], v[28:31]
	v_mfma_f32_16x16x32_bf16 v[24:27], v[104:107], v[136:139], v[24:27]
	v_mfma_f32_16x16x32_bf16 v[76:79], v[100:103], v[116:119], v[76:79]
	v_mfma_f32_16x16x32_bf16 v[72:75], v[108:111], v[116:119], v[72:75]
	v_mfma_f32_16x16x32_bf16 v[60:63], v[100:103], v[124:127], v[60:63]
	v_mfma_f32_16x16x32_bf16 v[56:59], v[108:111], v[124:127], v[56:59]
	v_mfma_f32_16x16x32_bf16 v[44:47], v[100:103], v[132:135], v[44:47]
	v_mfma_f32_16x16x32_bf16 v[40:43], v[108:111], v[132:135], v[40:43]
	v_mfma_f32_16x16x32_bf16 v[28:31], v[100:103], v[140:143], v[28:31]
	v_mfma_f32_16x16x32_bf16 v[24:27], v[108:111], v[140:143], v[24:27]
	s_setprio 0
	s_barrier
	s_mov_b32 m0, s36
	v_lshl_add_u64 v[162:163], v[162:163], 0, s[12:13]
	ds_read_b128 v[144:147], v95
	ds_read_b128 v[148:151], v95 offset:1024
	ds_read_b128 v[152:155], v95 offset:2048
	ds_read_b128 v[156:159], v95 offset:3072
	global_load_lds_dwordx4 v[162:163], off
	v_lshl_add_u64 v[162:163], v[164:165], 0, s[12:13]
	s_mov_b32 m0, s37
	s_nop 0
	global_load_lds_dwordx4 v[162:163], off
	s_barrier
	s_waitcnt lgkmcnt(0)
	s_setprio 1
	s_waitcnt lgkmcnt(0)
	v_mfma_f32_16x16x32_bf16 v[68:71], v[144:147], v[112:115], v[68:71]
	v_mfma_f32_16x16x32_bf16 v[64:67], v[152:155], v[112:115], v[64:67]
	v_mfma_f32_16x16x32_bf16 v[52:55], v[144:147], v[120:123], v[52:55]
	v_mfma_f32_16x16x32_bf16 v[48:51], v[152:155], v[120:123], v[48:51]
	v_mfma_f32_16x16x32_bf16 v[36:39], v[144:147], v[128:131], v[36:39]
	v_mfma_f32_16x16x32_bf16 v[32:35], v[152:155], v[128:131], v[32:35]
	v_mfma_f32_16x16x32_bf16 v[20:23], v[144:147], v[136:139], v[20:23]
	v_mfma_f32_16x16x32_bf16 v[16:19], v[152:155], v[136:139], v[16:19]
	v_mfma_f32_16x16x32_bf16 v[68:71], v[148:151], v[116:119], v[68:71]
	v_mfma_f32_16x16x32_bf16 v[64:67], v[156:159], v[116:119], v[64:67]
	v_mfma_f32_16x16x32_bf16 v[52:55], v[148:151], v[124:127], v[52:55]
	v_mfma_f32_16x16x32_bf16 v[48:51], v[156:159], v[124:127], v[48:51]
	v_mfma_f32_16x16x32_bf16 v[36:39], v[148:151], v[132:135], v[36:39]
	v_mfma_f32_16x16x32_bf16 v[32:35], v[156:159], v[132:135], v[32:35]
	v_mfma_f32_16x16x32_bf16 v[20:23], v[148:151], v[140:143], v[20:23]
	v_mfma_f32_16x16x32_bf16 v[16:19], v[156:159], v[140:143], v[16:19]
	s_setprio 0
	s_mov_b32 m0, s25
	v_lshl_add_u64 v[120:121], v[168:169], 0, s[12:13]
	s_barrier
	ds_read_b128 v[112:115], v92 offset:49152
	ds_read_b128 v[116:119], v92 offset:50176
	global_load_lds_dwordx4 v[120:121], off
	v_lshl_add_u64 v[120:121], v[170:171], 0, s[12:13]
	s_mov_b32 m0, s26
	s_nop 0
	global_load_lds_dwordx4 v[120:121], off
	s_barrier
	s_waitcnt lgkmcnt(0)
	s_setprio 1
	s_waitcnt lgkmcnt(0)
	v_mfma_f32_16x16x32_bf16 v[12:15], v[96:99], v[112:115], v[12:15]
	v_mfma_f32_16x16x32_bf16 v[8:11], v[104:107], v[112:115], v[8:11]
	v_mfma_f32_16x16x32_bf16 v[12:15], v[100:103], v[116:119], v[12:15]
	v_mfma_f32_16x16x32_bf16 v[8:11], v[108:111], v[116:119], v[8:11]
	s_setprio 0
	s_barrier
	s_add_u32 s16, s16, 0x80080
	s_addc_u32 s17, s17, 0
	s_mov_b32 m0, s38
	v_lshl_add_u64 v[96:97], s[16:17], 0, v[82:83]
	global_load_lds_dwordx4 v[96:97], off
	v_lshl_add_u64 v[96:97], s[16:17], 0, v[80:81]
	s_mov_b32 m0, s39
	s_nop 0
	global_load_lds_dwordx4 v[96:97], off
	s_waitcnt vmcnt(6)
	s_barrier
	s_setprio 1
	v_mfma_f32_16x16x32_bf16 v[4:7], v[144:147], v[112:115], v[4:7]
	v_mfma_f32_16x16x32_bf16 v[0:3], v[152:155], v[112:115], v[0:3]
	v_mfma_f32_16x16x32_bf16 v[4:7], v[148:151], v[116:119], v[4:7]
	v_mfma_f32_16x16x32_bf16 v[0:3], v[156:159], v[116:119], v[0:3]
	s_setprio 0
	s_add_i32 s27, s27, 2
	s_add_u32 s14, s14, 0x100
	s_addc_u32 s15, s15, 0
	s_cmp_gt_u32 s27, 29
	s_barrier
	s_cbranch_scc0 .LBB0_299
	s_add_u32 s8, s84, 0x7880000
	s_mov_b32 s10, 0xc000
	s_addc_u32 s9, s85, 0
	v_mul_lo_u32 v82, v89, s10
	s_lshl_b32 s10, s2, 8
	v_lshl_or_b32 v80, v90, 2, s10
	s_movk_i32 s12, 0x84
	v_or_b32_e32 v80, s24, v80
	v_cmp_gt_u32_e32 vcc, s12, v89
	v_ashrrev_i32_e32 v81, 31, v80
	v_lshlrev_b64 v[96:97], 2, v[80:81]
	v_lshl_add_u64 v[96:97], s[6:7], 0, v[96:97]
	global_load_dwordx4 v[100:103], v[96:97], off
	global_load_dwordx4 v[104:107], v[96:97], off offset:64
	global_load_dwordx4 v[108:111], v[96:97], off offset:512
	global_load_dwordx4 v[112:115], v[96:97], off offset:576
	s_and_saveexec_b64 s[10:11], vcc
	s_cbranch_execz .LBB0_302
	v_lshlrev_b64 v[90:91], 2, v[80:81]
	v_lshl_add_u64 v[92:93], s[6:7], 0, v[90:91]
	s_waitcnt vmcnt(0)
	s_nop 1
	v_mov_b32_e32 v84, v100
	v_mov_b32_e32 v85, v101
	v_mov_b32_e32 v86, v102
	v_mov_b32_e32 v87, v103
	v_mov_b32_e32 v83, 0
	v_lshl_add_u64 v[94:95], s[8:9], 0, v[82:83]
	v_lshl_add_u64 v[90:91], v[94:95], 0, v[90:91]
	v_pk_add_f32 v[78:79], v[78:79], v[86:87]
	v_pk_add_f32 v[76:77], v[76:77], v[84:85]
	global_store_dwordx4 v[90:91], v[76:79], off
	s_nop 1
	v_mov_b32_e32 v76, v104
	v_mov_b32_e32 v77, v105
	v_mov_b32_e32 v78, v106
	v_mov_b32_e32 v79, v107
	v_pk_add_f32 v[74:75], v[74:75], v[78:79]
	v_pk_add_f32 v[72:73], v[72:73], v[76:77]
	global_store_dwordx4 v[90:91], v[72:75], off offset:64
	s_nop 1
	v_mov_b32_e32 v72, v108
	v_mov_b32_e32 v73, v109
	v_mov_b32_e32 v74, v110
	v_mov_b32_e32 v75, v111
	v_pk_add_f32 v[70:71], v[70:71], v[74:75]
	v_pk_add_f32 v[68:69], v[68:69], v[72:73]
	global_store_dwordx4 v[90:91], v[68:71], off offset:512
	s_nop 1
	v_mov_b32_e32 v68, v112
	v_mov_b32_e32 v69, v113
	v_mov_b32_e32 v70, v114
	v_mov_b32_e32 v71, v115
	v_pk_add_f32 v[66:67], v[66:67], v[70:71]
	v_pk_add_f32 v[64:65], v[64:65], v[68:69]
	global_store_dwordx4 v[90:91], v[64:67], off offset:576
;     __device__ __forceinline__ void operator()(const Acc& acc, const Unit& u, int wr, int wc, int fr, int fq) const { if (u.piece == 0) e1(acc, u, wr, wc, fr, fq); else e2(acc, u, wr, wc, fr, fq); }
;     __device__ __forceinline__ void operator()(const Acc& acc, const Unit& u, int wr, int wc, int fr, int fq) const {
;         const int row0 = wr * 64 + fr, col0 = u.pn * BM + wc * 32 + 4 * fq;
; #pragma unroll
;         for (int ai = 0; ai < 2; ++ai)
; #pragma unroll
;             for (int m = 0; m < 4; ++m) { const int row = row0 + ai * HALF + m * 16; if (row < NB) {
; #pragma unroll
;                 for (int bj = 0; bj < 2; ++bj)
; #pragma unroll
;                     for (int n = 0; n < 2; ++n) { const int c = col0 + bj * HALF + n * 16; *(f32x4*)(C + (size_t)row * MODW + c) = acc[ai][bj][m][n] + *(const f32x4*)(bias + c); } } }
.LBB0_302:
	s_or_b64 exec, exec, s[10:11]
	s_nop 0
	v_or_b32_e32 v65, 16, v89
	v_add_u32_e32 v64, 0xc0000, v82
	v_cmp_gt_u32_e32 vcc, s12, v65
	s_and_saveexec_b64 s[10:11], vcc
	s_cbranch_execz .LBB0_304
	v_lshlrev_b64 v[70:71], 2, v[80:81]
	v_lshl_add_u64 v[72:73], s[6:7], 0, v[70:71]
	s_nop 1
	v_mov_b32_e32 v66, v100
	v_mov_b32_e32 v67, v101
	v_mov_b32_e32 v68, v102
	v_mov_b32_e32 v69, v103
	v_mov_b32_e32 v65, 0
	v_lshl_add_u64 v[74:75], s[8:9], 0, v[64:65]
	v_lshl_add_u64 v[70:71], v[74:75], 0, v[70:71]
	v_pk_add_f32 v[62:63], v[62:63], v[68:69]
	v_pk_add_f32 v[60:61], v[60:61], v[66:67]
	global_store_dwordx4 v[70:71], v[60:63], off
	s_nop 1
	v_mov_b32_e32 v60, v104
	v_mov_b32_e32 v61, v105
	v_mov_b32_e32 v62, v106
	v_mov_b32_e32 v63, v107
	v_pk_add_f32 v[58:59], v[58:59], v[62:63]
	v_pk_add_f32 v[56:57], v[56:57], v[60:61]
	global_store_dwordx4 v[70:71], v[56:59], off offset:64
	s_nop 1
	v_mov_b32_e32 v56, v108
	v_mov_b32_e32 v57, v109
	v_mov_b32_e32 v58, v110
	v_mov_b32_e32 v59, v111
	v_pk_add_f32 v[54:55], v[54:55], v[58:59]
	v_pk_add_f32 v[52:53], v[52:53], v[56:57]
	global_store_dwordx4 v[70:71], v[52:55], off offset:512
	s_nop 1
	v_mov_b32_e32 v52, v112
	v_mov_b32_e32 v53, v113
	v_mov_b32_e32 v54, v114
	v_mov_b32_e32 v55, v115
	v_pk_add_f32 v[50:51], v[50:51], v[54:55]
	v_pk_add_f32 v[48:49], v[48:49], v[52:53]
	global_store_dwordx4 v[70:71], v[48:51], off offset:576
.LBB0_304:
	s_or_b64 exec, exec, s[10:11]
	s_nop 0
	v_or_b32_e32 v49, 32, v89
	v_add_u32_e32 v48, 0xc0000, v64
	v_cmp_gt_u32_e32 vcc, s12, v49
	s_and_saveexec_b64 s[10:11], vcc
	s_cbranch_execz .LBB0_306
	v_lshlrev_b64 v[54:55], 2, v[80:81]
	v_lshl_add_u64 v[56:57], s[6:7], 0, v[54:55]
	s_nop 1
	v_mov_b32_e32 v50, v100
	v_mov_b32_e32 v51, v101
	v_mov_b32_e32 v52, v102
	v_mov_b32_e32 v53, v103
	v_mov_b32_e32 v49, 0
	v_lshl_add_u64 v[58:59], s[8:9], 0, v[48:49]
	v_lshl_add_u64 v[54:55], v[58:59], 0, v[54:55]
	v_pk_add_f32 v[46:47], v[46:47], v[52:53]
	v_pk_add_f32 v[44:45], v[44:45], v[50:51]
	global_store_dwordx4 v[54:55], v[44:47], off
	s_nop 1
	v_mov_b32_e32 v44, v104
	v_mov_b32_e32 v45, v105
	v_mov_b32_e32 v46, v106
	v_mov_b32_e32 v47, v107
	v_pk_add_f32 v[42:43], v[42:43], v[46:47]
	v_pk_add_f32 v[40:41], v[40:41], v[44:45]
	global_store_dwordx4 v[54:55], v[40:43], off offset:64
	s_nop 1
	v_mov_b32_e32 v40, v108
	v_mov_b32_e32 v41, v109
	v_mov_b32_e32 v42, v110
	v_mov_b32_e32 v43, v111
	v_pk_add_f32 v[38:39], v[38:39], v[42:43]
	v_pk_add_f32 v[36:37], v[36:37], v[40:41]
	global_store_dwordx4 v[54:55], v[36:39], off offset:512
	s_nop 1
	v_mov_b32_e32 v36, v112
	v_mov_b32_e32 v37, v113
	v_mov_b32_e32 v38, v114
	v_mov_b32_e32 v39, v115
	v_pk_add_f32 v[34:35], v[34:35], v[38:39]
	v_pk_add_f32 v[32:33], v[32:33], v[36:37]
	global_store_dwordx4 v[54:55], v[32:35], off offset:576
.LBB0_306:
	s_or_b64 exec, exec, s[10:11]
	s_nop 0
	v_or_b32_e32 v32, 48, v89
	v_cmp_gt_u32_e32 vcc, s12, v32
	s_and_saveexec_b64 s[10:11], vcc
	s_cbranch_execz .LBB0_308
	v_lshlrev_b64 v[36:37], 2, v[80:81]
	v_lshl_add_u64 v[38:39], s[6:7], 0, v[36:37]
	s_nop 1
	v_mov_b32_e32 v32, v100
	v_mov_b32_e32 v33, v101
	v_mov_b32_e32 v34, v102
	v_mov_b32_e32 v35, v103
	v_add_u32_e32 v40, 0xc0000, v48
	v_mov_b32_e32 v41, 0
	v_lshl_add_u64 v[40:41], s[8:9], 0, v[40:41]
	v_lshl_add_u64 v[36:37], v[40:41], 0, v[36:37]
	v_pk_add_f32 v[30:31], v[30:31], v[34:35]
	v_pk_add_f32 v[28:29], v[28:29], v[32:33]
	global_store_dwordx4 v[36:37], v[28:31], off
	s_nop 1
	v_mov_b32_e32 v28, v104
	v_mov_b32_e32 v29, v105
	v_mov_b32_e32 v30, v106
	v_mov_b32_e32 v31, v107
	v_pk_add_f32 v[26:27], v[26:27], v[30:31]
	v_pk_add_f32 v[24:25], v[24:25], v[28:29]
	global_store_dwordx4 v[36:37], v[24:27], off offset:64
	s_nop 1
	v_mov_b32_e32 v24, v108
	v_mov_b32_e32 v25, v109
	v_mov_b32_e32 v26, v110
	v_mov_b32_e32 v27, v111
	v_pk_add_f32 v[22:23], v[22:23], v[26:27]
	v_pk_add_f32 v[20:21], v[20:21], v[24:25]
	global_store_dwordx4 v[36:37], v[20:23], off offset:512
	s_nop 1
	v_mov_b32_e32 v20, v112
	v_mov_b32_e32 v21, v113
	v_mov_b32_e32 v22, v114
	v_mov_b32_e32 v23, v115
	v_pk_add_f32 v[18:19], v[18:19], v[22:23]
	v_pk_add_f32 v[16:17], v[16:17], v[20:21]
	global_store_dwordx4 v[36:37], v[16:19], off offset:576
.LBB0_308:
	s_or_b64 exec, exec, s[10:11]
	v_cmp_gt_u32_e32 vcc, 4, v89
	s_and_saveexec_b64 s[10:11], vcc
	s_cbranch_execz .LBB0_310
	v_lshlrev_b64 v[20:21], 2, v[80:81]
	v_lshl_add_u64 v[22:23], s[6:7], 0, v[20:21]
	s_nop 1
	v_mov_b32_e32 v16, v100
	v_mov_b32_e32 v17, v101
	v_mov_b32_e32 v18, v102
	v_mov_b32_e32 v19, v103
	v_mul_u32_u24_e32 v24, 0xc000, v88
	v_mov_b32_e32 v25, 0
	s_mov_b64 s[6:7], 0x600000
	v_lshl_add_u64 v[24:25], s[8:9], 0, v[24:25]
	v_lshl_add_u64 v[24:25], v[24:25], 0, s[6:7]
	v_lshl_add_u64 v[20:21], v[24:25], 0, v[20:21]
	v_pk_add_f32 v[14:15], v[14:15], v[18:19]
	v_pk_add_f32 v[12:13], v[12:13], v[16:17]
	global_store_dwordx4 v[20:21], v[12:15], off
	s_nop 1
	v_mov_b32_e32 v12, v104
	v_mov_b32_e32 v13, v105
	v_mov_b32_e32 v14, v106
	v_mov_b32_e32 v15, v107
	v_or_b32_e32 v16, 16, v80
	v_ashrrev_i32_e32 v17, 31, v16
	v_lshl_add_u64 v[16:17], v[16:17], 2, v[24:25]
	v_pk_add_f32 v[10:11], v[10:11], v[14:15]
	v_pk_add_f32 v[8:9], v[8:9], v[12:13]
	global_store_dwordx4 v[16:17], v[8:11], off
	s_nop 1
	v_mov_b32_e32 v8, v108
	v_mov_b32_e32 v9, v109
	v_mov_b32_e32 v10, v110
	v_mov_b32_e32 v11, v111
	v_or_b32_e32 v12, 0x80, v80
	v_ashrrev_i32_e32 v13, 31, v12
	v_lshl_add_u64 v[12:13], v[12:13], 2, v[24:25]
	v_pk_add_f32 v[6:7], v[6:7], v[10:11]
	v_pk_add_f32 v[4:5], v[4:5], v[8:9]
	global_store_dwordx4 v[12:13], v[4:7], off
	s_nop 1
	v_mov_b32_e32 v4, v112
	v_mov_b32_e32 v5, v113
	v_mov_b32_e32 v6, v114
	v_mov_b32_e32 v7, v115
	v_or_b32_e32 v8, 0x90, v80
	v_ashrrev_i32_e32 v9, 31, v8
	v_pk_add_f32 v[2:3], v[2:3], v[6:7]
	v_pk_add_f32 v[0:1], v[0:1], v[4:5]
	v_lshl_add_u64 v[4:5], v[8:9], 2, v[24:25]
	global_store_dwordx4 v[4:5], v[0:3], off

; #define LAS __attribute__((address_space(3)))
; __device__ __forceinline__ float bf2f(unsigned short x) { return __uint_as_float(((unsigned)x) << 16); }
; __device__ __forceinline__ void chunk_prep_phase(const Params& p, int bid, int nblk, LAS unsigned char* lds0) {
;     ...
;         if (w8 < 4) {
;             const int g2 = w8 >> 1, c = (w8 & 1) * 64 + lane; const int item2 = it0 + g2;
;             LAS unsigned char* lg = lds0 + g2 * P5_GRP; LAS float* Mg = (LAS float*)(lg + P5_MM); LAS float* decg = (LAS float*)(lg + P5_DEC); LAS float* betg = (LAS float*)(lg + P5_BETA);
;             f32x2 xy[64]; f32x4 mq[6]; f32x2 ab0, ab1;
;             float* up = ub + (size_t)item2 * 8192 + c; bf16_t* wp = wdc + (size_t)item2 * 8192 + c;
;             { const float br = betg[0]; ab0 = (f32x2){bf2f(*(const LAS bf16_t*)(lg + P5_VS + 0 + c * 2)) * br, bf2f(*(const LAS bf16_t*)(lg + P5_KS + 0 + c * 2)) * br * __expf(decg[0])}; ab1 = (f32x2){0.f, 0.f}; } xy[0] = ab0; up[0] = xy[0][0]; wp[0] = f2bf(-xy[0][1]);
;             mq[0] = *(const LAS f32x4*)(Mg + 64); mq[1] = *(const LAS f32x4*)(Mg + 128); mq[2] = *(const LAS f32x4*)(Mg + 192); mq[3] = *(const LAS f32x4*)(Mg + 256); mq[4] = *(const LAS f32x4*)(Mg + 320); mq[5] = *(const LAS f32x4*)(Mg + 324);
;             { const float br = betg[1]; ab0 = (f32x2){bf2f(*(const LAS bf16_t*)(lg + P5_VS + 272 + c * 2)) * br, bf2f(*(const LAS bf16_t*)(lg + P5_KS + 272 + c * 2)) * br * __expf(decg[1])}; ab1 = (f32x2){0.f, 0.f}; } ab0 -= mq[0][0] * xy[0]; xy[1] = ab0 + ab1; up[128] = xy[1][0]; wp[128] = f2bf(-xy[1][1]); mq[0] = *(const LAS f32x4*)(Mg + 384);
;             { const float br = betg[2]; ab0 = (f32x2){bf2f(*(const LAS bf16_t*)(lg + P5_VS + 544 + c * 2)) * br, bf2f(*(const LAS bf16_t*)(lg + P5_KS + 544 + c * 2)) * br * __expf(decg[2])}; ab1 = (f32x2){0.f, 0.f}; } ab0 -= mq[1][0] * xy[0]; ab1 -= mq[1][1] * xy[1]; xy[2] = ab0 + ab1; up[256] = xy[2][0]; wp[256] = f2bf(-xy[2][1]); mq[1] = *(const LAS f32x4*)(Mg + 388);
;             { const float br = betg[3]; ab0 = (f32x2){bf2f(*(const LAS bf16_t*)(lg + P5_VS + 816 + c * 2)) * br, bf2f(*(const LAS bf16_t*)(lg + P5_KS + 816 + c * 2)) * br * __expf(decg[3])}; ab1 = (f32x2){0.f, 0.f}; } ab0 -= mq[2][0] * xy[0]; ab1 -= mq[2][1] * xy[1]; ab0 -= mq[2][2] * xy[2]; xy[3] = ab0 + ab1; up[384] = xy[3][0]; wp[384] = f2bf(-xy[3][1]); mq[2] = *(const LAS f32x4*)(Mg + 448);
.LBB0_1007:
	s_lshr_b32 s11, s7, 2
	s_bfe_u32 s10, s7, 0x10001
	s_add_i32 s9, s97, s10
	s_mul_i32 s10, s10, 0x11000
	s_and_b32 s16, s7, 1
	s_lshl_b32 s16, s16, 6
	v_or_b32_e32 v232, s16, v149
	v_lshlrev_b32_e32 v234, 2, v232
	v_lshlrev_b32_e32 v6, 1, v232
	s_cmp_lg_u32 s11, 0
	s_cselect_b64 vcc, -1, 0
	s_cselect_b32 s16, 0x3fb8aa3b, 0
	s_mov_b32 s8, 0x8800
	s_cselect_b32 s8, 0x4400, s8
	s_add_i32 s8, s8, s10
	v_add_u32_e32 v7, s8, v6
	s_add_i32 s8, s10, 0xcc00
	v_mov_b32_e32 v8, s8
	s_cbranch_vccnz .Ls4_wbase
	s_load_dwordx2 s[10:11], s[0:1], 0xc0
	s_lshl_b32 s8, s9, 15
	s_waitcnt lgkmcnt(0)
	s_add_u32 s8, s8, s10
	s_addc_u32 s9, s11, 0
	s_add_u32 s8, s8, 0x2200000
	s_addc_u32 s9, s9, 0
	s_branch .Ls4_go
.Ls4_wbase:
	s_lshl_b32 s8, s9, 14
	s_add_u32 s8, s8, s84
	s_addc_u32 s9, s85, 0
	s_add_u32 s8, s8, 0xe539000
	s_addc_u32 s9, s9, 0
.Ls4_go:
	ds_read_b128 v[216:219], v8 offset:16640
	ds_read_b128 v[0:3], v8 offset:16384
	ds_read_u16 v228, v7 offset:0
	ds_read_b128 v[220:223], v8 offset:16656
	ds_read_b128 v[224:227], v8 offset:16400
	ds_read_b128 v[192:195], v8 offset:256
	ds_read_b128 v[196:199], v8 offset:512
	ds_read_b128 v[200:203], v8 offset:768
	ds_read_b128 v[204:207], v8 offset:1024
	ds_read_b128 v[208:211], v8 offset:1280
	ds_read_b128 v[212:215], v8 offset:1296
	s_waitcnt lgkmcnt(9)
	v_mul_f32_e32 v0, s16, v0
	v_mul_f32_e32 v1, s16, v1
	v_mul_f32_e32 v2, s16, v2
	v_mul_f32_e32 v3, s16, v3
	v_exp_f32_e32 v0, v0
	v_exp_f32_e32 v1, v1
	v_exp_f32_e32 v2, v2
	v_exp_f32_e32 v3, v3
	s_nop 0
	s_waitcnt lgkmcnt(8)
	v_lshlrev_b32_e32 v228, 16, v228
	v_mul_f32_e32 v232, v228, v216
	v_mul_f32_e32 v230, v232, v0
	ds_read_u16 v229, v7 offset:272
	v_mov_b32_e32 v84, v230
	s_cbranch_vccz .Ls4_u0
	v_cvt_pk_bf16_f32 v233, -v84, v84
	global_store_short v6, v233, s[8:9] offset:0
	s_branch .Ls4_n0
.Ls4_u0:
	global_store_dword v234, v84, s[8:9] offset:0
.Ls4_n0:
	s_waitcnt lgkmcnt(0)
	v_lshlrev_b32_e32 v229, 16, v229
	v_mul_f32_e32 v232, v229, v217
	v_mul_f32_e32 v230, v232, v1
	ds_read_u16 v228, v7 offset:544
	v_fma_f32 v230, -v192, v84, v230
	ds_read_b128 v[192:195], v8 offset:1536
	v_mov_b32_e32 v85, v230
	s_cbranch_vccz .Ls4_u1
	v_cvt_pk_bf16_f32 v233, -v85, v85
	global_store_short v6, v233, s[8:9] offset:256
	s_branch .Ls4_n1
.Ls4_u1:
	global_store_dword v234, v85, s[8:9] offset:512
.Ls4_n1:
	s_waitcnt lgkmcnt(1)
	v_lshlrev_b32_e32 v228, 16, v228
	v_mul_f32_e32 v232, v228, v218
	v_mul_f32_e32 v230, v232, v2
	v_mov_b32_e32 v231, 0
	ds_read_u16 v229, v7 offset:816
	v_fma_f32 v230, -v196, v84, v230
	v_fma_f32 v231, -v197, v85, v231
	ds_read_b128 v[196:199], v8 offset:1552
	v_add_f32_e32 v86, v230, v231
	s_cbranch_vccz .Ls4_u2
	v_cvt_pk_bf16_f32 v233, -v86, v86
	global_store_short v6, v233, s[8:9] offset:512
	s_branch .Ls4_n2
.Ls4_u2:
	global_store_dword v234, v86, s[8:9] offset:1024
.Ls4_n2:
	s_waitcnt lgkmcnt(1)
	v_lshlrev_b32_e32 v229, 16, v229
	v_mul_f32_e32 v232, v229, v219
	v_mul_f32_e32 v230, v232, v3
	v_mov_b32_e32 v231, 0
	ds_read_u16 v228, v7 offset:1088
	ds_read_b128 v[216:219], v8 offset:16672
	ds_read_b128 v[0:3], v8 offset:16416
	v_fma_f32 v230, -v200, v84, v230
	v_fma_f32 v231, -v201, v85, v231
	v_fma_f32 v230, -v202, v86, v230
	ds_read_b128 v[200:203], v8 offset:1792
	v_add_f32_e32 v87, v230, v231
	s_cbranch_vccz .Ls4_u3
	v_cvt_pk_bf16_f32 v233, -v87, v87
	global_store_short v6, v233, s[8:9] offset:768
	s_branch .Ls4_n3
.Ls4_u3:
	global_store_dword v234, v87, s[8:9] offset:1536
.Ls4_n3:
	v_mul_f32_e32 v224, s16, v224
	v_mul_f32_e32 v225, s16, v225
	v_mul_f32_e32 v226, s16, v226
	v_mul_f32_e32 v227, s16, v227
	v_exp_f32_e32 v224, v224
	v_exp_f32_e32 v225, v225
	v_exp_f32_e32 v226, v226
	v_exp_f32_e32 v227, v227
	s_nop 0
	s_waitcnt lgkmcnt(3)
	v_lshlrev_b32_e32 v228, 16, v228
	v_mul_f32_e32 v232, v228, v220
	v_mul_f32_e32 v230, v232, v224
	v_mov_b32_e32 v231, 0
	ds_read_u16 v229, v7 offset:1360
	v_fma_f32 v230, -v204, v84, v230
	v_fma_f32 v231, -v205, v85, v231
	v_fma_f32 v230, -v206, v86, v230
	v_fma_f32 v231, -v207, v87, v231
	ds_read_b128 v[204:207], v8 offset:1808
	v_add_f32_e32 v88, v230, v231
	s_cbranch_vccz .Ls4_u4
	v_cvt_pk_bf16_f32 v233, -v88, v88
	global_store_short v6, v233, s[8:9] offset:1024
	s_branch .Ls4_n4
.Ls4_u4:
	global_store_dword v234, v88, s[8:9] offset:2048
.Ls4_n4:
	s_waitcnt lgkmcnt(1)
	v_lshlrev_b32_e32 v229, 16, v229
	v_mul_f32_e32 v232, v229, v221
	v_mul_f32_e32 v230, v232, v225
	v_mov_b32_e32 v231, 0
	ds_read_u16 v228, v7 offset:1632
	v_fma_f32 v230, -v208, v84, v230
	v_fma_f32 v231, -v209, v85, v231
	v_fma_f32 v230, -v210, v86, v230
	v_fma_f32 v231, -v211, v87, v231
	ds_read_b128 v[208:211], v8 offset:2048
	v_fma_f32 v230, -v212, v88, v230
	ds_read_b128 v[212:215], v8 offset:2064
	v_add_f32_e32 v89, v230, v231
	s_cbranch_vccz .Ls4_u5
	v_cvt_pk_bf16_f32 v233, -v89, v89
	global_store_short v6, v233, s[8:9] offset:1280
	s_branch .Ls4_n5
.Ls4_u5:
	global_store_dword v234, v89, s[8:9] offset:2560
.Ls4_n5:
	s_waitcnt lgkmcnt(2)
	v_lshlrev_b32_e32 v228, 16, v228
	v_mul_f32_e32 v232, v228, v222
	v_mul_f32_e32 v230, v232, v226
	v_mov_b32_e32 v231, 0
	ds_read_u16 v229, v7 offset:1904
	v_fma_f32 v230, -v192, v84, v230
	v_fma_f32 v231, -v193, v85, v231
	v_fma_f32 v230, -v194, v86, v230
	v_fma_f32 v231, -v195, v87, v231
	ds_read_b128 v[192:195], v8 offset:2304
	v_fma_f32 v230, -v196, v88, v230
	v_fma_f32 v231, -v197, v89, v231
	ds_read_b128 v[196:199], v8 offset:2320
	v_add_f32_e32 v90, v230, v231
	s_cbranch_vccz .Ls4_u6
	v_cvt_pk_bf16_f32 v233, -v90, v90
	global_store_short v6, v233, s[8:9] offset:1536
	s_branch .Ls4_n6
.Ls4_u6:
	global_store_dword v234, v90, s[8:9] offset:3072
; #define LAS __attribute__((address_space(3)))
; __device__ __forceinline__ void chunk_prep_phase(const Params& p, int bid, int nblk, LAS unsigned char* lds0) {
;     ...
;             { const float br = betg[7]; ab0 = (f32x2){bf2f(*(const LAS bf16_t*)(lg + P5_VS + 1904 + c * 2)) * br, bf2f(*(const LAS bf16_t*)(lg + P5_KS + 1904 + c * 2)) * br * __expf(decg[7])}; ab1 = (f32x2){0.f, 0.f}; } ab0 -= mq[2][0] * xy[0]; ab1 -= mq[2][1] * xy[1]; ab0 -= mq[2][2] * xy[2]; ab1 -= mq[2][3] * xy[3]; mq[2] = *(const LAS f32x4*)(Mg + 584);
;             ab0 -= mq[3][0] * xy[4]; ab1 -= mq[3][1] * xy[5]; ab0 -= mq[3][2] * xy[6]; xy[7] = ab0 + ab1; up[896] = xy[7][0]; wp[896] = f2bf(-xy[7][1]); mq[3] = *(const LAS f32x4*)(Mg + 640);
;             { const float br = betg[8]; ab0 = (f32x2){bf2f(*(const LAS bf16_t*)(lg + P5_VS + 2176 + c * 2)) * br, bf2f(*(const LAS bf16_t*)(lg + P5_KS + 2176 + c * 2)) * br * __expf(decg[8])}; ab1 = (f32x2){0.f, 0.f}; } ab0 -= mq[4][0] * xy[0]; ab1 -= mq[4][1] * xy[1]; ab0 -= mq[4][2] * xy[2]; ab1 -= mq[4][3] * xy[3]; mq[4] = *(const LAS f32x4*)(Mg + 644);
;             ab0 -= mq[5][0] * xy[4]; ab1 -= mq[5][1] * xy[5]; ab0 -= mq[5][2] * xy[6]; ab1 -= mq[5][3] * xy[7]; xy[8] = ab0 + ab1; up[1024] = xy[8][0]; wp[1024] = f2bf(-xy[8][1]); mq[5] = *(const LAS f32x4*)(Mg + 648);
;             { const float br = betg[9]; ab0 = (f32x2){bf2f(*(const LAS bf16_t*)(lg + P5_VS + 2448 + c * 2)) * br, bf2f(*(const LAS bf16_t*)(lg + P5_KS + 2448 + c * 2)) * br * __expf(decg[9])}; ab1 = (f32x2){0.f, 0.f}; } ab0 -= mq[0][0] * xy[0]; ab1 -= mq[0][1] * xy[1]; ab0 -= mq[0][2] * xy[2]; ab1 -= mq[0][3] * xy[3]; mq[0] = *(const LAS f32x4*)(Mg + 704);
;             ab0 -= mq[1][0] * xy[4]; ab1 -= mq[1][1] * xy[5]; ab0 -= mq[1][2] * xy[6]; ab1 -= mq[1][3] * xy[7]; mq[1] = *(const LAS f32x4*)(Mg + 708);
;             ab0 -= mq[2][0] * xy[8]; xy[9] = ab0 + ab1; up[1152] = xy[9][0]; wp[1152] = f2bf(-xy[9][1]); mq[2] = *(const LAS f32x4*)(Mg + 712);
;             { const float br = betg[10]; ab0 = (f32x2){bf2f(*(const LAS bf16_t*)(lg + P5_VS + 2720 + c * 2)) * br, bf2f(*(const LAS bf16_t*)(lg + P5_KS + 2720 + c * 2)) * br * __expf(decg[10])}; ab1 = (f32x2){0.f, 0.f}; } ab0 -= mq[3][0] * xy[0]; ab1 -= mq[3][1] * xy[1]; ab0 -= mq[3][2] * xy[2]; ab1 -= mq[3][3] * xy[3]; mq[3] = *(const LAS f32x4*)(Mg + 768);
.Ls4_n6:
	s_waitcnt lgkmcnt(2)
	v_lshlrev_b32_e32 v229, 16, v229
	v_mul_f32_e32 v232, v229, v223
	v_mul_f32_e32 v230, v232, v227
	v_mov_b32_e32 v231, 0
	ds_read_u16 v228, v7 offset:2176
	ds_read_b128 v[220:223], v8 offset:16688
	ds_read_b128 v[224:227], v8 offset:16432
	v_fma_f32 v230, -v200, v84, v230
	v_fma_f32 v231, -v201, v85, v231
	v_fma_f32 v230, -v202, v86, v230
	v_fma_f32 v231, -v203, v87, v231
	ds_read_b128 v[200:203], v8 offset:2336
	v_fma_f32 v230, -v204, v88, v230
	v_fma_f32 v231, -v205, v89, v231
	v_fma_f32 v230, -v206, v90, v230
	ds_read_b128 v[204:207], v8 offset:2560
	v_add_f32_e32 v91, v230, v231
	s_cbranch_vccz .Ls4_u7
	v_cvt_pk_bf16_f32 v233, -v91, v91
	global_store_short v6, v233, s[8:9] offset:1792
	s_branch .Ls4_n7
.Ls4_u7:
	global_store_dword v234, v91, s[8:9] offset:3584
.Ls4_n7:
	v_mul_f32_e32 v0, s16, v0
	v_mul_f32_e32 v1, s16, v1
	v_mul_f32_e32 v2, s16, v2
	v_mul_f32_e32 v3, s16, v3
	v_exp_f32_e32 v0, v0
	v_exp_f32_e32 v1, v1
	v_exp_f32_e32 v2, v2
	v_exp_f32_e32 v3, v3
	s_nop 0
	s_waitcnt lgkmcnt(4)
	v_lshlrev_b32_e32 v228, 16, v228
	v_mul_f32_e32 v232, v228, v216
	v_mul_f32_e32 v230, v232, v0
	v_mov_b32_e32 v231, 0
	ds_read_u16 v229, v7 offset:2448
	v_fma_f32 v230, -v208, v84, v230
	v_fma_f32 v231, -v209, v85, v231
	v_fma_f32 v230, -v210, v86, v230
	v_fma_f32 v231, -v211, v87, v231
	ds_read_b128 v[208:211], v8 offset:2576
	v_fma_f32 v230, -v212, v88, v230
	v_fma_f32 v231, -v213, v89, v231
	v_fma_f32 v230, -v214, v90, v230
	v_fma_f32 v231, -v215, v91, v231
	ds_read_b128 v[212:215], v8 offset:2592
	v_add_f32_e32 v92, v230, v231
	s_cbranch_vccz .Ls4_u8
	v_cvt_pk_bf16_f32 v233, -v92, v92
	global_store_short v6, v233, s[8:9] offset:2048
	s_branch .Ls4_n8
.Ls4_u8:
	s_add_u32 s8, s8, 0x1000
	s_addc_u32 s9, s9, 0
	global_store_dword v234, v92, s[8:9] offset:0
.Ls4_n8:
	s_waitcnt lgkmcnt(2)
	v_lshlrev_b32_e32 v229, 16, v229
	v_mul_f32_e32 v232, v229, v217
	v_mul_f32_e32 v230, v232, v1
	v_mov_b32_e32 v231, 0
	ds_read_u16 v228, v7 offset:2720
	v_fma_f32 v230, -v192, v84, v230
	v_fma_f32 v231, -v193, v85, v231
	v_fma_f32 v230, -v194, v86, v230
	v_fma_f32 v231, -v195, v87, v231
	ds_read_b128 v[192:195], v8 offset:2816
	v_fma_f32 v230, -v196, v88, v230
	v_fma_f32 v231, -v197, v89, v231
	v_fma_f32 v230, -v198, v90, v230
	v_fma_f32 v231, -v199, v91, v231
	ds_read_b128 v[196:199], v8 offset:2832
	v_fma_f32 v230, -v200, v92, v230
	ds_read_b128 v[200:203], v8 offset:2848
	v_add_f32_e32 v93, v230, v231
	s_cbranch_vccz .Ls4_u9
	v_cvt_pk_bf16_f32 v233, -v93, v93
	global_store_short v6, v233, s[8:9] offset:2304
	s_branch .Ls4_n9
.Ls4_u9:
	global_store_dword v234, v93, s[8:9] offset:512
.Ls4_n9:
	s_waitcnt lgkmcnt(3)
	v_lshlrev_b32_e32 v228, 16, v228
	v_mul_f32_e32 v232, v228, v218
	v_mul_f32_e32 v230, v232, v2
	v_mov_b32_e32 v231, 0
	ds_read_u16 v229, v7 offset:2992
	v_fma_f32 v230, -v204, v84, v230
	v_fma_f32 v231, -v205, v85, v231
	v_fma_f32 v230, -v206, v86, v230
	v_fma_f32 v231, -v207, v87, v231
	ds_read_b128 v[204:207], v8 offset:3072
	v_fma_f32 v230, -v208, v88, v230
	v_fma_f32 v231, -v209, v89, v231
	v_fma_f32 v230, -v210, v90, v230
	v_fma_f32 v231, -v211, v91, v231
	ds_read_b128 v[208:211], v8 offset:3088
	v_fma_f32 v230, -v212, v92, v230
	v_fma_f32 v231, -v213, v93, v231
	ds_read_b128 v[212:215], v8 offset:3104
	v_add_f32_e32 v94, v230, v231
	s_cbranch_vccz .Ls4_u10
	v_cvt_pk_bf16_f32 v233, -v94, v94
	global_store_short v6, v233, s[8:9] offset:2560
	s_branch .Ls4_n10
.Ls4_u10:
	global_store_dword v234, v94, s[8:9] offset:1024
.Ls4_n10:
	s_waitcnt lgkmcnt(3)
	v_lshlrev_b32_e32 v229, 16, v229
	v_mul_f32_e32 v232, v229, v219
	v_mul_f32_e32 v230, v232, v3
	v_mov_b32_e32 v231, 0
	ds_read_u16 v228, v7 offset:3264
	ds_read_b128 v[216:219], v8 offset:16704
	ds_read_b128 v[0:3], v8 offset:16448
	v_fma_f32 v230, -v192, v84, v230
	v_fma_f32 v231, -v193, v85, v231
	v_fma_f32 v230, -v194, v86, v230
	v_fma_f32 v231, -v195, v87, v231
	ds_read_b128 v[192:195], v8 offset:3328
	v_fma_f32 v230, -v196, v88, v230
	v_fma_f32 v231, -v197, v89, v231
	v_fma_f32 v230, -v198, v90, v230
	v_fma_f32 v231, -v199, v91, v231
	ds_read_b128 v[196:199], v8 offset:3344
	v_fma_f32 v230, -v200, v92, v230
	v_fma_f32 v231, -v201, v93, v231
	v_fma_f32 v230, -v202, v94, v230
	ds_read_b128 v[200:203], v8 offset:3360
	v_add_f32_e32 v95, v230, v231
	s_cbranch_vccz .Ls4_u11
	v_cvt_pk_bf16_f32 v233, -v95, v95
	global_store_short v6, v233, s[8:9] offset:2816
	s_branch .Ls4_n11
.Ls4_u11:
	global_store_dword v234, v95, s[8:9] offset:1536
.Ls4_n11:
	v_mul_f32_e32 v224, s16, v224
	v_mul_f32_e32 v225, s16, v225
	v_mul_f32_e32 v226, s16, v226
	v_mul_f32_e32 v227, s16, v227
	v_exp_f32_e32 v224, v224
	v_exp_f32_e32 v225, v225
	v_exp_f32_e32 v226, v226
	v_exp_f32_e32 v227, v227
	s_nop 0
	s_waitcnt lgkmcnt(5)
	v_lshlrev_b32_e32 v228, 16, v228
	v_mul_f32_e32 v232, v228, v220
	v_mul_f32_e32 v230, v232, v224
	v_mov_b32_e32 v231, 0
	ds_read_u16 v229, v7 offset:3536
	v_fma_f32 v230, -v204, v84, v230
	v_fma_f32 v231, -v205, v85, v231
	v_fma_f32 v230, -v206, v86, v230
	v_fma_f32 v231, -v207, v87, v231
	ds_read_b128 v[204:207], v8 offset:3376
	v_fma_f32 v230, -v208, v88, v230
	v_fma_f32 v231, -v209, v89, v231
	v_fma_f32 v230, -v210, v90, v230
	v_fma_f32 v231, -v211, v91, v231
	ds_read_b128 v[208:211], v8 offset:3584
	v_fma_f32 v230, -v212, v92, v230
	v_fma_f32 v231, -v213, v93, v231
	v_fma_f32 v230, -v214, v94, v230
	v_fma_f32 v231, -v215, v95, v231
	ds_read_b128 v[212:215], v8 offset:3600
	v_add_f32_e32 v96, v230, v231
	s_cbranch_vccz .Ls4_u12
	v_cvt_pk_bf16_f32 v233, -v96, v96
	global_store_short v6, v233, s[8:9] offset:3072
	s_branch .Ls4_n12
.Ls4_u12:
	global_store_dword v234, v96, s[8:9] offset:2048
; #define LAS __attribute__((address_space(3)))
; __device__ __forceinline__ void chunk_prep_phase(const Params& p, int bid, int nblk, LAS unsigned char* lds0) {
;     ...
;             { const float br = betg[13]; ab0 = (f32x2){bf2f(*(const LAS bf16_t*)(lg + P5_VS + 3536 + c * 2)) * br, bf2f(*(const LAS bf16_t*)(lg + P5_KS + 3536 + c * 2)) * br * __expf(decg[13])}; ab1 = (f32x2){0.f, 0.f}; } ab0 -= mq[0][0] * xy[0]; ab1 -= mq[0][1] * xy[1]; ab0 -= mq[0][2] * xy[2]; ab1 -= mq[0][3] * xy[3]; mq[0] = *(const LAS f32x4*)(Mg + 904);
;             ab0 -= mq[1][0] * xy[4]; ab1 -= mq[1][1] * xy[5]; ab0 -= mq[1][2] * xy[6]; ab1 -= mq[1][3] * xy[7]; mq[1] = *(const LAS f32x4*)(Mg + 908);
;             ab0 -= mq[2][0] * xy[8]; ab1 -= mq[2][1] * xy[9]; ab0 -= mq[2][2] * xy[10]; ab1 -= mq[2][3] * xy[11]; mq[2] = *(const LAS f32x4*)(Mg + 960);
;             ab0 -= mq[3][0] * xy[12]; xy[13] = ab0 + ab1; up[1664] = xy[13][0]; wp[1664] = f2bf(-xy[13][1]); mq[3] = *(const LAS f32x4*)(Mg + 964);
;             { const float br = betg[14]; ab0 = (f32x2){bf2f(*(const LAS bf16_t*)(lg + P5_VS + 3808 + c * 2)) * br, bf2f(*(const LAS bf16_t*)(lg + P5_KS + 3808 + c * 2)) * br * __expf(decg[14])}; ab1 = (f32x2){0.f, 0.f}; } ab0 -= mq[4][0] * xy[0]; ab1 -= mq[4][1] * xy[1]; ab0 -= mq[4][2] * xy[2]; ab1 -= mq[4][3] * xy[3]; mq[4] = *(const LAS f32x4*)(Mg + 968);
;             ab0 -= mq[5][0] * xy[4]; ab1 -= mq[5][1] * xy[5]; ab0 -= mq[5][2] * xy[6]; ab1 -= mq[5][3] * xy[7]; mq[5] = *(const LAS f32x4*)(Mg + 972);
;             ab0 -= mq[0][0] * xy[8]; ab1 -= mq[0][1] * xy[9]; ab0 -= mq[0][2] * xy[10]; ab1 -= mq[0][3] * xy[11]; mq[0] = *(const LAS f32x4*)(Mg + 1024);
;             ab0 -= mq[1][0] * xy[12]; ab1 -= mq[1][1] * xy[13]; xy[14] = ab0 + ab1; up[1792] = xy[14][0]; wp[1792] = f2bf(-xy[14][1]); mq[1] = *(const LAS f32x4*)(Mg + 1028);
;             { const float br = betg[15]; ab0 = (f32x2){bf2f(*(const LAS bf16_t*)(lg + P5_VS + 4080 + c * 2)) * br, bf2f(*(const LAS bf16_t*)(lg + P5_KS + 4080 + c * 2)) * br * __expf(decg[15])}; ab1 = (f32x2){0.f, 0.f}; } ab0 -= mq[2][0] * xy[0]; ab1 -= mq[2][1] * xy[1]; ab0 -= mq[2][2] * xy[2]; ab1 -= mq[2][3] * xy[3]; mq[2] = *(const LAS f32x4*)(Mg + 1032);
;             ab0 -= mq[3][0] * xy[4]; ab1 -= mq[3][1] * xy[5]; ab0 -= mq[3][2] * xy[6]; ab1 -= mq[3][3] * xy[7]; mq[3] = *(const LAS f32x4*)(Mg + 1036);
.Ls4_n12:
	s_waitcnt lgkmcnt(3)
	v_lshlrev_b32_e32 v229, 16, v229
	v_mul_f32_e32 v232, v229, v221
	v_mul_f32_e32 v230, v232, v225
	v_mov_b32_e32 v231, 0
	ds_read_u16 v228, v7 offset:3808
	v_fma_f32 v230, -v192, v84, v230
	v_fma_f32 v231, -v193, v85, v231
	v_fma_f32 v230, -v194, v86, v230
	v_fma_f32 v231, -v195, v87, v231
	ds_read_b128 v[192:195], v8 offset:3616
	v_fma_f32 v230, -v196, v88, v230
	v_fma_f32 v231, -v197, v89, v231
	v_fma_f32 v230, -v198, v90, v230
	v_fma_f32 v231, -v199, v91, v231
	ds_read_b128 v[196:199], v8 offset:3632
	v_fma_f32 v230, -v200, v92, v230
	v_fma_f32 v231, -v201, v93, v231
	v_fma_f32 v230, -v202, v94, v230
	v_fma_f32 v231, -v203, v95, v231
	ds_read_b128 v[200:203], v8 offset:3840
	s_waitcnt lgkmcnt(6)
	v_fma_f32 v230, -v204, v96, v230
	ds_read_b128 v[204:207], v8 offset:3856
	v_add_f32_e32 v97, v230, v231
	s_cbranch_vccz .Ls4_u13
	v_cvt_pk_bf16_f32 v233, -v97, v97
	global_store_short v6, v233, s[8:9] offset:3328
	s_branch .Ls4_n13
.Ls4_u13:
	global_store_dword v234, v97, s[8:9] offset:2560
.Ls4_n13:
	s_waitcnt lgkmcnt(4)
	v_lshlrev_b32_e32 v228, 16, v228
	v_mul_f32_e32 v232, v228, v222
	v_mul_f32_e32 v230, v232, v226
	v_mov_b32_e32 v231, 0
	ds_read_u16 v229, v7 offset:4080
	v_fma_f32 v230, -v208, v84, v230
	v_fma_f32 v231, -v209, v85, v231
	v_fma_f32 v230, -v210, v86, v230
	v_fma_f32 v231, -v211, v87, v231
	ds_read_b128 v[208:211], v8 offset:3872
	v_fma_f32 v230, -v212, v88, v230
	v_fma_f32 v231, -v213, v89, v231
	v_fma_f32 v230, -v214, v90, v230
	v_fma_f32 v231, -v215, v91, v231
	ds_read_b128 v[212:215], v8 offset:3888
	s_waitcnt lgkmcnt(6)
	v_fma_f32 v230, -v192, v92, v230
	v_fma_f32 v231, -v193, v93, v231
	v_fma_f32 v230, -v194, v94, v230
	v_fma_f32 v231, -v195, v95, v231
	ds_read_b128 v[192:195], v8 offset:4096
	s_waitcnt lgkmcnt(6)
	v_fma_f32 v230, -v196, v96, v230
	v_fma_f32 v231, -v197, v97, v231
	ds_read_b128 v[196:199], v8 offset:4112
	v_add_f32_e32 v98, v230, v231
	s_cbranch_vccz .Ls4_u14
	v_cvt_pk_bf16_f32 v233, -v98, v98
	global_store_short v6, v233, s[8:9] offset:3584
	s_branch .Ls4_n14
.Ls4_u14:
	global_store_dword v234, v98, s[8:9] offset:3072
.Ls4_n14:
	s_waitcnt lgkmcnt(4)
	v_lshlrev_b32_e32 v229, 16, v229
	v_mul_f32_e32 v232, v229, v223
	v_mul_f32_e32 v230, v232, v227
	v_mov_b32_e32 v231, 0
	ds_read_u16 v228, v7 offset:4352
	ds_read_b128 v[220:223], v8 offset:16720
	ds_read_b128 v[224:227], v8 offset:16464
	v_fma_f32 v230, -v200, v84, v230
	v_fma_f32 v231, -v201, v85, v231
	v_fma_f32 v230, -v202, v86, v230
	v_fma_f32 v231, -v203, v87, v231
	ds_read_b128 v[200:203], v8 offset:4128
	v_fma_f32 v230, -v204, v88, v230
	v_fma_f32 v231, -v205, v89, v231
	v_fma_f32 v230, -v206, v90, v230
	v_fma_f32 v231, -v207, v91, v231
	ds_read_b128 v[204:207], v8 offset:4144
	s_waitcnt lgkmcnt(8)
	v_fma_f32 v230, -v208, v92, v230
	v_fma_f32 v231, -v209, v93, v231
	v_fma_f32 v230, -v210, v94, v230
	v_fma_f32 v231, -v211, v95, v231
	ds_read_b128 v[208:211], v8 offset:4352
	s_waitcnt lgkmcnt(8)
	v_fma_f32 v230, -v212, v96, v230
	v_fma_f32 v231, -v213, v97, v231
	v_fma_f32 v230, -v214, v98, v230
	ds_read_b128 v[212:215], v8 offset:4368
	v_add_f32_e32 v99, v230, v231
	s_cbranch_vccz .Ls4_u15
	v_cvt_pk_bf16_f32 v233, -v99, v99
	global_store_short v6, v233, s[8:9] offset:3840
	s_branch .Ls4_n15
.Ls4_u15:
	global_store_dword v234, v99, s[8:9] offset:3584
.Ls4_n15:
	v_mul_f32_e32 v0, s16, v0
	v_mul_f32_e32 v1, s16, v1
	v_mul_f32_e32 v2, s16, v2
	v_mul_f32_e32 v3, s16, v3
	v_exp_f32_e32 v0, v0
	v_exp_f32_e32 v1, v1
	v_exp_f32_e32 v2, v2
	v_exp_f32_e32 v3, v3
	s_nop 0
	s_waitcnt lgkmcnt(6)
	v_lshlrev_b32_e32 v228, 16, v228
	v_mul_f32_e32 v232, v228, v216
	v_mul_f32_e32 v230, v232, v0
	v_mov_b32_e32 v231, 0
	ds_read_u16 v229, v7 offset:4624
	v_fma_f32 v230, -v192, v84, v230
	v_fma_f32 v231, -v193, v85, v231
	v_fma_f32 v230, -v194, v86, v230
	v_fma_f32 v231, -v195, v87, v231
	ds_read_b128 v[192:195], v8 offset:4384
	v_fma_f32 v230, -v196, v88, v230
	v_fma_f32 v231, -v197, v89, v231
	v_fma_f32 v230, -v198, v90, v230
	v_fma_f32 v231, -v199, v91, v231
	ds_read_b128 v[196:199], v8 offset:4400
	s_waitcnt lgkmcnt(6)
	v_fma_f32 v230, -v200, v92, v230
	v_fma_f32 v231, -v201, v93, v231
	v_fma_f32 v230, -v202, v94, v230
	v_fma_f32 v231, -v203, v95, v231
	ds_read_b128 v[200:203], v8 offset:4416
	s_waitcnt lgkmcnt(6)
	v_fma_f32 v230, -v204, v96, v230
	v_fma_f32 v231, -v205, v97, v231
	v_fma_f32 v230, -v206, v98, v230
	v_fma_f32 v231, -v207, v99, v231
	ds_read_b128 v[204:207], v8 offset:4608
	v_add_f32_e32 v100, v230, v231
	s_cbranch_vccz .Ls4_u16
	s_add_u32 s8, s8, 0x1000
	s_addc_u32 s9, s9, 0
	v_cvt_pk_bf16_f32 v233, -v100, v100
	global_store_short v6, v233, s[8:9] offset:0
	s_branch .Ls4_n16
.Ls4_u16:
	s_add_u32 s8, s8, 0x1000
	s_addc_u32 s9, s9, 0
	global_store_dword v234, v100, s[8:9] offset:0
.Ls4_n16:
	s_waitcnt lgkmcnt(4)
	v_lshlrev_b32_e32 v229, 16, v229
	v_mul_f32_e32 v232, v229, v217
	v_mul_f32_e32 v230, v232, v1
	v_mov_b32_e32 v231, 0
	ds_read_u16 v228, v7 offset:4896
	v_fma_f32 v230, -v208, v84, v230
	v_fma_f32 v231, -v209, v85, v231
	v_fma_f32 v230, -v210, v86, v230
	v_fma_f32 v231, -v211, v87, v231
	ds_read_b128 v[208:211], v8 offset:4624
	v_fma_f32 v230, -v212, v88, v230
	v_fma_f32 v231, -v213, v89, v231
	v_fma_f32 v230, -v214, v90, v230
	v_fma_f32 v231, -v215, v91, v231
	ds_read_b128 v[212:215], v8 offset:4640
	s_waitcnt lgkmcnt(6)
	v_fma_f32 v230, -v192, v92, v230
	v_fma_f32 v231, -v193, v93, v231
	v_fma_f32 v230, -v194, v94, v230
	v_fma_f32 v231, -v195, v95, v231
	ds_read_b128 v[192:195], v8 offset:4656
	s_waitcnt lgkmcnt(6)
	v_fma_f32 v230, -v196, v96, v230
	v_fma_f32 v231, -v197, v97, v231
	v_fma_f32 v230, -v198, v98, v230
	v_fma_f32 v231, -v199, v99, v231
	ds_read_b128 v[196:199], v8 offset:4672
	s_waitcnt lgkmcnt(6)
	v_fma_f32 v230, -v200, v100, v230
	ds_read_b128 v[200:203], v8 offset:4864
	v_add_f32_e32 v101, v230, v231
	s_cbranch_vccz .Ls4_u17
	v_cvt_pk_bf16_f32 v233, -v101, v101
	global_store_short v6, v233, s[8:9] offset:256
	s_branch .Ls4_n17
; #define LAS __attribute__((address_space(3)))
; __device__ __forceinline__ float bf2f(unsigned short x) { return __uint_as_float(((unsigned)x) << 16); }
; __device__ __forceinline__ void chunk_prep_phase(const Params& p, int bid, int nblk, LAS unsigned char* lds0) {
;     ...
;             { const float br = betg[18]; ab0 = (f32x2){bf2f(*(const LAS bf16_t*)(lg + P5_VS + 4896 + c * 2)) * br, bf2f(*(const LAS bf16_t*)(lg + P5_KS + 4896 + c * 2)) * br * __expf(decg[18])}; ab1 = (f32x2){0.f, 0.f}; } ab0 -= mq[3][0] * xy[0]; ab1 -= mq[3][1] * xy[1]; ab0 -= mq[3][2] * xy[2]; ab1 -= mq[3][3] * xy[3]; mq[3] = *(const LAS f32x4*)(Mg + 1220);
;             ab0 -= mq[4][0] * xy[4]; ab1 -= mq[4][1] * xy[5]; ab0 -= mq[4][2] * xy[6]; ab1 -= mq[4][3] * xy[7]; mq[4] = *(const LAS f32x4*)(Mg + 1224);
;             ab0 -= mq[5][0] * xy[8]; ab1 -= mq[5][1] * xy[9]; ab0 -= mq[5][2] * xy[10]; ab1 -= mq[5][3] * xy[11]; mq[5] = *(const LAS f32x4*)(Mg + 1228);
;             ab0 -= mq[0][0] * xy[12]; ab1 -= mq[0][1] * xy[13]; ab0 -= mq[0][2] * xy[14]; ab1 -= mq[0][3] * xy[15]; mq[0] = *(const LAS f32x4*)(Mg + 1232);
;             ab0 -= mq[1][0] * xy[16]; ab1 -= mq[1][1] * xy[17]; xy[18] = ab0 + ab1; up[2304] = xy[18][0]; wp[2304] = f2bf(-xy[18][1]); mq[1] = *(const LAS f32x4*)(Mg + 1280);
;             { const float br = betg[19]; ab0 = (f32x2){bf2f(*(const LAS bf16_t*)(lg + P5_VS + 5168 + c * 2)) * br, bf2f(*(const LAS bf16_t*)(lg + P5_KS + 5168 + c * 2)) * br * __expf(decg[19])}; ab1 = (f32x2){0.f, 0.f}; } ab0 -= mq[2][0] * xy[0]; ab1 -= mq[2][1] * xy[1]; ab0 -= mq[2][2] * xy[2]; ab1 -= mq[2][3] * xy[3]; mq[2] = *(const LAS f32x4*)(Mg + 1284);
;             ab0 -= mq[3][0] * xy[4]; ab1 -= mq[3][1] * xy[5]; ab0 -= mq[3][2] * xy[6]; ab1 -= mq[3][3] * xy[7]; mq[3] = *(const LAS f32x4*)(Mg + 1288);
;             ab0 -= mq[4][0] * xy[8]; ab1 -= mq[4][1] * xy[9]; ab0 -= mq[4][2] * xy[10]; ab1 -= mq[4][3] * xy[11]; mq[4] = *(const LAS f32x4*)(Mg + 1292);
;             ab0 -= mq[5][0] * xy[12]; ab1 -= mq[5][1] * xy[13]; ab0 -= mq[5][2] * xy[14]; ab1 -= mq[5][3] * xy[15]; mq[5] = *(const LAS f32x4*)(Mg + 1296);
;             ab0 -= mq[0][0] * xy[16]; ab1 -= mq[0][1] * xy[17]; ab0 -= mq[0][2] * xy[18]; xy[19] = ab0 + ab1; up[2432] = xy[19][0]; wp[2432] = f2bf(-xy[19][1]); mq[0] = *(const LAS f32x4*)(Mg + 1344);
.Ls4_u17:
	global_store_dword v234, v101, s[8:9] offset:512
.Ls4_n17:
	s_waitcnt lgkmcnt(5)
	v_lshlrev_b32_e32 v228, 16, v228
	v_mul_f32_e32 v232, v228, v218
	v_mul_f32_e32 v230, v232, v2
	v_mov_b32_e32 v231, 0
	ds_read_u16 v229, v7 offset:5168
	v_fma_f32 v230, -v204, v84, v230
	v_fma_f32 v231, -v205, v85, v231
	v_fma_f32 v230, -v206, v86, v230
	v_fma_f32 v231, -v207, v87, v231
	ds_read_b128 v[204:207], v8 offset:4880
	s_waitcnt lgkmcnt(6)
	v_fma_f32 v230, -v208, v88, v230
	v_fma_f32 v231, -v209, v89, v231
	v_fma_f32 v230, -v210, v90, v230
	v_fma_f32 v231, -v211, v91, v231
	ds_read_b128 v[208:211], v8 offset:4896
	s_waitcnt lgkmcnt(6)
	v_fma_f32 v230, -v212, v92, v230
	v_fma_f32 v231, -v213, v93, v231
	v_fma_f32 v230, -v214, v94, v230
	v_fma_f32 v231, -v215, v95, v231
	ds_read_b128 v[212:215], v8 offset:4912
	s_waitcnt lgkmcnt(6)
	v_fma_f32 v230, -v192, v96, v230
	v_fma_f32 v231, -v193, v97, v231
	v_fma_f32 v230, -v194, v98, v230
	v_fma_f32 v231, -v195, v99, v231
	ds_read_b128 v[192:195], v8 offset:4928
	s_waitcnt lgkmcnt(6)
	v_fma_f32 v230, -v196, v100, v230
	v_fma_f32 v231, -v197, v101, v231
	ds_read_b128 v[196:199], v8 offset:5120
	v_add_f32_e32 v102, v230, v231
	s_cbranch_vccz .Ls4_u18
	v_cvt_pk_bf16_f32 v233, -v102, v102
	global_store_short v6, v233, s[8:9] offset:512
	s_branch .Ls4_n18
.Ls4_u18:
	global_store_dword v234, v102, s[8:9] offset:1024
.Ls4_n18:
	s_waitcnt lgkmcnt(5)
	v_lshlrev_b32_e32 v229, 16, v229
	v_mul_f32_e32 v232, v229, v219
	v_mul_f32_e32 v230, v232, v3
	v_mov_b32_e32 v231, 0
	ds_read_u16 v228, v7 offset:5440
	ds_read_b128 v[216:219], v8 offset:16736
	ds_read_b128 v[0:3], v8 offset:16480
	v_fma_f32 v230, -v200, v84, v230
	v_fma_f32 v231, -v201, v85, v231
	v_fma_f32 v230, -v202, v86, v230
	v_fma_f32 v231, -v203, v87, v231
	ds_read_b128 v[200:203], v8 offset:5136
	s_waitcnt lgkmcnt(8)
	v_fma_f32 v230, -v204, v88, v230
	v_fma_f32 v231, -v205, v89, v231
	v_fma_f32 v230, -v206, v90, v230
	v_fma_f32 v231, -v207, v91, v231
	ds_read_b128 v[204:207], v8 offset:5152
	s_waitcnt lgkmcnt(8)
	v_fma_f32 v230, -v208, v92, v230
	v_fma_f32 v231, -v209, v93, v231
	v_fma_f32 v230, -v210, v94, v230
	v_fma_f32 v231, -v211, v95, v231
	ds_read_b128 v[208:211], v8 offset:5168
	s_waitcnt lgkmcnt(8)
	v_fma_f32 v230, -v212, v96, v230
	v_fma_f32 v231, -v213, v97, v231
	v_fma_f32 v230, -v214, v98, v230
	v_fma_f32 v231, -v215, v99, v231
	ds_read_b128 v[212:215], v8 offset:5184
	s_waitcnt lgkmcnt(8)
	v_fma_f32 v230, -v192, v100, v230
	v_fma_f32 v231, -v193, v101, v231
	v_fma_f32 v230, -v194, v102, v230
	ds_read_b128 v[192:195], v8 offset:5376
	v_add_f32_e32 v103, v230, v231
	s_cbranch_vccz .Ls4_u19
	v_cvt_pk_bf16_f32 v233, -v103, v103
	global_store_short v6, v233, s[8:9] offset:768
	s_branch .Ls4_n19
.Ls4_u19:
	global_store_dword v234, v103, s[8:9] offset:1536
.Ls4_n19:
	v_mul_f32_e32 v224, s16, v224
	v_mul_f32_e32 v225, s16, v225
	v_mul_f32_e32 v226, s16, v226
	v_mul_f32_e32 v227, s16, v227
	v_exp_f32_e32 v224, v224
	v_exp_f32_e32 v225, v225
	v_exp_f32_e32 v226, v226
	v_exp_f32_e32 v227, v227
	s_nop 0
	s_waitcnt lgkmcnt(7)
	v_lshlrev_b32_e32 v228, 16, v228
	v_mul_f32_e32 v232, v228, v220
	v_mul_f32_e32 v230, v232, v224
	v_mov_b32_e32 v231, 0
	ds_read_u16 v229, v7 offset:5712
	v_fma_f32 v230, -v196, v84, v230
	v_fma_f32 v231, -v197, v85, v231
	v_fma_f32 v230, -v198, v86, v230
	v_fma_f32 v231, -v199, v87, v231
	ds_read_b128 v[196:199], v8 offset:5392
	s_waitcnt lgkmcnt(6)
	v_fma_f32 v230, -v200, v88, v230
	v_fma_f32 v231, -v201, v89, v231
	v_fma_f32 v230, -v202, v90, v230
	v_fma_f32 v231, -v203, v91, v231
	ds_read_b128 v[200:203], v8 offset:5408
	s_waitcnt lgkmcnt(6)
	v_fma_f32 v230, -v204, v92, v230
	v_fma_f32 v231, -v205, v93, v231
	v_fma_f32 v230, -v206, v94, v230
	v_fma_f32 v231, -v207, v95, v231
	ds_read_b128 v[204:207], v8 offset:5424
	s_waitcnt lgkmcnt(6)
	v_fma_f32 v230, -v208, v96, v230
	v_fma_f32 v231, -v209, v97, v231
	v_fma_f32 v230, -v210, v98, v230
	v_fma_f32 v231, -v211, v99, v231
	ds_read_b128 v[208:211], v8 offset:5440
	s_waitcnt lgkmcnt(6)
	v_fma_f32 v230, -v212, v100, v230
	v_fma_f32 v231, -v213, v101, v231
	v_fma_f32 v230, -v214, v102, v230
	v_fma_f32 v231, -v215, v103, v231
	ds_read_b128 v[212:215], v8 offset:5456
	v_add_f32_e32 v104, v230, v231
	s_cbranch_vccz .Ls4_u20
	v_cvt_pk_bf16_f32 v233, -v104, v104
	global_store_short v6, v233, s[8:9] offset:1024
	s_branch .Ls4_n20
.Ls4_u20:
	global_store_dword v234, v104, s[8:9] offset:2048
.Ls4_n20:
	s_waitcnt lgkmcnt(5)
	v_lshlrev_b32_e32 v229, 16, v229
	v_mul_f32_e32 v232, v229, v221
	v_mul_f32_e32 v230, v232, v225
	v_mov_b32_e32 v231, 0
	ds_read_u16 v228, v7 offset:5984
	v_fma_f32 v230, -v192, v84, v230
	v_fma_f32 v231, -v193, v85, v231
	v_fma_f32 v230, -v194, v86, v230
	v_fma_f32 v231, -v195, v87, v231
	ds_read_b128 v[192:195], v8 offset:5632
	s_waitcnt lgkmcnt(6)
	v_fma_f32 v230, -v196, v88, v230
	v_fma_f32 v231, -v197, v89, v231
	v_fma_f32 v230, -v198, v90, v230
	v_fma_f32 v231, -v199, v91, v231
	ds_read_b128 v[196:199], v8 offset:5648
	s_waitcnt lgkmcnt(6)
	v_fma_f32 v230, -v200, v92, v230
	v_fma_f32 v231, -v201, v93, v231
	v_fma_f32 v230, -v202, v94, v230
	v_fma_f32 v231, -v203, v95, v231
	ds_read_b128 v[200:203], v8 offset:5664
	s_waitcnt lgkmcnt(6)
	v_fma_f32 v230, -v204, v96, v230
	v_fma_f32 v231, -v205, v97, v231
	v_fma_f32 v230, -v206, v98, v230
	v_fma_f32 v231, -v207, v99, v231
	ds_read_b128 v[204:207], v8 offset:5680
	s_waitcnt lgkmcnt(6)
	v_fma_f32 v230, -v208, v100, v230
	v_fma_f32 v231, -v209, v101, v231
	v_fma_f32 v230, -v210, v102, v230
	v_fma_f32 v231, -v211, v103, v231
	ds_read_b128 v[208:211], v8 offset:5696
	s_waitcnt lgkmcnt(6)
	v_fma_f32 v230, -v212, v104, v230
	ds_read_b128 v[212:215], v8 offset:5712
	v_add_f32_e32 v105, v230, v231
	s_cbranch_vccz .Ls4_u21
	v_cvt_pk_bf16_f32 v233, -v105, v105
	global_store_short v6, v233, s[8:9] offset:1280
	s_branch .Ls4_n21
; #define LAS __attribute__((address_space(3)))
; __device__ __forceinline__ void chunk_prep_phase(const Params& p, int bid, int nblk, LAS unsigned char* lds0) {
;     ...
;             { const float br = betg[22]; ab0 = (f32x2){bf2f(*(const LAS bf16_t*)(lg + P5_VS + 5984 + c * 2)) * br, bf2f(*(const LAS bf16_t*)(lg + P5_KS + 5984 + c * 2)) * br * __expf(decg[22])}; ab1 = (f32x2){0.f, 0.f}; } ab0 -= mq[0][0] * xy[0]; ab1 -= mq[0][1] * xy[1]; ab0 -= mq[0][2] * xy[2]; ab1 -= mq[0][3] * xy[3]; mq[0] = *(const LAS f32x4*)(Mg + 1472);
;             ab0 -= mq[1][0] * xy[4]; ab1 -= mq[1][1] * xy[5]; ab0 -= mq[1][2] * xy[6]; ab1 -= mq[1][3] * xy[7]; mq[1] = *(const LAS f32x4*)(Mg + 1476);
;             ab0 -= mq[2][0] * xy[8]; ab1 -= mq[2][1] * xy[9]; ab0 -= mq[2][2] * xy[10]; ab1 -= mq[2][3] * xy[11]; mq[2] = *(const LAS f32x4*)(Mg + 1480);
;             ab0 -= mq[3][0] * xy[12]; ab1 -= mq[3][1] * xy[13]; ab0 -= mq[3][2] * xy[14]; ab1 -= mq[3][3] * xy[15]; mq[3] = *(const LAS f32x4*)(Mg + 1484);
;             ab0 -= mq[4][0] * xy[16]; ab1 -= mq[4][1] * xy[17]; ab0 -= mq[4][2] * xy[18]; ab1 -= mq[4][3] * xy[19]; mq[4] = *(const LAS f32x4*)(Mg + 1488);
;             ab0 -= mq[5][0] * xy[20]; ab1 -= mq[5][1] * xy[21]; xy[22] = ab0 + ab1; up[2816] = xy[22][0]; wp[2816] = f2bf(-xy[22][1]); mq[5] = *(const LAS f32x4*)(Mg + 1492);
;             { const float br = betg[23]; ab0 = (f32x2){bf2f(*(const LAS bf16_t*)(lg + P5_VS + 6256 + c * 2)) * br, bf2f(*(const LAS bf16_t*)(lg + P5_KS + 6256 + c * 2)) * br * __expf(decg[23])}; ab1 = (f32x2){0.f, 0.f}; } ab0 -= mq[0][0] * xy[0]; ab1 -= mq[0][1] * xy[1]; ab0 -= mq[0][2] * xy[2]; ab1 -= mq[0][3] * xy[3]; mq[0] = *(const LAS f32x4*)(Mg + 1536);
;             ab0 -= mq[1][0] * xy[4]; ab1 -= mq[1][1] * xy[5]; ab0 -= mq[1][2] * xy[6]; ab1 -= mq[1][3] * xy[7]; mq[1] = *(const LAS f32x4*)(Mg + 1540);
;             ab0 -= mq[2][0] * xy[8]; ab1 -= mq[2][1] * xy[9]; ab0 -= mq[2][2] * xy[10]; ab1 -= mq[2][3] * xy[11]; mq[2] = *(const LAS f32x4*)(Mg + 1544);
;             ab0 -= mq[3][0] * xy[12]; ab1 -= mq[3][1] * xy[13]; ab0 -= mq[3][2] * xy[14]; ab1 -= mq[3][3] * xy[15]; mq[3] = *(const LAS f32x4*)(Mg + 1548);
;             ab0 -= mq[4][0] * xy[16]; ab1 -= mq[4][1] * xy[17]; ab0 -= mq[4][2] * xy[18]; ab1 -= mq[4][3] * xy[19]; mq[4] = *(const LAS f32x4*)(Mg + 1552);
.Ls4_u21:
	global_store_dword v234, v105, s[8:9] offset:2560
.Ls4_n21:
	s_waitcnt lgkmcnt(6)
	v_lshlrev_b32_e32 v228, 16, v228
	v_mul_f32_e32 v232, v228, v222
	v_mul_f32_e32 v230, v232, v226
	v_mov_b32_e32 v231, 0
	ds_read_u16 v229, v7 offset:6256
	s_waitcnt lgkmcnt(6)
	v_fma_f32 v230, -v192, v84, v230
	v_fma_f32 v231, -v193, v85, v231
	v_fma_f32 v230, -v194, v86, v230
	v_fma_f32 v231, -v195, v87, v231
	ds_read_b128 v[192:195], v8 offset:5888
	s_waitcnt lgkmcnt(6)
	v_fma_f32 v230, -v196, v88, v230
	v_fma_f32 v231, -v197, v89, v231
	v_fma_f32 v230, -v198, v90, v230
	v_fma_f32 v231, -v199, v91, v231
	ds_read_b128 v[196:199], v8 offset:5904
	s_waitcnt lgkmcnt(6)
	v_fma_f32 v230, -v200, v92, v230
	v_fma_f32 v231, -v201, v93, v231
	v_fma_f32 v230, -v202, v94, v230
	v_fma_f32 v231, -v203, v95, v231
	ds_read_b128 v[200:203], v8 offset:5920
	s_waitcnt lgkmcnt(6)
	v_fma_f32 v230, -v204, v96, v230
	v_fma_f32 v231, -v205, v97, v231
	v_fma_f32 v230, -v206, v98, v230
	v_fma_f32 v231, -v207, v99, v231
	ds_read_b128 v[204:207], v8 offset:5936
	s_waitcnt lgkmcnt(6)
	v_fma_f32 v230, -v208, v100, v230
	v_fma_f32 v231, -v209, v101, v231
	v_fma_f32 v230, -v210, v102, v230
	v_fma_f32 v231, -v211, v103, v231
	ds_read_b128 v[208:211], v8 offset:5952
	s_waitcnt lgkmcnt(6)
	v_fma_f32 v230, -v212, v104, v230
	v_fma_f32 v231, -v213, v105, v231
	ds_read_b128 v[212:215], v8 offset:5968
	v_add_f32_e32 v106, v230, v231
	s_cbranch_vccz .Ls4_u22
	v_cvt_pk_bf16_f32 v233, -v106, v106
	global_store_short v6, v233, s[8:9] offset:1536
	s_branch .Ls4_n22
.Ls4_u22:
	global_store_dword v234, v106, s[8:9] offset:3072
.Ls4_n22:
	s_waitcnt lgkmcnt(6)
	v_lshlrev_b32_e32 v229, 16, v229
	v_mul_f32_e32 v232, v229, v223
	v_mul_f32_e32 v230, v232, v227
	v_mov_b32_e32 v231, 0
	ds_read_u16 v228, v7 offset:6528
	ds_read_b128 v[220:223], v8 offset:16752
	ds_read_b128 v[224:227], v8 offset:16496
	s_waitcnt lgkmcnt(8)
	v_fma_f32 v230, -v192, v84, v230
	v_fma_f32 v231, -v193, v85, v231
	v_fma_f32 v230, -v194, v86, v230
	v_fma_f32 v231, -v195, v87, v231
	ds_read_b128 v[192:195], v8 offset:6144
	s_waitcnt lgkmcnt(8)
	v_fma_f32 v230, -v196, v88, v230
	v_fma_f32 v231, -v197, v89, v231
	v_fma_f32 v230, -v198, v90, v230
	v_fma_f32 v231, -v199, v91, v231
	ds_read_b128 v[196:199], v8 offset:6160
	s_waitcnt lgkmcnt(8)
	v_fma_f32 v230, -v200, v92, v230
	v_fma_f32 v231, -v201, v93, v231
	v_fma_f32 v230, -v202, v94, v230
	v_fma_f32 v231, -v203, v95, v231
	ds_read_b128 v[200:203], v8 offset:6176
	s_waitcnt lgkmcnt(8)
	v_fma_f32 v230, -v204, v96, v230
	v_fma_f32 v231, -v205, v97, v231
	v_fma_f32 v230, -v206, v98, v230
	v_fma_f32 v231, -v207, v99, v231
	ds_read_b128 v[204:207], v8 offset:6192
	s_waitcnt lgkmcnt(8)
	v_fma_f32 v230, -v208, v100, v230
	v_fma_f32 v231, -v209, v101, v231
	v_fma_f32 v230, -v210, v102, v230
	v_fma_f32 v231, -v211, v103, v231
	ds_read_b128 v[208:211], v8 offset:6208
	s_waitcnt lgkmcnt(8)
	v_fma_f32 v230, -v212, v104, v230
	v_fma_f32 v231, -v213, v105, v231
	v_fma_f32 v230, -v214, v106, v230
	ds_read_b128 v[212:215], v8 offset:6224
	v_add_f32_e32 v107, v230, v231
	s_cbranch_vccz .Ls4_u23
	v_cvt_pk_bf16_f32 v233, -v107, v107
	global_store_short v6, v233, s[8:9] offset:1792
	s_branch .Ls4_n23
.Ls4_u23:
	global_store_dword v234, v107, s[8:9] offset:3584
.Ls4_n23:
	v_mul_f32_e32 v0, s16, v0
	v_mul_f32_e32 v1, s16, v1
	v_mul_f32_e32 v2, s16, v2
	v_mul_f32_e32 v3, s16, v3
	v_exp_f32_e32 v0, v0
	v_exp_f32_e32 v1, v1
	v_exp_f32_e32 v2, v2
	v_exp_f32_e32 v3, v3
	s_nop 0
	s_waitcnt lgkmcnt(8)
	v_lshlrev_b32_e32 v228, 16, v228
	v_mul_f32_e32 v232, v228, v216
	v_mul_f32_e32 v230, v232, v0
	v_mov_b32_e32 v231, 0
	ds_read_u16 v229, v7 offset:6800
	s_waitcnt lgkmcnt(6)
	v_fma_f32 v230, -v192, v84, v230
	v_fma_f32 v231, -v193, v85, v231
	v_fma_f32 v230, -v194, v86, v230
	v_fma_f32 v231, -v195, v87, v231
	ds_read_b128 v[192:195], v8 offset:6400
	s_waitcnt lgkmcnt(6)
	v_fma_f32 v230, -v196, v88, v230
	v_fma_f32 v231, -v197, v89, v231
	v_fma_f32 v230, -v198, v90, v230
	v_fma_f32 v231, -v199, v91, v231
	ds_read_b128 v[196:199], v8 offset:6416
	s_waitcnt lgkmcnt(6)
	v_fma_f32 v230, -v200, v92, v230
	v_fma_f32 v231, -v201, v93, v231
	v_fma_f32 v230, -v202, v94, v230
	v_fma_f32 v231, -v203, v95, v231
	ds_read_b128 v[200:203], v8 offset:6432
	s_waitcnt lgkmcnt(6)
	v_fma_f32 v230, -v204, v96, v230
	v_fma_f32 v231, -v205, v97, v231
	v_fma_f32 v230, -v206, v98, v230
	v_fma_f32 v231, -v207, v99, v231
	ds_read_b128 v[204:207], v8 offset:6448
	s_waitcnt lgkmcnt(6)
	v_fma_f32 v230, -v208, v100, v230
	v_fma_f32 v231, -v209, v101, v231
	v_fma_f32 v230, -v210, v102, v230
	v_fma_f32 v231, -v211, v103, v231
	ds_read_b128 v[208:211], v8 offset:6464
	s_waitcnt lgkmcnt(6)
	v_fma_f32 v230, -v212, v104, v230
	v_fma_f32 v231, -v213, v105, v231
	v_fma_f32 v230, -v214, v106, v230
	v_fma_f32 v231, -v215, v107, v231
	ds_read_b128 v[212:215], v8 offset:6480
	v_add_f32_e32 v108, v230, v231
	s_cbranch_vccz .Ls4_u24
	v_cvt_pk_bf16_f32 v233, -v108, v108
	global_store_short v6, v233, s[8:9] offset:2048
	s_branch .Ls4_n24
.Ls4_u24:
	s_add_u32 s8, s8, 0x1000
	s_addc_u32 s9, s9, 0
	global_store_dword v234, v108, s[8:9] offset:0
; #define LAS __attribute__((address_space(3)))
; __device__ __forceinline__ float bf2f(unsigned short x) { return __uint_as_float(((unsigned)x) << 16); }
; __device__ __forceinline__ void chunk_prep_phase(const Params& p, int bid, int nblk, LAS unsigned char* lds0) {
;     ...
;             { const float br = betg[25]; ab0 = (f32x2){bf2f(*(const LAS bf16_t*)(lg + P5_VS + 6800 + c * 2)) * br, bf2f(*(const LAS bf16_t*)(lg + P5_KS + 6800 + c * 2)) * br * __expf(decg[25])}; ab1 = (f32x2){0.f, 0.f}; } ab0 -= mq[0][0] * xy[0]; ab1 -= mq[0][1] * xy[1]; ab0 -= mq[0][2] * xy[2]; ab1 -= mq[0][3] * xy[3]; mq[0] = *(const LAS f32x4*)(Mg + 1624);
;             ab0 -= mq[1][0] * xy[4]; ab1 -= mq[1][1] * xy[5]; ab0 -= mq[1][2] * xy[6]; ab1 -= mq[1][3] * xy[7]; mq[1] = *(const LAS f32x4*)(Mg + 1664);
;             ab0 -= mq[2][0] * xy[8]; ab1 -= mq[2][1] * xy[9]; ab0 -= mq[2][2] * xy[10]; ab1 -= mq[2][3] * xy[11]; mq[2] = *(const LAS f32x4*)(Mg + 1668);
;             ab0 -= mq[3][0] * xy[12]; ab1 -= mq[3][1] * xy[13]; ab0 -= mq[3][2] * xy[14]; ab1 -= mq[3][3] * xy[15]; mq[3] = *(const LAS f32x4*)(Mg + 1672);
;             ab0 -= mq[4][0] * xy[16]; ab1 -= mq[4][1] * xy[17]; ab0 -= mq[4][2] * xy[18]; ab1 -= mq[4][3] * xy[19]; mq[4] = *(const LAS f32x4*)(Mg + 1676);
;             ab0 -= mq[5][0] * xy[20]; ab1 -= mq[5][1] * xy[21]; ab0 -= mq[5][2] * xy[22]; ab1 -= mq[5][3] * xy[23]; mq[5] = *(const LAS f32x4*)(Mg + 1680);
;             ab0 -= mq[0][0] * xy[24]; xy[25] = ab0 + ab1; up[3200] = xy[25][0]; wp[3200] = f2bf(-xy[25][1]); mq[0] = *(const LAS f32x4*)(Mg + 1684);
;             { const float br = betg[26]; ab0 = (f32x2){bf2f(*(const LAS bf16_t*)(lg + P5_VS + 7072 + c * 2)) * br, bf2f(*(const LAS bf16_t*)(lg + P5_KS + 7072 + c * 2)) * br * __expf(decg[26])}; ab1 = (f32x2){0.f, 0.f}; } ab0 -= mq[1][0] * xy[0]; ab1 -= mq[1][1] * xy[1]; ab0 -= mq[1][2] * xy[2]; ab1 -= mq[1][3] * xy[3]; mq[1] = *(const LAS f32x4*)(Mg + 1688);
;             ab0 -= mq[2][0] * xy[4]; ab1 -= mq[2][1] * xy[5]; ab0 -= mq[2][2] * xy[6]; ab1 -= mq[2][3] * xy[7]; mq[2] = *(const LAS f32x4*)(Mg + 1728);
;             ab0 -= mq[3][0] * xy[8]; ab1 -= mq[3][1] * xy[9]; ab0 -= mq[3][2] * xy[10]; ab1 -= mq[3][3] * xy[11]; mq[3] = *(const LAS f32x4*)(Mg + 1732);
;             ab0 -= mq[4][0] * xy[12]; ab1 -= mq[4][1] * xy[13]; ab0 -= mq[4][2] * xy[14]; ab1 -= mq[4][3] * xy[15]; mq[4] = *(const LAS f32x4*)(Mg + 1736);
.Ls4_n24:
	s_waitcnt lgkmcnt(6)
	v_lshlrev_b32_e32 v229, 16, v229
	v_mul_f32_e32 v232, v229, v217
	v_mul_f32_e32 v230, v232, v1
	v_mov_b32_e32 v231, 0
	ds_read_u16 v228, v7 offset:7072
	s_waitcnt lgkmcnt(6)
	v_fma_f32 v230, -v192, v84, v230
	v_fma_f32 v231, -v193, v85, v231
	v_fma_f32 v230, -v194, v86, v230
	v_fma_f32 v231, -v195, v87, v231
	ds_read_b128 v[192:195], v8 offset:6496
	s_waitcnt lgkmcnt(6)
	v_fma_f32 v230, -v196, v88, v230
	v_fma_f32 v231, -v197, v89, v231
	v_fma_f32 v230, -v198, v90, v230
	v_fma_f32 v231, -v199, v91, v231
	ds_read_b128 v[196:199], v8 offset:6656
	s_waitcnt lgkmcnt(6)
	v_fma_f32 v230, -v200, v92, v230
	v_fma_f32 v231, -v201, v93, v231
	v_fma_f32 v230, -v202, v94, v230
	v_fma_f32 v231, -v203, v95, v231
	ds_read_b128 v[200:203], v8 offset:6672
	s_waitcnt lgkmcnt(6)
	v_fma_f32 v230, -v204, v96, v230
	v_fma_f32 v231, -v205, v97, v231
	v_fma_f32 v230, -v206, v98, v230
	v_fma_f32 v231, -v207, v99, v231
	ds_read_b128 v[204:207], v8 offset:6688
	s_waitcnt lgkmcnt(6)
	v_fma_f32 v230, -v208, v100, v230
	v_fma_f32 v231, -v209, v101, v231
	v_fma_f32 v230, -v210, v102, v230
	v_fma_f32 v231, -v211, v103, v231
	ds_read_b128 v[208:211], v8 offset:6704
	s_waitcnt lgkmcnt(6)
	v_fma_f32 v230, -v212, v104, v230
	v_fma_f32 v231, -v213, v105, v231
	v_fma_f32 v230, -v214, v106, v230
	v_fma_f32 v231, -v215, v107, v231
	ds_read_b128 v[212:215], v8 offset:6720
	s_waitcnt lgkmcnt(5)
	v_fma_f32 v230, -v192, v108, v230
	ds_read_b128 v[192:195], v8 offset:6736
	v_add_f32_e32 v109, v230, v231
	s_cbranch_vccz .Ls4_u25
	v_cvt_pk_bf16_f32 v233, -v109, v109
	global_store_short v6, v233, s[8:9] offset:2304
	s_branch .Ls4_n25
.Ls4_u25:
	global_store_dword v234, v109, s[8:9] offset:512
.Ls4_n25:
	v_lshlrev_b32_e32 v228, 16, v228
	v_mul_f32_e32 v232, v228, v218
	v_mul_f32_e32 v230, v232, v2
	v_mov_b32_e32 v231, 0
	ds_read_u16 v229, v7 offset:7344
	s_waitcnt lgkmcnt(6)
	v_fma_f32 v230, -v196, v84, v230
	v_fma_f32 v231, -v197, v85, v231
	v_fma_f32 v230, -v198, v86, v230
	v_fma_f32 v231, -v199, v87, v231
	ds_read_b128 v[196:199], v8 offset:6752
	s_waitcnt lgkmcnt(6)
	v_fma_f32 v230, -v200, v88, v230
	v_fma_f32 v231, -v201, v89, v231
	v_fma_f32 v230, -v202, v90, v230
	v_fma_f32 v231, -v203, v91, v231
	ds_read_b128 v[200:203], v8 offset:6912
	s_waitcnt lgkmcnt(6)
	v_fma_f32 v230, -v204, v92, v230
	v_fma_f32 v231, -v205, v93, v231
	v_fma_f32 v230, -v206, v94, v230
	v_fma_f32 v231, -v207, v95, v231
	ds_read_b128 v[204:207], v8 offset:6928
	s_waitcnt lgkmcnt(6)
	v_fma_f32 v230, -v208, v96, v230
	v_fma_f32 v231, -v209, v97, v231
	v_fma_f32 v230, -v210, v98, v230
	v_fma_f32 v231, -v211, v99, v231
	ds_read_b128 v[208:211], v8 offset:6944
	s_waitcnt lgkmcnt(6)
	v_fma_f32 v230, -v212, v100, v230
	v_fma_f32 v231, -v213, v101, v231
	v_fma_f32 v230, -v214, v102, v230
	v_fma_f32 v231, -v215, v103, v231
	ds_read_b128 v[212:215], v8 offset:6960
	s_waitcnt lgkmcnt(6)
	v_fma_f32 v230, -v192, v104, v230
	v_fma_f32 v231, -v193, v105, v231
	v_fma_f32 v230, -v194, v106, v230
	v_fma_f32 v231, -v195, v107, v231
	ds_read_b128 v[192:195], v8 offset:6976
	s_waitcnt lgkmcnt(5)
	v_fma_f32 v230, -v196, v108, v230
	v_fma_f32 v231, -v197, v109, v231
	ds_read_b128 v[196:199], v8 offset:6992
	v_add_f32_e32 v110, v230, v231
	s_cbranch_vccz .Ls4_u26
	v_cvt_pk_bf16_f32 v233, -v110, v110
	global_store_short v6, v233, s[8:9] offset:2560
	s_branch .Ls4_n26
.Ls4_u26:
	global_store_dword v234, v110, s[8:9] offset:1024
.Ls4_n26:
	v_lshlrev_b32_e32 v229, 16, v229
	v_mul_f32_e32 v232, v229, v219
	v_mul_f32_e32 v230, v232, v3
	v_mov_b32_e32 v231, 0
	ds_read_u16 v228, v7 offset:7616
	ds_read_b128 v[216:219], v8 offset:16768
	ds_read_b128 v[0:3], v8 offset:16512
	s_waitcnt lgkmcnt(8)
	v_fma_f32 v230, -v200, v84, v230
	v_fma_f32 v231, -v201, v85, v231
	v_fma_f32 v230, -v202, v86, v230
	v_fma_f32 v231, -v203, v87, v231
	ds_read_b128 v[200:203], v8 offset:7008
	s_waitcnt lgkmcnt(8)
	v_fma_f32 v230, -v204, v88, v230
	v_fma_f32 v231, -v205, v89, v231
	v_fma_f32 v230, -v206, v90, v230
	v_fma_f32 v231, -v207, v91, v231
	ds_read_b128 v[204:207], v8 offset:7168
	s_waitcnt lgkmcnt(8)
	v_fma_f32 v230, -v208, v92, v230
	v_fma_f32 v231, -v209, v93, v231
	v_fma_f32 v230, -v210, v94, v230
	v_fma_f32 v231, -v211, v95, v231
	ds_read_b128 v[208:211], v8 offset:7184
	s_waitcnt lgkmcnt(8)
	v_fma_f32 v230, -v212, v96, v230
	v_fma_f32 v231, -v213, v97, v231
	v_fma_f32 v230, -v214, v98, v230
	v_fma_f32 v231, -v215, v99, v231
	ds_read_b128 v[212:215], v8 offset:7200
	s_waitcnt lgkmcnt(8)
	v_fma_f32 v230, -v192, v100, v230
	v_fma_f32 v231, -v193, v101, v231
	v_fma_f32 v230, -v194, v102, v230
	v_fma_f32 v231, -v195, v103, v231
	ds_read_b128 v[192:195], v8 offset:7216
	s_waitcnt lgkmcnt(8)
	v_fma_f32 v230, -v196, v104, v230
	v_fma_f32 v231, -v197, v105, v231
	v_fma_f32 v230, -v198, v106, v230
	v_fma_f32 v231, -v199, v107, v231
	ds_read_b128 v[196:199], v8 offset:7232
	s_waitcnt lgkmcnt(5)
	v_fma_f32 v230, -v200, v108, v230
	v_fma_f32 v231, -v201, v109, v231
	v_fma_f32 v230, -v202, v110, v230
	ds_read_b128 v[200:203], v8 offset:7248
	v_add_f32_e32 v111, v230, v231
	s_cbranch_vccz .Ls4_u27
	v_cvt_pk_bf16_f32 v233, -v111, v111
	global_store_short v6, v233, s[8:9] offset:2816
	s_branch .Ls4_n27
.Ls4_u27:
	global_store_dword v234, v111, s[8:9] offset:1536
; #define LAS __attribute__((address_space(3)))
; __device__ __forceinline__ void chunk_prep_phase(const Params& p, int bid, int nblk, LAS unsigned char* lds0) {
;     ...
;             { const float br = betg[28]; ab0 = (f32x2){bf2f(*(const LAS bf16_t*)(lg + P5_VS + 7616 + c * 2)) * br, bf2f(*(const LAS bf16_t*)(lg + P5_KS + 7616 + c * 2)) * br * __expf(decg[28])}; ab1 = (f32x2){0.f, 0.f}; } ab0 -= mq[3][0] * xy[0]; ab1 -= mq[3][1] * xy[1]; ab0 -= mq[3][2] * xy[2]; ab1 -= mq[3][3] * xy[3]; mq[3] = *(const LAS f32x4*)(Mg + 1816);
;             ab0 -= mq[4][0] * xy[4]; ab1 -= mq[4][1] * xy[5]; ab0 -= mq[4][2] * xy[6]; ab1 -= mq[4][3] * xy[7]; mq[4] = *(const LAS f32x4*)(Mg + 1856);
;             ab0 -= mq[5][0] * xy[8]; ab1 -= mq[5][1] * xy[9]; ab0 -= mq[5][2] * xy[10]; ab1 -= mq[5][3] * xy[11]; mq[5] = *(const LAS f32x4*)(Mg + 1860);
;             ab0 -= mq[0][0] * xy[12]; ab1 -= mq[0][1] * xy[13]; ab0 -= mq[0][2] * xy[14]; ab1 -= mq[0][3] * xy[15]; mq[0] = *(const LAS f32x4*)(Mg + 1864);
;             ab0 -= mq[1][0] * xy[16]; ab1 -= mq[1][1] * xy[17]; ab0 -= mq[1][2] * xy[18]; ab1 -= mq[1][3] * xy[19]; mq[1] = *(const LAS f32x4*)(Mg + 1868);
;             ab0 -= mq[2][0] * xy[20]; ab1 -= mq[2][1] * xy[21]; ab0 -= mq[2][2] * xy[22]; ab1 -= mq[2][3] * xy[23]; mq[2] = *(const LAS f32x4*)(Mg + 1872);
;             ab0 -= mq[3][0] * xy[24]; ab1 -= mq[3][1] * xy[25]; ab0 -= mq[3][2] * xy[26]; ab1 -= mq[3][3] * xy[27]; xy[28] = ab0 + ab1; up[3584] = xy[28][0]; wp[3584] = f2bf(-xy[28][1]); mq[3] = *(const LAS f32x4*)(Mg + 1876);
;             { const float br = betg[29]; ab0 = (f32x2){bf2f(*(const LAS bf16_t*)(lg + P5_VS + 7888 + c * 2)) * br, bf2f(*(const LAS bf16_t*)(lg + P5_KS + 7888 + c * 2)) * br * __expf(decg[29])}; ab1 = (f32x2){0.f, 0.f}; } ab0 -= mq[4][0] * xy[0]; ab1 -= mq[4][1] * xy[1]; ab0 -= mq[4][2] * xy[2]; ab1 -= mq[4][3] * xy[3]; mq[4] = *(const LAS f32x4*)(Mg + 1880);
;             ab0 -= mq[5][0] * xy[4]; ab1 -= mq[5][1] * xy[5]; ab0 -= mq[5][2] * xy[6]; ab1 -= mq[5][3] * xy[7]; mq[5] = *(const LAS f32x4*)(Mg + 1884);
;             ab0 -= mq[0][0] * xy[8]; ab1 -= mq[0][1] * xy[9]; ab0 -= mq[0][2] * xy[10]; ab1 -= mq[0][3] * xy[11]; mq[0] = *(const LAS f32x4*)(Mg + 1920);
;             ab0 -= mq[1][0] * xy[12]; ab1 -= mq[1][1] * xy[13]; ab0 -= mq[1][2] * xy[14]; ab1 -= mq[1][3] * xy[15]; mq[1] = *(const LAS f32x4*)(Mg + 1924);
.Ls4_n27:
	v_mul_f32_e32 v224, s16, v224
	v_mul_f32_e32 v225, s16, v225
	v_mul_f32_e32 v226, s16, v226
	v_mul_f32_e32 v227, s16, v227
	v_exp_f32_e32 v224, v224
	v_exp_f32_e32 v225, v225
	v_exp_f32_e32 v226, v226
	v_exp_f32_e32 v227, v227
	s_nop 0
	v_lshlrev_b32_e32 v228, 16, v228
	v_mul_f32_e32 v232, v228, v220
	v_mul_f32_e32 v230, v232, v224
	v_mov_b32_e32 v231, 0
	ds_read_u16 v229, v7 offset:7888
	s_waitcnt lgkmcnt(6)
	v_fma_f32 v230, -v204, v84, v230
	v_fma_f32 v231, -v205, v85, v231
	v_fma_f32 v230, -v206, v86, v230
	v_fma_f32 v231, -v207, v87, v231
	ds_read_b128 v[204:207], v8 offset:7264
	s_waitcnt lgkmcnt(6)
	v_fma_f32 v230, -v208, v88, v230
	v_fma_f32 v231, -v209, v89, v231
	v_fma_f32 v230, -v210, v90, v230
	v_fma_f32 v231, -v211, v91, v231
	ds_read_b128 v[208:211], v8 offset:7424
	s_waitcnt lgkmcnt(6)
	v_fma_f32 v230, -v212, v92, v230
	v_fma_f32 v231, -v213, v93, v231
	v_fma_f32 v230, -v214, v94, v230
	v_fma_f32 v231, -v215, v95, v231
	ds_read_b128 v[212:215], v8 offset:7440
	s_waitcnt lgkmcnt(6)
	v_fma_f32 v230, -v192, v96, v230
	v_fma_f32 v231, -v193, v97, v231
	v_fma_f32 v230, -v194, v98, v230
	v_fma_f32 v231, -v195, v99, v231
	ds_read_b128 v[192:195], v8 offset:7456
	s_waitcnt lgkmcnt(6)
	v_fma_f32 v230, -v196, v100, v230
	v_fma_f32 v231, -v197, v101, v231
	v_fma_f32 v230, -v198, v102, v230
	v_fma_f32 v231, -v199, v103, v231
	ds_read_b128 v[196:199], v8 offset:7472
	s_waitcnt lgkmcnt(6)
	v_fma_f32 v230, -v200, v104, v230
	v_fma_f32 v231, -v201, v105, v231
	v_fma_f32 v230, -v202, v106, v230
	v_fma_f32 v231, -v203, v107, v231
	ds_read_b128 v[200:203], v8 offset:7488
	s_waitcnt lgkmcnt(5)
	v_fma_f32 v230, -v204, v108, v230
	v_fma_f32 v231, -v205, v109, v231
	v_fma_f32 v230, -v206, v110, v230
	v_fma_f32 v231, -v207, v111, v231
	ds_read_b128 v[204:207], v8 offset:7504
	v_add_f32_e32 v112, v230, v231
	s_cbranch_vccz .Ls4_u28
	v_cvt_pk_bf16_f32 v233, -v112, v112
	global_store_short v6, v233, s[8:9] offset:3072
	s_branch .Ls4_n28
.Ls4_u28:
	global_store_dword v234, v112, s[8:9] offset:2048
.Ls4_n28:
	v_lshlrev_b32_e32 v229, 16, v229
	v_mul_f32_e32 v232, v229, v221
	v_mul_f32_e32 v230, v232, v225
	v_mov_b32_e32 v231, 0
	ds_read_u16 v228, v7 offset:8160
	s_waitcnt lgkmcnt(6)
	v_fma_f32 v230, -v208, v84, v230
	v_fma_f32 v231, -v209, v85, v231
	v_fma_f32 v230, -v210, v86, v230
	v_fma_f32 v231, -v211, v87, v231
	ds_read_b128 v[208:211], v8 offset:7520
	s_waitcnt lgkmcnt(6)
	v_fma_f32 v230, -v212, v88, v230
	v_fma_f32 v231, -v213, v89, v231
	v_fma_f32 v230, -v214, v90, v230
	v_fma_f32 v231, -v215, v91, v231
	ds_read_b128 v[212:215], v8 offset:7536
	s_waitcnt lgkmcnt(6)
	v_fma_f32 v230, -v192, v92, v230
	v_fma_f32 v231, -v193, v93, v231
	v_fma_f32 v230, -v194, v94, v230
	v_fma_f32 v231, -v195, v95, v231
	ds_read_b128 v[192:195], v8 offset:7680
	s_waitcnt lgkmcnt(6)
	v_fma_f32 v230, -v196, v96, v230
	v_fma_f32 v231, -v197, v97, v231
	v_fma_f32 v230, -v198, v98, v230
	v_fma_f32 v231, -v199, v99, v231
	ds_read_b128 v[196:199], v8 offset:7696
	s_waitcnt lgkmcnt(6)
	v_fma_f32 v230, -v200, v100, v230
	v_fma_f32 v231, -v201, v101, v231
	v_fma_f32 v230, -v202, v102, v230
	v_fma_f32 v231, -v203, v103, v231
	ds_read_b128 v[200:203], v8 offset:7712
	s_waitcnt lgkmcnt(6)
	v_fma_f32 v230, -v204, v104, v230
	v_fma_f32 v231, -v205, v105, v231
	v_fma_f32 v230, -v206, v106, v230
	v_fma_f32 v231, -v207, v107, v231
	ds_read_b128 v[204:207], v8 offset:7728
	s_waitcnt lgkmcnt(5)
	v_fma_f32 v230, -v208, v108, v230
	v_fma_f32 v231, -v209, v109, v231
	v_fma_f32 v230, -v210, v110, v230
	v_fma_f32 v231, -v211, v111, v231
	ds_read_b128 v[208:211], v8 offset:7744
	s_waitcnt lgkmcnt(5)
	v_fma_f32 v230, -v212, v112, v230
	ds_read_b128 v[212:215], v8 offset:7760
	v_add_f32_e32 v113, v230, v231
	s_cbranch_vccz .Ls4_u29
	v_cvt_pk_bf16_f32 v233, -v113, v113
	global_store_short v6, v233, s[8:9] offset:3328
	s_branch .Ls4_n29
.Ls4_u29:
	global_store_dword v234, v113, s[8:9] offset:2560
.Ls4_n29:
	v_lshlrev_b32_e32 v228, 16, v228
	v_mul_f32_e32 v232, v228, v222
	v_mul_f32_e32 v230, v232, v226
	v_mov_b32_e32 v231, 0
	ds_read_u16 v229, v7 offset:8432
	s_waitcnt lgkmcnt(6)
	v_fma_f32 v230, -v192, v84, v230
	v_fma_f32 v231, -v193, v85, v231
	v_fma_f32 v230, -v194, v86, v230
	v_fma_f32 v231, -v195, v87, v231
	ds_read_b128 v[192:195], v8 offset:7776
	s_waitcnt lgkmcnt(6)
	v_fma_f32 v230, -v196, v88, v230
	v_fma_f32 v231, -v197, v89, v231
	v_fma_f32 v230, -v198, v90, v230
	v_fma_f32 v231, -v199, v91, v231
	ds_read_b128 v[196:199], v8 offset:7792
	s_waitcnt lgkmcnt(6)
	v_fma_f32 v230, -v200, v92, v230
	v_fma_f32 v231, -v201, v93, v231
	v_fma_f32 v230, -v202, v94, v230
	v_fma_f32 v231, -v203, v95, v231
	ds_read_b128 v[200:203], v8 offset:7936
	s_waitcnt lgkmcnt(6)
	v_fma_f32 v230, -v204, v96, v230
	v_fma_f32 v231, -v205, v97, v231
	v_fma_f32 v230, -v206, v98, v230
	v_fma_f32 v231, -v207, v99, v231
	ds_read_b128 v[204:207], v8 offset:7952
	s_waitcnt lgkmcnt(6)
	v_fma_f32 v230, -v208, v100, v230
	v_fma_f32 v231, -v209, v101, v231
	v_fma_f32 v230, -v210, v102, v230
	v_fma_f32 v231, -v211, v103, v231
	ds_read_b128 v[208:211], v8 offset:7968
	s_waitcnt lgkmcnt(6)
	v_fma_f32 v230, -v212, v104, v230
	v_fma_f32 v231, -v213, v105, v231
	v_fma_f32 v230, -v214, v106, v230
	v_fma_f32 v231, -v215, v107, v231
	ds_read_b128 v[212:215], v8 offset:7984
	s_waitcnt lgkmcnt(5)
	v_fma_f32 v230, -v192, v108, v230
	v_fma_f32 v231, -v193, v109, v231
	v_fma_f32 v230, -v194, v110, v230
	v_fma_f32 v231, -v195, v111, v231
	ds_read_b128 v[192:195], v8 offset:8000
	s_waitcnt lgkmcnt(5)
	v_fma_f32 v230, -v196, v112, v230
	v_fma_f32 v231, -v197, v113, v231
	ds_read_b128 v[196:199], v8 offset:8016
	v_add_f32_e32 v114, v230, v231
	s_cbranch_vccz .Ls4_u30
	v_cvt_pk_bf16_f32 v233, -v114, v114
	global_store_short v6, v233, s[8:9] offset:3584
	s_branch .Ls4_n30
; #define LAS __attribute__((address_space(3)))
; __device__ __forceinline__ void chunk_prep_phase(const Params& p, int bid, int nblk, LAS unsigned char* lds0) {
;     ...
;             { const float br = betg[31]; ab0 = (f32x2){bf2f(*(const LAS bf16_t*)(lg + P5_VS + 8432 + c * 2)) * br, bf2f(*(const LAS bf16_t*)(lg + P5_KS + 8432 + c * 2)) * br * __expf(decg[31])}; ab1 = (f32x2){0.f, 0.f}; } ab0 -= mq[2][0] * xy[0]; ab1 -= mq[2][1] * xy[1]; ab0 -= mq[2][2] * xy[2]; ab1 -= mq[2][3] * xy[3]; mq[2] = *(const LAS f32x4*)(Mg + 2008);
;             ab0 -= mq[3][0] * xy[4]; ab1 -= mq[3][1] * xy[5]; ab0 -= mq[3][2] * xy[6]; ab1 -= mq[3][3] * xy[7]; mq[3] = *(const LAS f32x4*)(Mg + 2012);
;             ab0 -= mq[4][0] * xy[8]; ab1 -= mq[4][1] * xy[9]; ab0 -= mq[4][2] * xy[10]; ab1 -= mq[4][3] * xy[11]; mq[4] = *(const LAS f32x4*)(Mg + 2048);
;             ab0 -= mq[5][0] * xy[12]; ab1 -= mq[5][1] * xy[13]; ab0 -= mq[5][2] * xy[14]; ab1 -= mq[5][3] * xy[15]; mq[5] = *(const LAS f32x4*)(Mg + 2052);
;             ab0 -= mq[0][0] * xy[16]; ab1 -= mq[0][1] * xy[17]; ab0 -= mq[0][2] * xy[18]; ab1 -= mq[0][3] * xy[19]; mq[0] = *(const LAS f32x4*)(Mg + 2056);
;             ab0 -= mq[1][0] * xy[20]; ab1 -= mq[1][1] * xy[21]; ab0 -= mq[1][2] * xy[22]; ab1 -= mq[1][3] * xy[23]; mq[1] = *(const LAS f32x4*)(Mg + 2060);
;             ab0 -= mq[2][0] * xy[24]; ab1 -= mq[2][1] * xy[25]; ab0 -= mq[2][2] * xy[26]; ab1 -= mq[2][3] * xy[27]; mq[2] = *(const LAS f32x4*)(Mg + 2064);
;             ab0 -= mq[3][0] * xy[28]; ab1 -= mq[3][1] * xy[29]; ab0 -= mq[3][2] * xy[30]; xy[31] = ab0 + ab1; up[3968] = xy[31][0]; wp[3968] = f2bf(-xy[31][1]); mq[3] = *(const LAS f32x4*)(Mg + 2068);
;             { const float br = betg[32]; ab0 = (f32x2){bf2f(*(const LAS bf16_t*)(lg + P5_VS + 8704 + c * 2)) * br, bf2f(*(const LAS bf16_t*)(lg + P5_KS + 8704 + c * 2)) * br * __expf(decg[32])}; ab1 = (f32x2){0.f, 0.f}; } ab0 -= mq[4][0] * xy[0]; ab1 -= mq[4][1] * xy[1]; ab0 -= mq[4][2] * xy[2]; ab1 -= mq[4][3] * xy[3]; mq[4] = *(const LAS f32x4*)(Mg + 2072);
;             ab0 -= mq[5][0] * xy[4]; ab1 -= mq[5][1] * xy[5]; ab0 -= mq[5][2] * xy[6]; ab1 -= mq[5][3] * xy[7]; mq[5] = *(const LAS f32x4*)(Mg + 2076);
;             ab0 -= mq[0][0] * xy[8]; ab1 -= mq[0][1] * xy[9]; ab0 -= mq[0][2] * xy[10]; ab1 -= mq[0][3] * xy[11]; mq[0] = *(const LAS f32x4*)(Mg + 2112);
.Ls4_u30:
	global_store_dword v234, v114, s[8:9] offset:3072
.Ls4_n30:
	v_lshlrev_b32_e32 v229, 16, v229
	v_mul_f32_e32 v232, v229, v223
	v_mul_f32_e32 v230, v232, v227
	v_mov_b32_e32 v231, 0
	ds_read_u16 v228, v7 offset:8704
	ds_read_b128 v[220:223], v8 offset:16784
	ds_read_b128 v[224:227], v8 offset:16528
	s_waitcnt lgkmcnt(8)
	v_fma_f32 v230, -v200, v84, v230
	v_fma_f32 v231, -v201, v85, v231
	v_fma_f32 v230, -v202, v86, v230
	v_fma_f32 v231, -v203, v87, v231
	ds_read_b128 v[200:203], v8 offset:8032
	s_waitcnt lgkmcnt(8)
	v_fma_f32 v230, -v204, v88, v230
	v_fma_f32 v231, -v205, v89, v231
	v_fma_f32 v230, -v206, v90, v230
	v_fma_f32 v231, -v207, v91, v231
	ds_read_b128 v[204:207], v8 offset:8048
	s_waitcnt lgkmcnt(8)
	v_fma_f32 v230, -v208, v92, v230
	v_fma_f32 v231, -v209, v93, v231
	v_fma_f32 v230, -v210, v94, v230
	v_fma_f32 v231, -v211, v95, v231
	ds_read_b128 v[208:211], v8 offset:8192
	s_waitcnt lgkmcnt(8)
	v_fma_f32 v230, -v212, v96, v230
	v_fma_f32 v231, -v213, v97, v231
	v_fma_f32 v230, -v214, v98, v230
	v_fma_f32 v231, -v215, v99, v231
	ds_read_b128 v[212:215], v8 offset:8208
	s_waitcnt lgkmcnt(8)
	v_fma_f32 v230, -v192, v100, v230
	v_fma_f32 v231, -v193, v101, v231
	v_fma_f32 v230, -v194, v102, v230
	v_fma_f32 v231, -v195, v103, v231
	ds_read_b128 v[192:195], v8 offset:8224
	s_waitcnt lgkmcnt(8)
	v_fma_f32 v230, -v196, v104, v230
	v_fma_f32 v231, -v197, v105, v231
	v_fma_f32 v230, -v198, v106, v230
	v_fma_f32 v231, -v199, v107, v231
	ds_read_b128 v[196:199], v8 offset:8240
	s_waitcnt lgkmcnt(5)
	v_fma_f32 v230, -v200, v108, v230
	v_fma_f32 v231, -v201, v109, v231
	v_fma_f32 v230, -v202, v110, v230
	v_fma_f32 v231, -v203, v111, v231
	ds_read_b128 v[200:203], v8 offset:8256
	s_waitcnt lgkmcnt(5)
	v_fma_f32 v230, -v204, v112, v230
	v_fma_f32 v231, -v205, v113, v231
	v_fma_f32 v230, -v206, v114, v230
	ds_read_b128 v[204:207], v8 offset:8272
	v_add_f32_e32 v115, v230, v231
	s_cbranch_vccz .Ls4_u31
	v_cvt_pk_bf16_f32 v233, -v115, v115
	global_store_short v6, v233, s[8:9] offset:3840
	s_branch .Ls4_n31
.Ls4_u31:
	global_store_dword v234, v115, s[8:9] offset:3584
.Ls4_n31:
	v_mul_f32_e32 v0, s16, v0
	v_mul_f32_e32 v1, s16, v1
	v_mul_f32_e32 v2, s16, v2
	v_mul_f32_e32 v3, s16, v3
	v_exp_f32_e32 v0, v0
	v_exp_f32_e32 v1, v1
	v_exp_f32_e32 v2, v2
	v_exp_f32_e32 v3, v3
	s_nop 0
	v_lshlrev_b32_e32 v228, 16, v228
	v_mul_f32_e32 v232, v228, v216
	v_mul_f32_e32 v230, v232, v0
	v_mov_b32_e32 v231, 0
	ds_read_u16 v229, v7 offset:8976
	s_waitcnt lgkmcnt(6)
	v_fma_f32 v230, -v208, v84, v230
	v_fma_f32 v231, -v209, v85, v231
	v_fma_f32 v230, -v210, v86, v230
	v_fma_f32 v231, -v211, v87, v231
	ds_read_b128 v[208:211], v8 offset:8288
	s_waitcnt lgkmcnt(6)
	v_fma_f32 v230, -v212, v88, v230
	v_fma_f32 v231, -v213, v89, v231
	v_fma_f32 v230, -v214, v90, v230
	v_fma_f32 v231, -v215, v91, v231
	ds_read_b128 v[212:215], v8 offset:8304
	s_waitcnt lgkmcnt(6)
	v_fma_f32 v230, -v192, v92, v230
	v_fma_f32 v231, -v193, v93, v231
	v_fma_f32 v230, -v194, v94, v230
	v_fma_f32 v231, -v195, v95, v231
	ds_read_b128 v[192:195], v8 offset:8448
	s_waitcnt lgkmcnt(6)
	v_fma_f32 v230, -v196, v96, v230
	v_fma_f32 v231, -v197, v97, v231
	v_fma_f32 v230, -v198, v98, v230
	v_fma_f32 v231, -v199, v99, v231
	ds_read_b128 v[196:199], v8 offset:8464
	s_waitcnt lgkmcnt(6)
	v_fma_f32 v230, -v200, v100, v230
	v_fma_f32 v231, -v201, v101, v231
	v_fma_f32 v230, -v202, v102, v230
	v_fma_f32 v231, -v203, v103, v231
	ds_read_b128 v[200:203], v8 offset:8480
	s_waitcnt lgkmcnt(6)
	v_fma_f32 v230, -v204, v104, v230
	v_fma_f32 v231, -v205, v105, v231
	v_fma_f32 v230, -v206, v106, v230
	v_fma_f32 v231, -v207, v107, v231
	ds_read_b128 v[204:207], v8 offset:8496
	s_waitcnt lgkmcnt(5)
	v_fma_f32 v230, -v208, v108, v230
	v_fma_f32 v231, -v209, v109, v231
	v_fma_f32 v230, -v210, v110, v230
	v_fma_f32 v231, -v211, v111, v231
	ds_read_b128 v[208:211], v8 offset:8512
	s_waitcnt lgkmcnt(5)
	v_fma_f32 v230, -v212, v112, v230
	v_fma_f32 v231, -v213, v113, v231
	v_fma_f32 v230, -v214, v114, v230
	v_fma_f32 v231, -v215, v115, v231
	ds_read_b128 v[212:215], v8 offset:8528
	v_add_f32_e32 v116, v230, v231
	s_cbranch_vccz .Ls4_u32
	s_add_u32 s8, s8, 0x1000
	s_addc_u32 s9, s9, 0
	v_cvt_pk_bf16_f32 v233, -v116, v116
	global_store_short v6, v233, s[8:9] offset:0
	s_branch .Ls4_n32
.Ls4_u32:
	s_add_u32 s8, s8, 0x1000
	s_addc_u32 s9, s9, 0
	global_store_dword v234, v116, s[8:9] offset:0
.Ls4_n32:
	v_lshlrev_b32_e32 v229, 16, v229
	v_mul_f32_e32 v232, v229, v217
	v_mul_f32_e32 v230, v232, v1
	v_mov_b32_e32 v231, 0
	ds_read_u16 v228, v7 offset:9248
	s_waitcnt lgkmcnt(6)
	v_fma_f32 v230, -v192, v84, v230
	v_fma_f32 v231, -v193, v85, v231
	v_fma_f32 v230, -v194, v86, v230
	v_fma_f32 v231, -v195, v87, v231
	ds_read_b128 v[192:195], v8 offset:8544
	s_waitcnt lgkmcnt(6)
	v_fma_f32 v230, -v196, v88, v230
	v_fma_f32 v231, -v197, v89, v231
	v_fma_f32 v230, -v198, v90, v230
	v_fma_f32 v231, -v199, v91, v231
	ds_read_b128 v[196:199], v8 offset:8560
	s_waitcnt lgkmcnt(6)
	v_fma_f32 v230, -v200, v92, v230
	v_fma_f32 v231, -v201, v93, v231
	v_fma_f32 v230, -v202, v94, v230
	v_fma_f32 v231, -v203, v95, v231
	ds_read_b128 v[200:203], v8 offset:8576
	s_waitcnt lgkmcnt(6)
	v_fma_f32 v230, -v204, v96, v230
	v_fma_f32 v231, -v205, v97, v231
	v_fma_f32 v230, -v206, v98, v230
	v_fma_f32 v231, -v207, v99, v231
	ds_read_b128 v[204:207], v8 offset:8704
	s_waitcnt lgkmcnt(6)
	v_fma_f32 v230, -v208, v100, v230
	v_fma_f32 v231, -v209, v101, v231
	v_fma_f32 v230, -v210, v102, v230
	v_fma_f32 v231, -v211, v103, v231
	ds_read_b128 v[208:211], v8 offset:8720
	s_waitcnt lgkmcnt(6)
	v_fma_f32 v230, -v212, v104, v230
	v_fma_f32 v231, -v213, v105, v231
	v_fma_f32 v230, -v214, v106, v230
	v_fma_f32 v231, -v215, v107, v231
	ds_read_b128 v[212:215], v8 offset:8736
	s_waitcnt lgkmcnt(5)
	v_fma_f32 v230, -v192, v108, v230
	v_fma_f32 v231, -v193, v109, v231
	v_fma_f32 v230, -v194, v110, v230
	v_fma_f32 v231, -v195, v111, v231
	ds_read_b128 v[192:195], v8 offset:8752
	s_waitcnt lgkmcnt(5)
	v_fma_f32 v230, -v196, v112, v230
	v_fma_f32 v231, -v197, v113, v231
	v_fma_f32 v230, -v198, v114, v230
	v_fma_f32 v231, -v199, v115, v231
	ds_read_b128 v[196:199], v8 offset:8768
	s_waitcnt lgkmcnt(5)
	v_fma_f32 v230, -v200, v116, v230
	ds_read_b128 v[200:203], v8 offset:8784
	v_add_f32_e32 v117, v230, v231
	s_cbranch_vccz .Ls4_u33
	v_cvt_pk_bf16_f32 v233, -v117, v117
	global_store_short v6, v233, s[8:9] offset:256
	s_branch .Ls4_n33
; #define LAS __attribute__((address_space(3)))
; __device__ __forceinline__ void chunk_prep_phase(const Params& p, int bid, int nblk, LAS unsigned char* lds0) {
;     ...
;             { const float br = betg[34]; ab0 = (f32x2){bf2f(*(const LAS bf16_t*)(lg + P5_VS + 9248 + c * 2)) * br, bf2f(*(const LAS bf16_t*)(lg + P5_KS + 9248 + c * 2)) * br * __expf(decg[34])}; ab1 = (f32x2){0.f, 0.f}; } ab0 -= mq[3][0] * xy[0]; ab1 -= mq[3][1] * xy[1]; ab0 -= mq[3][2] * xy[2]; ab1 -= mq[3][3] * xy[3]; mq[3] = *(const LAS f32x4*)(Mg + 2200);
;             ab0 -= mq[4][0] * xy[4]; ab1 -= mq[4][1] * xy[5]; ab0 -= mq[4][2] * xy[6]; ab1 -= mq[4][3] * xy[7]; mq[4] = *(const LAS f32x4*)(Mg + 2204);
;             ab0 -= mq[5][0] * xy[8]; ab1 -= mq[5][1] * xy[9]; ab0 -= mq[5][2] * xy[10]; ab1 -= mq[5][3] * xy[11]; mq[5] = *(const LAS f32x4*)(Mg + 2208);
;             ab0 -= mq[0][0] * xy[12]; ab1 -= mq[0][1] * xy[13]; ab0 -= mq[0][2] * xy[14]; ab1 -= mq[0][3] * xy[15]; mq[0] = *(const LAS f32x4*)(Mg + 2240);
;             ab0 -= mq[1][0] * xy[16]; ab1 -= mq[1][1] * xy[17]; ab0 -= mq[1][2] * xy[18]; ab1 -= mq[1][3] * xy[19]; mq[1] = *(const LAS f32x4*)(Mg + 2244);
;             ab0 -= mq[2][0] * xy[20]; ab1 -= mq[2][1] * xy[21]; ab0 -= mq[2][2] * xy[22]; ab1 -= mq[2][3] * xy[23]; mq[2] = *(const LAS f32x4*)(Mg + 2248);
;             ab0 -= mq[3][0] * xy[24]; ab1 -= mq[3][1] * xy[25]; ab0 -= mq[3][2] * xy[26]; ab1 -= mq[3][3] * xy[27]; mq[3] = *(const LAS f32x4*)(Mg + 2252);
;             ab0 -= mq[4][0] * xy[28]; ab1 -= mq[4][1] * xy[29]; ab0 -= mq[4][2] * xy[30]; ab1 -= mq[4][3] * xy[31]; mq[4] = *(const LAS f32x4*)(Mg + 2256);
;             ab0 -= mq[5][0] * xy[32]; ab1 -= mq[5][1] * xy[33]; xy[34] = ab0 + ab1; up[4352] = xy[34][0]; wp[4352] = f2bf(-xy[34][1]); mq[5] = *(const LAS f32x4*)(Mg + 2260);
;             { const float br = betg[35]; ab0 = (f32x2){bf2f(*(const LAS bf16_t*)(lg + P5_VS + 9520 + c * 2)) * br, bf2f(*(const LAS bf16_t*)(lg + P5_KS + 9520 + c * 2)) * br * __expf(decg[35])}; ab1 = (f32x2){0.f, 0.f}; } ab0 -= mq[0][0] * xy[0]; ab1 -= mq[0][1] * xy[1]; ab0 -= mq[0][2] * xy[2]; ab1 -= mq[0][3] * xy[3]; mq[0] = *(const LAS f32x4*)(Mg + 2264);
;             ab0 -= mq[1][0] * xy[4]; ab1 -= mq[1][1] * xy[5]; ab0 -= mq[1][2] * xy[6]; ab1 -= mq[1][3] * xy[7]; mq[1] = *(const LAS f32x4*)(Mg + 2268);
.Ls4_u33:
	global_store_dword v234, v117, s[8:9] offset:512
.Ls4_n33:
	v_lshlrev_b32_e32 v228, 16, v228
	v_mul_f32_e32 v232, v228, v218
	v_mul_f32_e32 v230, v232, v2
	v_mov_b32_e32 v231, 0
	ds_read_u16 v229, v7 offset:9520
	s_waitcnt lgkmcnt(6)
	v_fma_f32 v230, -v204, v84, v230
	v_fma_f32 v231, -v205, v85, v231
	v_fma_f32 v230, -v206, v86, v230
	v_fma_f32 v231, -v207, v87, v231
	ds_read_b128 v[204:207], v8 offset:8800
	s_waitcnt lgkmcnt(6)
	v_fma_f32 v230, -v208, v88, v230
	v_fma_f32 v231, -v209, v89, v231
	v_fma_f32 v230, -v210, v90, v230
	v_fma_f32 v231, -v211, v91, v231
	ds_read_b128 v[208:211], v8 offset:8816
	s_waitcnt lgkmcnt(6)
	v_fma_f32 v230, -v212, v92, v230
	v_fma_f32 v231, -v213, v93, v231
	v_fma_f32 v230, -v214, v94, v230
	v_fma_f32 v231, -v215, v95, v231
	ds_read_b128 v[212:215], v8 offset:8832
	s_waitcnt lgkmcnt(6)
	v_fma_f32 v230, -v192, v96, v230
	v_fma_f32 v231, -v193, v97, v231
	v_fma_f32 v230, -v194, v98, v230
	v_fma_f32 v231, -v195, v99, v231
	ds_read_b128 v[192:195], v8 offset:8960
	s_waitcnt lgkmcnt(6)
	v_fma_f32 v230, -v196, v100, v230
	v_fma_f32 v231, -v197, v101, v231
	v_fma_f32 v230, -v198, v102, v230
	v_fma_f32 v231, -v199, v103, v231
	ds_read_b128 v[196:199], v8 offset:8976
	s_waitcnt lgkmcnt(6)
	v_fma_f32 v230, -v200, v104, v230
	v_fma_f32 v231, -v201, v105, v231
	v_fma_f32 v230, -v202, v106, v230
	v_fma_f32 v231, -v203, v107, v231
	ds_read_b128 v[200:203], v8 offset:8992
	s_waitcnt lgkmcnt(5)
	v_fma_f32 v230, -v204, v108, v230
	v_fma_f32 v231, -v205, v109, v231
	v_fma_f32 v230, -v206, v110, v230
	v_fma_f32 v231, -v207, v111, v231
	ds_read_b128 v[204:207], v8 offset:9008
	s_waitcnt lgkmcnt(5)
	v_fma_f32 v230, -v208, v112, v230
	v_fma_f32 v231, -v209, v113, v231
	v_fma_f32 v230, -v210, v114, v230
	v_fma_f32 v231, -v211, v115, v231
	ds_read_b128 v[208:211], v8 offset:9024
	s_waitcnt lgkmcnt(5)
	v_fma_f32 v230, -v212, v116, v230
	v_fma_f32 v231, -v213, v117, v231
	ds_read_b128 v[212:215], v8 offset:9040
	v_add_f32_e32 v118, v230, v231
	s_cbranch_vccz .Ls4_u34
	v_cvt_pk_bf16_f32 v233, -v118, v118
	global_store_short v6, v233, s[8:9] offset:512
	s_branch .Ls4_n34
.Ls4_u34:
	global_store_dword v234, v118, s[8:9] offset:1024
.Ls4_n34:
	v_lshlrev_b32_e32 v229, 16, v229
	v_mul_f32_e32 v232, v229, v219
	v_mul_f32_e32 v230, v232, v3
	v_mov_b32_e32 v231, 0
	ds_read_u16 v228, v7 offset:9792
	ds_read_b128 v[216:219], v8 offset:16800
	ds_read_b128 v[0:3], v8 offset:16544
	s_waitcnt lgkmcnt(8)
	v_fma_f32 v230, -v192, v84, v230
	v_fma_f32 v231, -v193, v85, v231
	v_fma_f32 v230, -v194, v86, v230
	v_fma_f32 v231, -v195, v87, v231
	ds_read_b128 v[192:195], v8 offset:9056
	s_waitcnt lgkmcnt(8)
	v_fma_f32 v230, -v196, v88, v230
	v_fma_f32 v231, -v197, v89, v231
	v_fma_f32 v230, -v198, v90, v230
	v_fma_f32 v231, -v199, v91, v231
	ds_read_b128 v[196:199], v8 offset:9072
	s_waitcnt lgkmcnt(8)
	v_fma_f32 v230, -v200, v92, v230
	v_fma_f32 v231, -v201, v93, v231
	v_fma_f32 v230, -v202, v94, v230
	v_fma_f32 v231, -v203, v95, v231
	ds_read_b128 v[200:203], v8 offset:9088
	s_waitcnt lgkmcnt(8)
	v_fma_f32 v230, -v204, v96, v230
	v_fma_f32 v231, -v205, v97, v231
	v_fma_f32 v230, -v206, v98, v230
	v_fma_f32 v231, -v207, v99, v231
	ds_read_b128 v[204:207], v8 offset:9216
	s_waitcnt lgkmcnt(8)
	v_fma_f32 v230, -v208, v100, v230
	v_fma_f32 v231, -v209, v101, v231
	v_fma_f32 v230, -v210, v102, v230
	v_fma_f32 v231, -v211, v103, v231
	ds_read_b128 v[208:211], v8 offset:9232
	s_waitcnt lgkmcnt(8)
	v_fma_f32 v230, -v212, v104, v230
	v_fma_f32 v231, -v213, v105, v231
	v_fma_f32 v230, -v214, v106, v230
	v_fma_f32 v231, -v215, v107, v231
	ds_read_b128 v[212:215], v8 offset:9248
	s_waitcnt lgkmcnt(5)
	v_fma_f32 v230, -v192, v108, v230
	v_fma_f32 v231, -v193, v109, v231
	v_fma_f32 v230, -v194, v110, v230
	v_fma_f32 v231, -v195, v111, v231
	ds_read_b128 v[192:195], v8 offset:9264
	s_waitcnt lgkmcnt(5)
	v_fma_f32 v230, -v196, v112, v230
	v_fma_f32 v231, -v197, v113, v231
	v_fma_f32 v230, -v198, v114, v230
	v_fma_f32 v231, -v199, v115, v231
	ds_read_b128 v[196:199], v8 offset:9280
	s_waitcnt lgkmcnt(5)
	v_fma_f32 v230, -v200, v116, v230
	v_fma_f32 v231, -v201, v117, v231
	v_fma_f32 v230, -v202, v118, v230
	ds_read_b128 v[200:203], v8 offset:9296
	v_add_f32_e32 v119, v230, v231
	s_cbranch_vccz .Ls4_u35
	v_cvt_pk_bf16_f32 v233, -v119, v119
	global_store_short v6, v233, s[8:9] offset:768
	s_branch .Ls4_n35
.Ls4_u35:
	global_store_dword v234, v119, s[8:9] offset:1536
.Ls4_n35:
	v_mul_f32_e32 v224, s16, v224
	v_mul_f32_e32 v225, s16, v225
	v_mul_f32_e32 v226, s16, v226
	v_mul_f32_e32 v227, s16, v227
	v_exp_f32_e32 v224, v224
	v_exp_f32_e32 v225, v225
	v_exp_f32_e32 v226, v226
	v_exp_f32_e32 v227, v227
	s_nop 0
	v_lshlrev_b32_e32 v228, 16, v228
	v_mul_f32_e32 v232, v228, v220
	v_mul_f32_e32 v230, v232, v224
	v_mov_b32_e32 v231, 0
	ds_read_u16 v229, v7 offset:10064
	s_waitcnt lgkmcnt(6)
	v_fma_f32 v230, -v204, v84, v230
	v_fma_f32 v231, -v205, v85, v231
	v_fma_f32 v230, -v206, v86, v230
	v_fma_f32 v231, -v207, v87, v231
	ds_read_b128 v[204:207], v8 offset:9312
	s_waitcnt lgkmcnt(6)
	v_fma_f32 v230, -v208, v88, v230
	v_fma_f32 v231, -v209, v89, v231
	v_fma_f32 v230, -v210, v90, v230
	v_fma_f32 v231, -v211, v91, v231
	ds_read_b128 v[208:211], v8 offset:9328
	s_waitcnt lgkmcnt(6)
	v_fma_f32 v230, -v212, v92, v230
	v_fma_f32 v231, -v213, v93, v231
	v_fma_f32 v230, -v214, v94, v230
	v_fma_f32 v231, -v215, v95, v231
	ds_read_b128 v[212:215], v8 offset:9344
	s_waitcnt lgkmcnt(6)
	v_fma_f32 v230, -v192, v96, v230
	v_fma_f32 v231, -v193, v97, v231
	v_fma_f32 v230, -v194, v98, v230
	v_fma_f32 v231, -v195, v99, v231
	ds_read_b128 v[192:195], v8 offset:9472
	s_waitcnt lgkmcnt(6)
	v_fma_f32 v230, -v196, v100, v230
	v_fma_f32 v231, -v197, v101, v231
	v_fma_f32 v230, -v198, v102, v230
	v_fma_f32 v231, -v199, v103, v231
	ds_read_b128 v[196:199], v8 offset:9488
	s_waitcnt lgkmcnt(6)
	v_fma_f32 v230, -v200, v104, v230
	v_fma_f32 v231, -v201, v105, v231
	v_fma_f32 v230, -v202, v106, v230
	v_fma_f32 v231, -v203, v107, v231
	ds_read_b128 v[200:203], v8 offset:9504
	s_waitcnt lgkmcnt(5)
	v_fma_f32 v230, -v204, v108, v230
	v_fma_f32 v231, -v205, v109, v231
	v_fma_f32 v230, -v206, v110, v230
	v_fma_f32 v231, -v207, v111, v231
	ds_read_b128 v[204:207], v8 offset:9520
	s_waitcnt lgkmcnt(5)
	v_fma_f32 v230, -v208, v112, v230
	v_fma_f32 v231, -v209, v113, v231
	v_fma_f32 v230, -v210, v114, v230
	v_fma_f32 v231, -v211, v115, v231
	ds_read_b128 v[208:211], v8 offset:9536
	s_waitcnt lgkmcnt(5)
	v_fma_f32 v230, -v212, v116, v230
	v_fma_f32 v231, -v213, v117, v231
	v_fma_f32 v230, -v214, v118, v230
	v_fma_f32 v231, -v215, v119, v231
	ds_read_b128 v[212:215], v8 offset:9552
	v_add_f32_e32 v120, v230, v231
	s_cbranch_vccz .Ls4_u36
	v_cvt_pk_bf16_f32 v233, -v120, v120
	global_store_short v6, v233, s[8:9] offset:1024
	s_branch .Ls4_n36
; #define LAS __attribute__((address_space(3)))
; __device__ __forceinline__ void chunk_prep_phase(const Params& p, int bid, int nblk, LAS unsigned char* lds0) {
;     ...
;             { const float br = betg[37]; ab0 = (f32x2){bf2f(*(const LAS bf16_t*)(lg + P5_VS + 10064 + c * 2)) * br, bf2f(*(const LAS bf16_t*)(lg + P5_KS + 10064 + c * 2)) * br * __expf(decg[37])}; ab1 = (f32x2){0.f, 0.f}; } ab0 -= mq[0][0] * xy[0]; ab1 -= mq[0][1] * xy[1]; ab0 -= mq[0][2] * xy[2]; ab1 -= mq[0][3] * xy[3]; mq[0] = *(const LAS f32x4*)(Mg + 2392);
;             ab0 -= mq[1][0] * xy[4]; ab1 -= mq[1][1] * xy[5]; ab0 -= mq[1][2] * xy[6]; ab1 -= mq[1][3] * xy[7]; mq[1] = *(const LAS f32x4*)(Mg + 2396);
;             ab0 -= mq[2][0] * xy[8]; ab1 -= mq[2][1] * xy[9]; ab0 -= mq[2][2] * xy[10]; ab1 -= mq[2][3] * xy[11]; mq[2] = *(const LAS f32x4*)(Mg + 2400);
;             ab0 -= mq[3][0] * xy[12]; ab1 -= mq[3][1] * xy[13]; ab0 -= mq[3][2] * xy[14]; ab1 -= mq[3][3] * xy[15]; mq[3] = *(const LAS f32x4*)(Mg + 2404);
;             ab0 -= mq[4][0] * xy[16]; ab1 -= mq[4][1] * xy[17]; ab0 -= mq[4][2] * xy[18]; ab1 -= mq[4][3] * xy[19]; mq[4] = *(const LAS f32x4*)(Mg + 2432);
;             ab0 -= mq[5][0] * xy[20]; ab1 -= mq[5][1] * xy[21]; ab0 -= mq[5][2] * xy[22]; ab1 -= mq[5][3] * xy[23]; mq[5] = *(const LAS f32x4*)(Mg + 2436);
;             ab0 -= mq[0][0] * xy[24]; ab1 -= mq[0][1] * xy[25]; ab0 -= mq[0][2] * xy[26]; ab1 -= mq[0][3] * xy[27]; mq[0] = *(const LAS f32x4*)(Mg + 2440);
;             ab0 -= mq[1][0] * xy[28]; ab1 -= mq[1][1] * xy[29]; ab0 -= mq[1][2] * xy[30]; ab1 -= mq[1][3] * xy[31]; mq[1] = *(const LAS f32x4*)(Mg + 2444);
;             ab0 -= mq[2][0] * xy[32]; ab1 -= mq[2][1] * xy[33]; ab0 -= mq[2][2] * xy[34]; ab1 -= mq[2][3] * xy[35]; mq[2] = *(const LAS f32x4*)(Mg + 2448);
;             ab0 -= mq[3][0] * xy[36]; xy[37] = ab0 + ab1; up[4736] = xy[37][0]; wp[4736] = f2bf(-xy[37][1]); mq[3] = *(const LAS f32x4*)(Mg + 2452);
;             { const float br = betg[38]; ab0 = (f32x2){bf2f(*(const LAS bf16_t*)(lg + P5_VS + 10336 + c * 2)) * br, bf2f(*(const LAS bf16_t*)(lg + P5_KS + 10336 + c * 2)) * br * __expf(decg[38])}; ab1 = (f32x2){0.f, 0.f}; } ab0 -= mq[4][0] * xy[0]; ab1 -= mq[4][1] * xy[1]; ab0 -= mq[4][2] * xy[2]; ab1 -= mq[4][3] * xy[3]; mq[4] = *(const LAS f32x4*)(Mg + 2456);
.Ls4_u36:
	global_store_dword v234, v120, s[8:9] offset:2048
.Ls4_n36:
	v_lshlrev_b32_e32 v229, 16, v229
	v_mul_f32_e32 v232, v229, v221
	v_mul_f32_e32 v230, v232, v225
	v_mov_b32_e32 v231, 0
	ds_read_u16 v228, v7 offset:10336
	s_waitcnt lgkmcnt(6)
	v_fma_f32 v230, -v192, v84, v230
	v_fma_f32 v231, -v193, v85, v231
	v_fma_f32 v230, -v194, v86, v230
	v_fma_f32 v231, -v195, v87, v231
	ds_read_b128 v[192:195], v8 offset:9568
	s_waitcnt lgkmcnt(6)
	v_fma_f32 v230, -v196, v88, v230
	v_fma_f32 v231, -v197, v89, v231
	v_fma_f32 v230, -v198, v90, v230
	v_fma_f32 v231, -v199, v91, v231
	ds_read_b128 v[196:199], v8 offset:9584
	s_waitcnt lgkmcnt(6)
	v_fma_f32 v230, -v200, v92, v230
	v_fma_f32 v231, -v201, v93, v231
	v_fma_f32 v230, -v202, v94, v230
	v_fma_f32 v231, -v203, v95, v231
	ds_read_b128 v[200:203], v8 offset:9600
	s_waitcnt lgkmcnt(6)
	v_fma_f32 v230, -v204, v96, v230
	v_fma_f32 v231, -v205, v97, v231
	v_fma_f32 v230, -v206, v98, v230
	v_fma_f32 v231, -v207, v99, v231
	ds_read_b128 v[204:207], v8 offset:9616
	s_waitcnt lgkmcnt(6)
	v_fma_f32 v230, -v208, v100, v230
	v_fma_f32 v231, -v209, v101, v231
	v_fma_f32 v230, -v210, v102, v230
	v_fma_f32 v231, -v211, v103, v231
	ds_read_b128 v[208:211], v8 offset:9728
	s_waitcnt lgkmcnt(6)
	v_fma_f32 v230, -v212, v104, v230
	v_fma_f32 v231, -v213, v105, v231
	v_fma_f32 v230, -v214, v106, v230
	v_fma_f32 v231, -v215, v107, v231
	ds_read_b128 v[212:215], v8 offset:9744
	s_waitcnt lgkmcnt(5)
	v_fma_f32 v230, -v192, v108, v230
	v_fma_f32 v231, -v193, v109, v231
	v_fma_f32 v230, -v194, v110, v230
	v_fma_f32 v231, -v195, v111, v231
	ds_read_b128 v[192:195], v8 offset:9760
	s_waitcnt lgkmcnt(5)
	v_fma_f32 v230, -v196, v112, v230
	v_fma_f32 v231, -v197, v113, v231
	v_fma_f32 v230, -v198, v114, v230
	v_fma_f32 v231, -v199, v115, v231
	ds_read_b128 v[196:199], v8 offset:9776
	s_waitcnt lgkmcnt(5)
	v_fma_f32 v230, -v200, v116, v230
	v_fma_f32 v231, -v201, v117, v231
	v_fma_f32 v230, -v202, v118, v230
	v_fma_f32 v231, -v203, v119, v231
	ds_read_b128 v[200:203], v8 offset:9792
	s_waitcnt lgkmcnt(5)
	v_fma_f32 v230, -v204, v120, v230
	ds_read_b128 v[204:207], v8 offset:9808
	v_add_f32_e32 v121, v230, v231
	s_cbranch_vccz .Ls4_u37
	v_cvt_pk_bf16_f32 v233, -v121, v121
	global_store_short v6, v233, s[8:9] offset:1280
	s_branch .Ls4_n37
.Ls4_u37:
	global_store_dword v234, v121, s[8:9] offset:2560
.Ls4_n37:
	v_lshlrev_b32_e32 v228, 16, v228
	v_mul_f32_e32 v232, v228, v222
	v_mul_f32_e32 v230, v232, v226
	v_mov_b32_e32 v231, 0
	ds_read_u16 v229, v7 offset:10608
	s_waitcnt lgkmcnt(6)
	v_fma_f32 v230, -v208, v84, v230
	v_fma_f32 v231, -v209, v85, v231
	v_fma_f32 v230, -v210, v86, v230
	v_fma_f32 v231, -v211, v87, v231
	ds_read_b128 v[208:211], v8 offset:9824
	s_waitcnt lgkmcnt(6)
	v_fma_f32 v230, -v212, v88, v230
	v_fma_f32 v231, -v213, v89, v231
	v_fma_f32 v230, -v214, v90, v230
	v_fma_f32 v231, -v215, v91, v231
	ds_read_b128 v[212:215], v8 offset:9840
	s_waitcnt lgkmcnt(6)
	v_fma_f32 v230, -v192, v92, v230
	v_fma_f32 v231, -v193, v93, v231
	v_fma_f32 v230, -v194, v94, v230
	v_fma_f32 v231, -v195, v95, v231
	ds_read_b128 v[192:195], v8 offset:9856
	s_waitcnt lgkmcnt(6)
	v_fma_f32 v230, -v196, v96, v230
	v_fma_f32 v231, -v197, v97, v231
	v_fma_f32 v230, -v198, v98, v230
	v_fma_f32 v231, -v199, v99, v231
	ds_read_b128 v[196:199], v8 offset:9872
	s_waitcnt lgkmcnt(6)
	v_fma_f32 v230, -v200, v100, v230
	v_fma_f32 v231, -v201, v101, v231
	v_fma_f32 v230, -v202, v102, v230
	v_fma_f32 v231, -v203, v103, v231
	ds_read_b128 v[200:203], v8 offset:9984
	s_waitcnt lgkmcnt(6)
	v_fma_f32 v230, -v204, v104, v230
	v_fma_f32 v231, -v205, v105, v231
	v_fma_f32 v230, -v206, v106, v230
	v_fma_f32 v231, -v207, v107, v231
	ds_read_b128 v[204:207], v8 offset:10000
	s_waitcnt lgkmcnt(5)
	v_fma_f32 v230, -v208, v108, v230
	v_fma_f32 v231, -v209, v109, v231
	v_fma_f32 v230, -v210, v110, v230
	v_fma_f32 v231, -v211, v111, v231
	ds_read_b128 v[208:211], v8 offset:10016
	s_waitcnt lgkmcnt(5)
	v_fma_f32 v230, -v212, v112, v230
	v_fma_f32 v231, -v213, v113, v231
	v_fma_f32 v230, -v214, v114, v230
	v_fma_f32 v231, -v215, v115, v231
	ds_read_b128 v[212:215], v8 offset:10032
	s_waitcnt lgkmcnt(5)
	v_fma_f32 v230, -v192, v116, v230
	v_fma_f32 v231, -v193, v117, v231
	v_fma_f32 v230, -v194, v118, v230
	v_fma_f32 v231, -v195, v119, v231
	ds_read_b128 v[192:195], v8 offset:10048
	s_waitcnt lgkmcnt(5)
	v_fma_f32 v230, -v196, v120, v230
	v_fma_f32 v231, -v197, v121, v231
	ds_read_b128 v[196:199], v8 offset:10064
	v_add_f32_e32 v122, v230, v231
	s_cbranch_vccz .Ls4_u38
	v_cvt_pk_bf16_f32 v233, -v122, v122
	global_store_short v6, v233, s[8:9] offset:1536
	s_branch .Ls4_n38
.Ls4_u38:
	global_store_dword v234, v122, s[8:9] offset:3072
; #define LAS __attribute__((address_space(3)))
; __device__ __forceinline__ void chunk_prep_phase(const Params& p, int bid, int nblk, LAS unsigned char* lds0) {
;     ...
;             { const float br = betg[39]; ab0 = (f32x2){bf2f(*(const LAS bf16_t*)(lg + P5_VS + 10608 + c * 2)) * br, bf2f(*(const LAS bf16_t*)(lg + P5_KS + 10608 + c * 2)) * br * __expf(decg[39])}; ab1 = (f32x2){0.f, 0.f}; } ab0 -= mq[2][0] * xy[0]; ab1 -= mq[2][1] * xy[1]; ab0 -= mq[2][2] * xy[2]; ab1 -= mq[2][3] * xy[3]; mq[2] = *(const LAS f32x4*)(Mg + 2520);
;             ab0 -= mq[3][0] * xy[4]; ab1 -= mq[3][1] * xy[5]; ab0 -= mq[3][2] * xy[6]; ab1 -= mq[3][3] * xy[7]; mq[3] = *(const LAS f32x4*)(Mg + 2524);
;             ab0 -= mq[4][0] * xy[8]; ab1 -= mq[4][1] * xy[9]; ab0 -= mq[4][2] * xy[10]; ab1 -= mq[4][3] * xy[11]; mq[4] = *(const LAS f32x4*)(Mg + 2528);
;             ab0 -= mq[5][0] * xy[12]; ab1 -= mq[5][1] * xy[13]; ab0 -= mq[5][2] * xy[14]; ab1 -= mq[5][3] * xy[15]; mq[5] = *(const LAS f32x4*)(Mg + 2532);
;             ab0 -= mq[0][0] * xy[16]; ab1 -= mq[0][1] * xy[17]; ab0 -= mq[0][2] * xy[18]; ab1 -= mq[0][3] * xy[19]; mq[0] = *(const LAS f32x4*)(Mg + 2560);
;             ab0 -= mq[1][0] * xy[20]; ab1 -= mq[1][1] * xy[21]; ab0 -= mq[1][2] * xy[22]; ab1 -= mq[1][3] * xy[23]; mq[1] = *(const LAS f32x4*)(Mg + 2564);
;             ab0 -= mq[2][0] * xy[24]; ab1 -= mq[2][1] * xy[25]; ab0 -= mq[2][2] * xy[26]; ab1 -= mq[2][3] * xy[27]; mq[2] = *(const LAS f32x4*)(Mg + 2568);
;             ab0 -= mq[3][0] * xy[28]; ab1 -= mq[3][1] * xy[29]; ab0 -= mq[3][2] * xy[30]; ab1 -= mq[3][3] * xy[31]; mq[3] = *(const LAS f32x4*)(Mg + 2572);
;             ab0 -= mq[4][0] * xy[32]; ab1 -= mq[4][1] * xy[33]; ab0 -= mq[4][2] * xy[34]; ab1 -= mq[4][3] * xy[35]; mq[4] = *(const LAS f32x4*)(Mg + 2576);
;             ab0 -= mq[5][0] * xy[36]; ab1 -= mq[5][1] * xy[37]; ab0 -= mq[5][2] * xy[38]; xy[39] = ab0 + ab1; up[4992] = xy[39][0]; wp[4992] = f2bf(-xy[39][1]); mq[5] = *(const LAS f32x4*)(Mg + 2580);
;             { const float br = betg[40]; ab0 = (f32x2){bf2f(*(const LAS bf16_t*)(lg + P5_VS + 10880 + c * 2)) * br, bf2f(*(const LAS bf16_t*)(lg + P5_KS + 10880 + c * 2)) * br * __expf(decg[40])}; ab1 = (f32x2){0.f, 0.f}; } ab0 -= mq[0][0] * xy[0]; ab1 -= mq[0][1] * xy[1]; ab0 -= mq[0][2] * xy[2]; ab1 -= mq[0][3] * xy[3]; mq[0] = *(const LAS f32x4*)(Mg + 2584);
.Ls4_n38:
	v_lshlrev_b32_e32 v229, 16, v229
	v_mul_f32_e32 v232, v229, v223
	v_mul_f32_e32 v230, v232, v227
	v_mov_b32_e32 v231, 0
	ds_read_u16 v228, v7 offset:10880
	ds_read_b128 v[220:223], v8 offset:16816
	ds_read_b128 v[224:227], v8 offset:16560
	s_waitcnt lgkmcnt(8)
	v_fma_f32 v230, -v200, v84, v230
	v_fma_f32 v231, -v201, v85, v231
	v_fma_f32 v230, -v202, v86, v230
	v_fma_f32 v231, -v203, v87, v231
	ds_read_b128 v[200:203], v8 offset:10080
	s_waitcnt lgkmcnt(8)
	v_fma_f32 v230, -v204, v88, v230
	v_fma_f32 v231, -v205, v89, v231
	v_fma_f32 v230, -v206, v90, v230
	v_fma_f32 v231, -v207, v91, v231
	ds_read_b128 v[204:207], v8 offset:10096
	s_waitcnt lgkmcnt(8)
	v_fma_f32 v230, -v208, v92, v230
	v_fma_f32 v231, -v209, v93, v231
	v_fma_f32 v230, -v210, v94, v230
	v_fma_f32 v231, -v211, v95, v231
	ds_read_b128 v[208:211], v8 offset:10112
	s_waitcnt lgkmcnt(8)
	v_fma_f32 v230, -v212, v96, v230
	v_fma_f32 v231, -v213, v97, v231
	v_fma_f32 v230, -v214, v98, v230
	v_fma_f32 v231, -v215, v99, v231
	ds_read_b128 v[212:215], v8 offset:10128
	s_waitcnt lgkmcnt(8)
	v_fma_f32 v230, -v192, v100, v230
	v_fma_f32 v231, -v193, v101, v231
	v_fma_f32 v230, -v194, v102, v230
	v_fma_f32 v231, -v195, v103, v231
	ds_read_b128 v[192:195], v8 offset:10240
	s_waitcnt lgkmcnt(8)
	v_fma_f32 v230, -v196, v104, v230
	v_fma_f32 v231, -v197, v105, v231
	v_fma_f32 v230, -v198, v106, v230
	v_fma_f32 v231, -v199, v107, v231
	ds_read_b128 v[196:199], v8 offset:10256
	s_waitcnt lgkmcnt(5)
	v_fma_f32 v230, -v200, v108, v230
	v_fma_f32 v231, -v201, v109, v231
	v_fma_f32 v230, -v202, v110, v230
	v_fma_f32 v231, -v203, v111, v231
	ds_read_b128 v[200:203], v8 offset:10272
	s_waitcnt lgkmcnt(5)
	v_fma_f32 v230, -v204, v112, v230
	v_fma_f32 v231, -v205, v113, v231
	v_fma_f32 v230, -v206, v114, v230
	v_fma_f32 v231, -v207, v115, v231
	ds_read_b128 v[204:207], v8 offset:10288
	s_waitcnt lgkmcnt(5)
	v_fma_f32 v230, -v208, v116, v230
	v_fma_f32 v231, -v209, v117, v231
	v_fma_f32 v230, -v210, v118, v230
	v_fma_f32 v231, -v211, v119, v231
	ds_read_b128 v[208:211], v8 offset:10304
	s_waitcnt lgkmcnt(5)
	v_fma_f32 v230, -v212, v120, v230
	v_fma_f32 v231, -v213, v121, v231
	v_fma_f32 v230, -v214, v122, v230
	ds_read_b128 v[212:215], v8 offset:10320
	v_add_f32_e32 v123, v230, v231
	s_cbranch_vccz .Ls4_u39
	v_cvt_pk_bf16_f32 v233, -v123, v123
	global_store_short v6, v233, s[8:9] offset:1792
	s_branch .Ls4_n39
.Ls4_u39:
	global_store_dword v234, v123, s[8:9] offset:3584
.Ls4_n39:
	v_mul_f32_e32 v0, s16, v0
	v_mul_f32_e32 v1, s16, v1
	v_mul_f32_e32 v2, s16, v2
	v_mul_f32_e32 v3, s16, v3
	v_exp_f32_e32 v0, v0
	v_exp_f32_e32 v1, v1
	v_exp_f32_e32 v2, v2
	v_exp_f32_e32 v3, v3
	s_nop 0
	v_lshlrev_b32_e32 v228, 16, v228
	v_mul_f32_e32 v232, v228, v216
	v_mul_f32_e32 v230, v232, v0
	v_mov_b32_e32 v231, 0
	ds_read_u16 v229, v7 offset:11152
	s_waitcnt lgkmcnt(6)
	v_fma_f32 v230, -v192, v84, v230
	v_fma_f32 v231, -v193, v85, v231
	v_fma_f32 v230, -v194, v86, v230
	v_fma_f32 v231, -v195, v87, v231
	ds_read_b128 v[192:195], v8 offset:10336
	s_waitcnt lgkmcnt(6)
	v_fma_f32 v230, -v196, v88, v230
	v_fma_f32 v231, -v197, v89, v231
	v_fma_f32 v230, -v198, v90, v230
	v_fma_f32 v231, -v199, v91, v231
	ds_read_b128 v[196:199], v8 offset:10352
	s_waitcnt lgkmcnt(6)
	v_fma_f32 v230, -v200, v92, v230
	v_fma_f32 v231, -v201, v93, v231
	v_fma_f32 v230, -v202, v94, v230
	v_fma_f32 v231, -v203, v95, v231
	ds_read_b128 v[200:203], v8 offset:10368
	s_waitcnt lgkmcnt(6)
	v_fma_f32 v230, -v204, v96, v230
	v_fma_f32 v231, -v205, v97, v231
	v_fma_f32 v230, -v206, v98, v230
	v_fma_f32 v231, -v207, v99, v231
	ds_read_b128 v[204:207], v8 offset:10384
	s_waitcnt lgkmcnt(6)
	v_fma_f32 v230, -v208, v100, v230
	v_fma_f32 v231, -v209, v101, v231
	v_fma_f32 v230, -v210, v102, v230
	v_fma_f32 v231, -v211, v103, v231
	ds_read_b128 v[208:211], v8 offset:10496
	s_waitcnt lgkmcnt(6)
	v_fma_f32 v230, -v212, v104, v230
	v_fma_f32 v231, -v213, v105, v231
	v_fma_f32 v230, -v214, v106, v230
	v_fma_f32 v231, -v215, v107, v231
	ds_read_b128 v[212:215], v8 offset:10512
	s_waitcnt lgkmcnt(5)
	v_fma_f32 v230, -v192, v108, v230
	v_fma_f32 v231, -v193, v109, v231
	v_fma_f32 v230, -v194, v110, v230
	v_fma_f32 v231, -v195, v111, v231
	ds_read_b128 v[192:195], v8 offset:10528
	s_waitcnt lgkmcnt(5)
	v_fma_f32 v230, -v196, v112, v230
	v_fma_f32 v231, -v197, v113, v231
	v_fma_f32 v230, -v198, v114, v230
	v_fma_f32 v231, -v199, v115, v231
	ds_read_b128 v[196:199], v8 offset:10544
	s_waitcnt lgkmcnt(5)
	v_fma_f32 v230, -v200, v116, v230
	v_fma_f32 v231, -v201, v117, v231
	v_fma_f32 v230, -v202, v118, v230
	v_fma_f32 v231, -v203, v119, v231
	ds_read_b128 v[200:203], v8 offset:10560
	s_waitcnt lgkmcnt(5)
	v_fma_f32 v230, -v204, v120, v230
	v_fma_f32 v231, -v205, v121, v231
	v_fma_f32 v230, -v206, v122, v230
	v_fma_f32 v231, -v207, v123, v231
	ds_read_b128 v[204:207], v8 offset:10576
	v_add_f32_e32 v124, v230, v231
	s_cbranch_vccz .Ls4_u40
	v_cvt_pk_bf16_f32 v233, -v124, v124
	global_store_short v6, v233, s[8:9] offset:2048
	s_branch .Ls4_n40
.Ls4_u40:
	s_add_u32 s8, s8, 0x1000
	s_addc_u32 s9, s9, 0
	global_store_dword v234, v124, s[8:9] offset:0
; #define LAS __attribute__((address_space(3)))
; __device__ __forceinline__ float bf2f(unsigned short x) { return __uint_as_float(((unsigned)x) << 16); }
; __device__ __forceinline__ void chunk_prep_phase(const Params& p, int bid, int nblk, LAS unsigned char* lds0) {
;     ...
;             { const float br = betg[41]; ab0 = (f32x2){bf2f(*(const LAS bf16_t*)(lg + P5_VS + 11152 + c * 2)) * br, bf2f(*(const LAS bf16_t*)(lg + P5_KS + 11152 + c * 2)) * br * __expf(decg[41])}; ab1 = (f32x2){0.f, 0.f}; } ab0 -= mq[4][0] * xy[0]; ab1 -= mq[4][1] * xy[1]; ab0 -= mq[4][2] * xy[2]; ab1 -= mq[4][3] * xy[3]; mq[4] = *(const LAS f32x4*)(Mg + 2648);
;             ab0 -= mq[5][0] * xy[4]; ab1 -= mq[5][1] * xy[5]; ab0 -= mq[5][2] * xy[6]; ab1 -= mq[5][3] * xy[7]; mq[5] = *(const LAS f32x4*)(Mg + 2652);
;             ab0 -= mq[0][0] * xy[8]; ab1 -= mq[0][1] * xy[9]; ab0 -= mq[0][2] * xy[10]; ab1 -= mq[0][3] * xy[11]; mq[0] = *(const LAS f32x4*)(Mg + 2656);
;             ab0 -= mq[1][0] * xy[12]; ab1 -= mq[1][1] * xy[13]; ab0 -= mq[1][2] * xy[14]; ab1 -= mq[1][3] * xy[15]; mq[1] = *(const LAS f32x4*)(Mg + 2660);
;             ab0 -= mq[2][0] * xy[16]; ab1 -= mq[2][1] * xy[17]; ab0 -= mq[2][2] * xy[18]; ab1 -= mq[2][3] * xy[19]; mq[2] = *(const LAS f32x4*)(Mg + 2664);
;             ab0 -= mq[3][0] * xy[20]; ab1 -= mq[3][1] * xy[21]; ab0 -= mq[3][2] * xy[22]; ab1 -= mq[3][3] * xy[23]; mq[3] = *(const LAS f32x4*)(Mg + 2688);
;             ab0 -= mq[4][0] * xy[24]; ab1 -= mq[4][1] * xy[25]; ab0 -= mq[4][2] * xy[26]; ab1 -= mq[4][3] * xy[27]; mq[4] = *(const LAS f32x4*)(Mg + 2692);
;             ab0 -= mq[5][0] * xy[28]; ab1 -= mq[5][1] * xy[29]; ab0 -= mq[5][2] * xy[30]; ab1 -= mq[5][3] * xy[31]; mq[5] = *(const LAS f32x4*)(Mg + 2696);
;             ab0 -= mq[0][0] * xy[32]; ab1 -= mq[0][1] * xy[33]; ab0 -= mq[0][2] * xy[34]; ab1 -= mq[0][3] * xy[35]; mq[0] = *(const LAS f32x4*)(Mg + 2700);
;             ab0 -= mq[1][0] * xy[36]; ab1 -= mq[1][1] * xy[37]; ab0 -= mq[1][2] * xy[38]; ab1 -= mq[1][3] * xy[39]; mq[1] = *(const LAS f32x4*)(Mg + 2704);
;             ab0 -= mq[2][0] * xy[40]; xy[41] = ab0 + ab1; up[5248] = xy[41][0]; wp[5248] = f2bf(-xy[41][1]); mq[2] = *(const LAS f32x4*)(Mg + 2708);
.Ls4_n40:
	v_lshlrev_b32_e32 v229, 16, v229
	v_mul_f32_e32 v232, v229, v217
	v_mul_f32_e32 v230, v232, v1
	v_mov_b32_e32 v231, 0
	ds_read_u16 v228, v7 offset:11424
	s_waitcnt lgkmcnt(6)
	v_fma_f32 v230, -v208, v84, v230
	v_fma_f32 v231, -v209, v85, v231
	v_fma_f32 v230, -v210, v86, v230
	v_fma_f32 v231, -v211, v87, v231
	ds_read_b128 v[208:211], v8 offset:10592
	s_waitcnt lgkmcnt(6)
	v_fma_f32 v230, -v212, v88, v230
	v_fma_f32 v231, -v213, v89, v231
	v_fma_f32 v230, -v214, v90, v230
	v_fma_f32 v231, -v215, v91, v231
	ds_read_b128 v[212:215], v8 offset:10608
	s_waitcnt lgkmcnt(6)
	v_fma_f32 v230, -v192, v92, v230
	v_fma_f32 v231, -v193, v93, v231
	v_fma_f32 v230, -v194, v94, v230
	v_fma_f32 v231, -v195, v95, v231
	ds_read_b128 v[192:195], v8 offset:10624
	s_waitcnt lgkmcnt(6)
	v_fma_f32 v230, -v196, v96, v230
	v_fma_f32 v231, -v197, v97, v231
	v_fma_f32 v230, -v198, v98, v230
	v_fma_f32 v231, -v199, v99, v231
	ds_read_b128 v[196:199], v8 offset:10640
	s_waitcnt lgkmcnt(6)
	v_fma_f32 v230, -v200, v100, v230
	v_fma_f32 v231, -v201, v101, v231
	v_fma_f32 v230, -v202, v102, v230
	v_fma_f32 v231, -v203, v103, v231
	ds_read_b128 v[200:203], v8 offset:10656
	s_waitcnt lgkmcnt(6)
	v_fma_f32 v230, -v204, v104, v230
	v_fma_f32 v231, -v205, v105, v231
	v_fma_f32 v230, -v206, v106, v230
	v_fma_f32 v231, -v207, v107, v231
	ds_read_b128 v[204:207], v8 offset:10752
	s_waitcnt lgkmcnt(5)
	v_fma_f32 v230, -v208, v108, v230
	v_fma_f32 v231, -v209, v109, v231
	v_fma_f32 v230, -v210, v110, v230
	v_fma_f32 v231, -v211, v111, v231
	ds_read_b128 v[208:211], v8 offset:10768
	s_waitcnt lgkmcnt(5)
	v_fma_f32 v230, -v212, v112, v230
	v_fma_f32 v231, -v213, v113, v231
	v_fma_f32 v230, -v214, v114, v230
	v_fma_f32 v231, -v215, v115, v231
	ds_read_b128 v[212:215], v8 offset:10784
	s_waitcnt lgkmcnt(5)
	v_fma_f32 v230, -v192, v116, v230
	v_fma_f32 v231, -v193, v117, v231
	v_fma_f32 v230, -v194, v118, v230
	v_fma_f32 v231, -v195, v119, v231
	ds_read_b128 v[192:195], v8 offset:10800
	s_waitcnt lgkmcnt(5)
	v_fma_f32 v230, -v196, v120, v230
	v_fma_f32 v231, -v197, v121, v231
	v_fma_f32 v230, -v198, v122, v230
	v_fma_f32 v231, -v199, v123, v231
	ds_read_b128 v[196:199], v8 offset:10816
	s_waitcnt lgkmcnt(5)
	v_fma_f32 v230, -v200, v124, v230
	ds_read_b128 v[200:203], v8 offset:10832
	v_add_f32_e32 v125, v230, v231
	s_cbranch_vccz .Ls4_u41
	v_cvt_pk_bf16_f32 v233, -v125, v125
	global_store_short v6, v233, s[8:9] offset:2304
	s_branch .Ls4_n41
.Ls4_u41:
	global_store_dword v234, v125, s[8:9] offset:512
.Ls4_n41:
	v_lshlrev_b32_e32 v228, 16, v228
	v_mul_f32_e32 v232, v228, v218
	v_mul_f32_e32 v230, v232, v2
	v_mov_b32_e32 v231, 0
	ds_read_u16 v229, v7 offset:11696
	s_waitcnt lgkmcnt(6)
	v_fma_f32 v230, -v204, v84, v230
	v_fma_f32 v231, -v205, v85, v231
	v_fma_f32 v230, -v206, v86, v230
	v_fma_f32 v231, -v207, v87, v231
	ds_read_b128 v[204:207], v8 offset:10848
	s_waitcnt lgkmcnt(6)
	v_fma_f32 v230, -v208, v88, v230
	v_fma_f32 v231, -v209, v89, v231
	v_fma_f32 v230, -v210, v90, v230
	v_fma_f32 v231, -v211, v91, v231
	ds_read_b128 v[208:211], v8 offset:10864
	s_waitcnt lgkmcnt(6)
	v_fma_f32 v230, -v212, v92, v230
	v_fma_f32 v231, -v213, v93, v231
	v_fma_f32 v230, -v214, v94, v230
	v_fma_f32 v231, -v215, v95, v231
	ds_read_b128 v[212:215], v8 offset:10880
	s_waitcnt lgkmcnt(6)
	v_fma_f32 v230, -v192, v96, v230
	v_fma_f32 v231, -v193, v97, v231
	v_fma_f32 v230, -v194, v98, v230
	v_fma_f32 v231, -v195, v99, v231
	ds_read_b128 v[192:195], v8 offset:10896
	s_waitcnt lgkmcnt(6)
	v_fma_f32 v230, -v196, v100, v230
	v_fma_f32 v231, -v197, v101, v231
	v_fma_f32 v230, -v198, v102, v230
	v_fma_f32 v231, -v199, v103, v231
	ds_read_b128 v[196:199], v8 offset:10912
	s_waitcnt lgkmcnt(6)
	v_fma_f32 v230, -v200, v104, v230
	v_fma_f32 v231, -v201, v105, v231
	v_fma_f32 v230, -v202, v106, v230
	v_fma_f32 v231, -v203, v107, v231
	ds_read_b128 v[200:203], v8 offset:11008
	s_waitcnt lgkmcnt(5)
	v_fma_f32 v230, -v204, v108, v230
	v_fma_f32 v231, -v205, v109, v231
	v_fma_f32 v230, -v206, v110, v230
	v_fma_f32 v231, -v207, v111, v231
	ds_read_b128 v[204:207], v8 offset:11024
	s_waitcnt lgkmcnt(5)
	v_fma_f32 v230, -v208, v112, v230
	v_fma_f32 v231, -v209, v113, v231
	v_fma_f32 v230, -v210, v114, v230
	v_fma_f32 v231, -v211, v115, v231
	ds_read_b128 v[208:211], v8 offset:11040
	s_waitcnt lgkmcnt(5)
	v_fma_f32 v230, -v212, v116, v230
	v_fma_f32 v231, -v213, v117, v231
	v_fma_f32 v230, -v214, v118, v230
	v_fma_f32 v231, -v215, v119, v231
	ds_read_b128 v[212:215], v8 offset:11056
	s_waitcnt lgkmcnt(5)
	v_fma_f32 v230, -v192, v120, v230
	v_fma_f32 v231, -v193, v121, v231
	v_fma_f32 v230, -v194, v122, v230
	v_fma_f32 v231, -v195, v123, v231
	ds_read_b128 v[192:195], v8 offset:11072
	s_waitcnt lgkmcnt(5)
	v_fma_f32 v230, -v196, v124, v230
	v_fma_f32 v231, -v197, v125, v231
	ds_read_b128 v[196:199], v8 offset:11088
	v_add_f32_e32 v126, v230, v231
	s_cbranch_vccz .Ls4_u42
	v_cvt_pk_bf16_f32 v233, -v126, v126
	global_store_short v6, v233, s[8:9] offset:2560
	s_branch .Ls4_n42
.Ls4_u42:
	global_store_dword v234, v126, s[8:9] offset:1024
; #define LAS __attribute__((address_space(3)))
; __device__ __forceinline__ float bf2f(unsigned short x) { return __uint_as_float(((unsigned)x) << 16); }
; __device__ __forceinline__ void chunk_prep_phase(const Params& p, int bid, int nblk, LAS unsigned char* lds0) {
;     ...
;             { const float br = betg[43]; ab0 = (f32x2){bf2f(*(const LAS bf16_t*)(lg + P5_VS + 11696 + c * 2)) * br, bf2f(*(const LAS bf16_t*)(lg + P5_KS + 11696 + c * 2)) * br * __expf(decg[43])}; ab1 = (f32x2){0.f, 0.f}; } ab0 -= mq[2][0] * xy[0]; ab1 -= mq[2][1] * xy[1]; ab0 -= mq[2][2] * xy[2]; ab1 -= mq[2][3] * xy[3]; mq[2] = *(const LAS f32x4*)(Mg + 2776);
;             ab0 -= mq[3][0] * xy[4]; ab1 -= mq[3][1] * xy[5]; ab0 -= mq[3][2] * xy[6]; ab1 -= mq[3][3] * xy[7]; mq[3] = *(const LAS f32x4*)(Mg + 2780);
;             ab0 -= mq[4][0] * xy[8]; ab1 -= mq[4][1] * xy[9]; ab0 -= mq[4][2] * xy[10]; ab1 -= mq[4][3] * xy[11]; mq[4] = *(const LAS f32x4*)(Mg + 2784);
;             ab0 -= mq[5][0] * xy[12]; ab1 -= mq[5][1] * xy[13]; ab0 -= mq[5][2] * xy[14]; ab1 -= mq[5][3] * xy[15]; mq[5] = *(const LAS f32x4*)(Mg + 2788);
;             ab0 -= mq[0][0] * xy[16]; ab1 -= mq[0][1] * xy[17]; ab0 -= mq[0][2] * xy[18]; ab1 -= mq[0][3] * xy[19]; mq[0] = *(const LAS f32x4*)(Mg + 2792);
;             ab0 -= mq[1][0] * xy[20]; ab1 -= mq[1][1] * xy[21]; ab0 -= mq[1][2] * xy[22]; ab1 -= mq[1][3] * xy[23]; mq[1] = *(const LAS f32x4*)(Mg + 2816);
;             ab0 -= mq[2][0] * xy[24]; ab1 -= mq[2][1] * xy[25]; ab0 -= mq[2][2] * xy[26]; ab1 -= mq[2][3] * xy[27]; mq[2] = *(const LAS f32x4*)(Mg + 2820);
;             ab0 -= mq[3][0] * xy[28]; ab1 -= mq[3][1] * xy[29]; ab0 -= mq[3][2] * xy[30]; ab1 -= mq[3][3] * xy[31]; mq[3] = *(const LAS f32x4*)(Mg + 2824);
;             ab0 -= mq[4][0] * xy[32]; ab1 -= mq[4][1] * xy[33]; ab0 -= mq[4][2] * xy[34]; ab1 -= mq[4][3] * xy[35]; mq[4] = *(const LAS f32x4*)(Mg + 2828);
;             ab0 -= mq[5][0] * xy[36]; ab1 -= mq[5][1] * xy[37]; ab0 -= mq[5][2] * xy[38]; ab1 -= mq[5][3] * xy[39]; mq[5] = *(const LAS f32x4*)(Mg + 2832);
;             ab0 -= mq[0][0] * xy[40]; ab1 -= mq[0][1] * xy[41]; ab0 -= mq[0][2] * xy[42]; xy[43] = ab0 + ab1; up[5504] = xy[43][0]; wp[5504] = f2bf(-xy[43][1]); mq[0] = *(const LAS f32x4*)(Mg + 2836);
.Ls4_n42:
	v_lshlrev_b32_e32 v229, 16, v229
	v_mul_f32_e32 v232, v229, v219
	v_mul_f32_e32 v230, v232, v3
	v_mov_b32_e32 v231, 0
	ds_read_u16 v228, v7 offset:11968
	ds_read_b128 v[216:219], v8 offset:16832
	ds_read_b128 v[0:3], v8 offset:16576
	s_waitcnt lgkmcnt(8)
	v_fma_f32 v230, -v200, v84, v230
	v_fma_f32 v231, -v201, v85, v231
	v_fma_f32 v230, -v202, v86, v230
	v_fma_f32 v231, -v203, v87, v231
	ds_read_b128 v[200:203], v8 offset:11104
	s_waitcnt lgkmcnt(8)
	v_fma_f32 v230, -v204, v88, v230
	v_fma_f32 v231, -v205, v89, v231
	v_fma_f32 v230, -v206, v90, v230
	v_fma_f32 v231, -v207, v91, v231
	ds_read_b128 v[204:207], v8 offset:11120
	s_waitcnt lgkmcnt(8)
	v_fma_f32 v230, -v208, v92, v230
	v_fma_f32 v231, -v209, v93, v231
	v_fma_f32 v230, -v210, v94, v230
	v_fma_f32 v231, -v211, v95, v231
	ds_read_b128 v[208:211], v8 offset:11136
	s_waitcnt lgkmcnt(8)
	v_fma_f32 v230, -v212, v96, v230
	v_fma_f32 v231, -v213, v97, v231
	v_fma_f32 v230, -v214, v98, v230
	v_fma_f32 v231, -v215, v99, v231
	ds_read_b128 v[212:215], v8 offset:11152
	s_waitcnt lgkmcnt(8)
	v_fma_f32 v230, -v192, v100, v230
	v_fma_f32 v231, -v193, v101, v231
	v_fma_f32 v230, -v194, v102, v230
	v_fma_f32 v231, -v195, v103, v231
	ds_read_b128 v[192:195], v8 offset:11168
	s_waitcnt lgkmcnt(8)
	v_fma_f32 v230, -v196, v104, v230
	v_fma_f32 v231, -v197, v105, v231
	v_fma_f32 v230, -v198, v106, v230
	v_fma_f32 v231, -v199, v107, v231
	ds_read_b128 v[196:199], v8 offset:11264
	s_waitcnt lgkmcnt(5)
	v_fma_f32 v230, -v200, v108, v230
	v_fma_f32 v231, -v201, v109, v231
	v_fma_f32 v230, -v202, v110, v230
	v_fma_f32 v231, -v203, v111, v231
	ds_read_b128 v[200:203], v8 offset:11280
	s_waitcnt lgkmcnt(5)
	v_fma_f32 v230, -v204, v112, v230
	v_fma_f32 v231, -v205, v113, v231
	v_fma_f32 v230, -v206, v114, v230
	v_fma_f32 v231, -v207, v115, v231
	ds_read_b128 v[204:207], v8 offset:11296
	s_waitcnt lgkmcnt(5)
	v_fma_f32 v230, -v208, v116, v230
	v_fma_f32 v231, -v209, v117, v231
	v_fma_f32 v230, -v210, v118, v230
	v_fma_f32 v231, -v211, v119, v231
	ds_read_b128 v[208:211], v8 offset:11312
	s_waitcnt lgkmcnt(5)
	v_fma_f32 v230, -v212, v120, v230
	v_fma_f32 v231, -v213, v121, v231
	v_fma_f32 v230, -v214, v122, v230
	v_fma_f32 v231, -v215, v123, v231
	ds_read_b128 v[212:215], v8 offset:11328
	s_waitcnt lgkmcnt(5)
	v_fma_f32 v230, -v192, v124, v230
	v_fma_f32 v231, -v193, v125, v231
	v_fma_f32 v230, -v194, v126, v230
	ds_read_b128 v[192:195], v8 offset:11344
	v_add_f32_e32 v127, v230, v231
	s_cbranch_vccz .Ls4_u43
	v_cvt_pk_bf16_f32 v233, -v127, v127
	global_store_short v6, v233, s[8:9] offset:2816
	s_branch .Ls4_n43
.Ls4_u43:
	global_store_dword v234, v127, s[8:9] offset:1536
.Ls4_n43:
	v_mul_f32_e32 v224, s16, v224
	v_mul_f32_e32 v225, s16, v225
	v_mul_f32_e32 v226, s16, v226
	v_mul_f32_e32 v227, s16, v227
	v_exp_f32_e32 v224, v224
	v_exp_f32_e32 v225, v225
	v_exp_f32_e32 v226, v226
	v_exp_f32_e32 v227, v227
	s_nop 0
	v_lshlrev_b32_e32 v228, 16, v228
	v_mul_f32_e32 v232, v228, v220
	v_mul_f32_e32 v230, v232, v224
	v_mov_b32_e32 v231, 0
	ds_read_u16 v229, v7 offset:12240
	s_waitcnt lgkmcnt(6)
	v_fma_f32 v230, -v196, v84, v230
	v_fma_f32 v231, -v197, v85, v231
	v_fma_f32 v230, -v198, v86, v230
	v_fma_f32 v231, -v199, v87, v231
	ds_read_b128 v[196:199], v8 offset:11360
	s_waitcnt lgkmcnt(6)
	v_fma_f32 v230, -v200, v88, v230
	v_fma_f32 v231, -v201, v89, v231
	v_fma_f32 v230, -v202, v90, v230
	v_fma_f32 v231, -v203, v91, v231
	ds_read_b128 v[200:203], v8 offset:11376
	s_waitcnt lgkmcnt(6)
	v_fma_f32 v230, -v204, v92, v230
	v_fma_f32 v231, -v205, v93, v231
	v_fma_f32 v230, -v206, v94, v230
	v_fma_f32 v231, -v207, v95, v231
	ds_read_b128 v[204:207], v8 offset:11392
	s_waitcnt lgkmcnt(6)
	v_fma_f32 v230, -v208, v96, v230
	v_fma_f32 v231, -v209, v97, v231
	v_fma_f32 v230, -v210, v98, v230
	v_fma_f32 v231, -v211, v99, v231
	ds_read_b128 v[208:211], v8 offset:11408
	s_waitcnt lgkmcnt(6)
	v_fma_f32 v230, -v212, v100, v230
	v_fma_f32 v231, -v213, v101, v231
	v_fma_f32 v230, -v214, v102, v230
	v_fma_f32 v231, -v215, v103, v231
	ds_read_b128 v[212:215], v8 offset:11424
	s_waitcnt lgkmcnt(6)
	v_fma_f32 v230, -v192, v104, v230
	v_fma_f32 v231, -v193, v105, v231
	v_fma_f32 v230, -v194, v106, v230
	v_fma_f32 v231, -v195, v107, v231
	ds_read_b128 v[192:195], v8 offset:11520
	s_waitcnt lgkmcnt(5)
	v_fma_f32 v230, -v196, v108, v230
	v_fma_f32 v231, -v197, v109, v231
	v_fma_f32 v230, -v198, v110, v230
	v_fma_f32 v231, -v199, v111, v231
	ds_read_b128 v[196:199], v8 offset:11536
	s_waitcnt lgkmcnt(5)
	v_fma_f32 v230, -v200, v112, v230
	v_fma_f32 v231, -v201, v113, v231
	v_fma_f32 v230, -v202, v114, v230
	v_fma_f32 v231, -v203, v115, v231
	ds_read_b128 v[200:203], v8 offset:11552
	s_waitcnt lgkmcnt(5)
	v_fma_f32 v230, -v204, v116, v230
	v_fma_f32 v231, -v205, v117, v231
	v_fma_f32 v230, -v206, v118, v230
	v_fma_f32 v231, -v207, v119, v231
	ds_read_b128 v[204:207], v8 offset:11568
	s_waitcnt lgkmcnt(5)
	v_fma_f32 v230, -v208, v120, v230
	v_fma_f32 v231, -v209, v121, v231
	v_fma_f32 v230, -v210, v122, v230
	v_fma_f32 v231, -v211, v123, v231
	ds_read_b128 v[208:211], v8 offset:11584
	s_waitcnt lgkmcnt(5)
	v_fma_f32 v230, -v212, v124, v230
	v_fma_f32 v231, -v213, v125, v231
	v_fma_f32 v230, -v214, v126, v230
	v_fma_f32 v231, -v215, v127, v231
	ds_read_b128 v[212:215], v8 offset:11600
	v_add_f32_e32 v128, v230, v231
	s_cbranch_vccz .Ls4_u44
	v_cvt_pk_bf16_f32 v233, -v128, v128
	global_store_short v6, v233, s[8:9] offset:3072
	s_branch .Ls4_n44
.Ls4_u44:
	global_store_dword v234, v128, s[8:9] offset:2048
; #define LAS __attribute__((address_space(3)))
; __device__ __forceinline__ float bf2f(unsigned short x) { return __uint_as_float(((unsigned)x) << 16); }
; __device__ __forceinline__ void chunk_prep_phase(const Params& p, int bid, int nblk, LAS unsigned char* lds0) {
;     ...
;             { const float br = betg[45]; ab0 = (f32x2){bf2f(*(const LAS bf16_t*)(lg + P5_VS + 12240 + c * 2)) * br, bf2f(*(const LAS bf16_t*)(lg + P5_KS + 12240 + c * 2)) * br * __expf(decg[45])}; ab1 = (f32x2){0.f, 0.f}; } ab0 -= mq[0][0] * xy[0]; ab1 -= mq[0][1] * xy[1]; ab0 -= mq[0][2] * xy[2]; ab1 -= mq[0][3] * xy[3]; mq[0] = *(const LAS f32x4*)(Mg + 2904);
;             ab0 -= mq[1][0] * xy[4]; ab1 -= mq[1][1] * xy[5]; ab0 -= mq[1][2] * xy[6]; ab1 -= mq[1][3] * xy[7]; mq[1] = *(const LAS f32x4*)(Mg + 2908);
;             ab0 -= mq[2][0] * xy[8]; ab1 -= mq[2][1] * xy[9]; ab0 -= mq[2][2] * xy[10]; ab1 -= mq[2][3] * xy[11]; mq[2] = *(const LAS f32x4*)(Mg + 2912);
;             ab0 -= mq[3][0] * xy[12]; ab1 -= mq[3][1] * xy[13]; ab0 -= mq[3][2] * xy[14]; ab1 -= mq[3][3] * xy[15]; mq[3] = *(const LAS f32x4*)(Mg + 2916);
;             ab0 -= mq[4][0] * xy[16]; ab1 -= mq[4][1] * xy[17]; ab0 -= mq[4][2] * xy[18]; ab1 -= mq[4][3] * xy[19]; mq[4] = *(const LAS f32x4*)(Mg + 2920);
;             ab0 -= mq[5][0] * xy[20]; ab1 -= mq[5][1] * xy[21]; ab0 -= mq[5][2] * xy[22]; ab1 -= mq[5][3] * xy[23]; mq[5] = *(const LAS f32x4*)(Mg + 2924);
;             ab0 -= mq[0][0] * xy[24]; ab1 -= mq[0][1] * xy[25]; ab0 -= mq[0][2] * xy[26]; ab1 -= mq[0][3] * xy[27]; mq[0] = *(const LAS f32x4*)(Mg + 2944);
;             ab0 -= mq[1][0] * xy[28]; ab1 -= mq[1][1] * xy[29]; ab0 -= mq[1][2] * xy[30]; ab1 -= mq[1][3] * xy[31]; mq[1] = *(const LAS f32x4*)(Mg + 2948);
;             ab0 -= mq[2][0] * xy[32]; ab1 -= mq[2][1] * xy[33]; ab0 -= mq[2][2] * xy[34]; ab1 -= mq[2][3] * xy[35]; mq[2] = *(const LAS f32x4*)(Mg + 2952);
;             ab0 -= mq[3][0] * xy[36]; ab1 -= mq[3][1] * xy[37]; ab0 -= mq[3][2] * xy[38]; ab1 -= mq[3][3] * xy[39]; mq[3] = *(const LAS f32x4*)(Mg + 2956);
;             ab0 -= mq[4][0] * xy[40]; ab1 -= mq[4][1] * xy[41]; ab0 -= mq[4][2] * xy[42]; ab1 -= mq[4][3] * xy[43]; mq[4] = *(const LAS f32x4*)(Mg + 2960);
;             ab0 -= mq[5][0] * xy[44]; xy[45] = ab0 + ab1; up[5760] = xy[45][0]; wp[5760] = f2bf(-xy[45][1]); mq[5] = *(const LAS f32x4*)(Mg + 2964);
.Ls4_n44:
	v_lshlrev_b32_e32 v229, 16, v229
	v_mul_f32_e32 v232, v229, v221
	v_mul_f32_e32 v230, v232, v225
	v_mov_b32_e32 v231, 0
	ds_read_u16 v228, v7 offset:12512
	s_waitcnt lgkmcnt(6)
	v_fma_f32 v230, -v192, v84, v230
	v_fma_f32 v231, -v193, v85, v231
	v_fma_f32 v230, -v194, v86, v230
	v_fma_f32 v231, -v195, v87, v231
	ds_read_b128 v[192:195], v8 offset:11616
	s_waitcnt lgkmcnt(6)
	v_fma_f32 v230, -v196, v88, v230
	v_fma_f32 v231, -v197, v89, v231
	v_fma_f32 v230, -v198, v90, v230
	v_fma_f32 v231, -v199, v91, v231
	ds_read_b128 v[196:199], v8 offset:11632
	s_waitcnt lgkmcnt(6)
	v_fma_f32 v230, -v200, v92, v230
	v_fma_f32 v231, -v201, v93, v231
	v_fma_f32 v230, -v202, v94, v230
	v_fma_f32 v231, -v203, v95, v231
	ds_read_b128 v[200:203], v8 offset:11648
	s_waitcnt lgkmcnt(6)
	v_fma_f32 v230, -v204, v96, v230
	v_fma_f32 v231, -v205, v97, v231
	v_fma_f32 v230, -v206, v98, v230
	v_fma_f32 v231, -v207, v99, v231
	ds_read_b128 v[204:207], v8 offset:11664
	s_waitcnt lgkmcnt(6)
	v_fma_f32 v230, -v208, v100, v230
	v_fma_f32 v231, -v209, v101, v231
	v_fma_f32 v230, -v210, v102, v230
	v_fma_f32 v231, -v211, v103, v231
	ds_read_b128 v[208:211], v8 offset:11680
	s_waitcnt lgkmcnt(6)
	v_fma_f32 v230, -v212, v104, v230
	v_fma_f32 v231, -v213, v105, v231
	v_fma_f32 v230, -v214, v106, v230
	v_fma_f32 v231, -v215, v107, v231
	ds_read_b128 v[212:215], v8 offset:11696
	s_waitcnt lgkmcnt(5)
	v_fma_f32 v230, -v192, v108, v230
	v_fma_f32 v231, -v193, v109, v231
	v_fma_f32 v230, -v194, v110, v230
	v_fma_f32 v231, -v195, v111, v231
	ds_read_b128 v[192:195], v8 offset:11776
	s_waitcnt lgkmcnt(5)
	v_fma_f32 v230, -v196, v112, v230
	v_fma_f32 v231, -v197, v113, v231
	v_fma_f32 v230, -v198, v114, v230
	v_fma_f32 v231, -v199, v115, v231
	ds_read_b128 v[196:199], v8 offset:11792
	s_waitcnt lgkmcnt(5)
	v_fma_f32 v230, -v200, v116, v230
	v_fma_f32 v231, -v201, v117, v231
	v_fma_f32 v230, -v202, v118, v230
	v_fma_f32 v231, -v203, v119, v231
	ds_read_b128 v[200:203], v8 offset:11808
	s_waitcnt lgkmcnt(5)
	v_fma_f32 v230, -v204, v120, v230
	v_fma_f32 v231, -v205, v121, v231
	v_fma_f32 v230, -v206, v122, v230
	v_fma_f32 v231, -v207, v123, v231
	ds_read_b128 v[204:207], v8 offset:11824
	s_waitcnt lgkmcnt(5)
	v_fma_f32 v230, -v208, v124, v230
	v_fma_f32 v231, -v209, v125, v231
	v_fma_f32 v230, -v210, v126, v230
	v_fma_f32 v231, -v211, v127, v231
	ds_read_b128 v[208:211], v8 offset:11840
	s_waitcnt lgkmcnt(5)
	v_fma_f32 v230, -v212, v128, v230
	ds_read_b128 v[212:215], v8 offset:11856
	v_add_f32_e32 v129, v230, v231
	s_cbranch_vccz .Ls4_u45
	v_cvt_pk_bf16_f32 v233, -v129, v129
	global_store_short v6, v233, s[8:9] offset:3328
	s_branch .Ls4_n45
.Ls4_u45:
	global_store_dword v234, v129, s[8:9] offset:2560
.Ls4_n45:
	v_lshlrev_b32_e32 v228, 16, v228
	v_mul_f32_e32 v232, v228, v222
	v_mul_f32_e32 v230, v232, v226
	v_mov_b32_e32 v231, 0
	ds_read_u16 v229, v7 offset:12784
	s_waitcnt lgkmcnt(6)
	v_fma_f32 v230, -v192, v84, v230
	v_fma_f32 v231, -v193, v85, v231
	v_fma_f32 v230, -v194, v86, v230
	v_fma_f32 v231, -v195, v87, v231
	ds_read_b128 v[192:195], v8 offset:11872
	s_waitcnt lgkmcnt(6)
	v_fma_f32 v230, -v196, v88, v230
	v_fma_f32 v231, -v197, v89, v231
	v_fma_f32 v230, -v198, v90, v230
	v_fma_f32 v231, -v199, v91, v231
	ds_read_b128 v[196:199], v8 offset:11888
	s_waitcnt lgkmcnt(6)
	v_fma_f32 v230, -v200, v92, v230
	v_fma_f32 v231, -v201, v93, v231
	v_fma_f32 v230, -v202, v94, v230
	v_fma_f32 v231, -v203, v95, v231
	ds_read_b128 v[200:203], v8 offset:11904
	s_waitcnt lgkmcnt(6)
	v_fma_f32 v230, -v204, v96, v230
	v_fma_f32 v231, -v205, v97, v231
	v_fma_f32 v230, -v206, v98, v230
	v_fma_f32 v231, -v207, v99, v231
	ds_read_b128 v[204:207], v8 offset:11920
	s_waitcnt lgkmcnt(6)
	v_fma_f32 v230, -v208, v100, v230
	v_fma_f32 v231, -v209, v101, v231
	v_fma_f32 v230, -v210, v102, v230
	v_fma_f32 v231, -v211, v103, v231
	ds_read_b128 v[208:211], v8 offset:11936
	s_waitcnt lgkmcnt(6)
	v_fma_f32 v230, -v212, v104, v230
	v_fma_f32 v231, -v213, v105, v231
	v_fma_f32 v230, -v214, v106, v230
	v_fma_f32 v231, -v215, v107, v231
	ds_read_b128 v[212:215], v8 offset:11952
	s_waitcnt lgkmcnt(5)
	v_fma_f32 v230, -v192, v108, v230
	v_fma_f32 v231, -v193, v109, v231
	v_fma_f32 v230, -v194, v110, v230
	v_fma_f32 v231, -v195, v111, v231
	ds_read_b128 v[192:195], v8 offset:12032
	s_waitcnt lgkmcnt(5)
	v_fma_f32 v230, -v196, v112, v230
	v_fma_f32 v231, -v197, v113, v231
	v_fma_f32 v230, -v198, v114, v230
	v_fma_f32 v231, -v199, v115, v231
	ds_read_b128 v[196:199], v8 offset:12048
	s_waitcnt lgkmcnt(5)
	v_fma_f32 v230, -v200, v116, v230
	v_fma_f32 v231, -v201, v117, v231
	v_fma_f32 v230, -v202, v118, v230
	v_fma_f32 v231, -v203, v119, v231
	ds_read_b128 v[200:203], v8 offset:12064
	s_waitcnt lgkmcnt(5)
	v_fma_f32 v230, -v204, v120, v230
	v_fma_f32 v231, -v205, v121, v231
	v_fma_f32 v230, -v206, v122, v230
	v_fma_f32 v231, -v207, v123, v231
	ds_read_b128 v[204:207], v8 offset:12080
	s_waitcnt lgkmcnt(5)
	v_fma_f32 v230, -v208, v124, v230
	v_fma_f32 v231, -v209, v125, v231
	v_fma_f32 v230, -v210, v126, v230
	v_fma_f32 v231, -v211, v127, v231
	ds_read_b128 v[208:211], v8 offset:12096
	s_waitcnt lgkmcnt(5)
	v_fma_f32 v230, -v212, v128, v230
	v_fma_f32 v231, -v213, v129, v231
	ds_read_b128 v[212:215], v8 offset:12112
	v_add_f32_e32 v130, v230, v231
	s_cbranch_vccz .Ls4_u46
	v_cvt_pk_bf16_f32 v233, -v130, v130
	global_store_short v6, v233, s[8:9] offset:3584
	s_branch .Ls4_n46
.Ls4_u46:
	global_store_dword v234, v130, s[8:9] offset:3072
; #define LAS __attribute__((address_space(3)))
; __device__ __forceinline__ void chunk_prep_phase(const Params& p, int bid, int nblk, LAS unsigned char* lds0) {
;     ...
;             { const float br = betg[47]; ab0 = (f32x2){bf2f(*(const LAS bf16_t*)(lg + P5_VS + 12784 + c * 2)) * br, bf2f(*(const LAS bf16_t*)(lg + P5_KS + 12784 + c * 2)) * br * __expf(decg[47])}; ab1 = (f32x2){0.f, 0.f}; } ab0 -= mq[0][0] * xy[0]; ab1 -= mq[0][1] * xy[1]; ab0 -= mq[0][2] * xy[2]; ab1 -= mq[0][3] * xy[3]; mq[0] = *(const LAS f32x4*)(Mg + 3032);
;             ab0 -= mq[1][0] * xy[4]; ab1 -= mq[1][1] * xy[5]; ab0 -= mq[1][2] * xy[6]; ab1 -= mq[1][3] * xy[7]; mq[1] = *(const LAS f32x4*)(Mg + 3036);
;             ab0 -= mq[2][0] * xy[8]; ab1 -= mq[2][1] * xy[9]; ab0 -= mq[2][2] * xy[10]; ab1 -= mq[2][3] * xy[11]; mq[2] = *(const LAS f32x4*)(Mg + 3040);
;             ab0 -= mq[3][0] * xy[12]; ab1 -= mq[3][1] * xy[13]; ab0 -= mq[3][2] * xy[14]; ab1 -= mq[3][3] * xy[15]; mq[3] = *(const LAS f32x4*)(Mg + 3044);
;             ab0 -= mq[4][0] * xy[16]; ab1 -= mq[4][1] * xy[17]; ab0 -= mq[4][2] * xy[18]; ab1 -= mq[4][3] * xy[19]; mq[4] = *(const LAS f32x4*)(Mg + 3048);
;             ab0 -= mq[5][0] * xy[20]; ab1 -= mq[5][1] * xy[21]; ab0 -= mq[5][2] * xy[22]; ab1 -= mq[5][3] * xy[23]; mq[5] = *(const LAS f32x4*)(Mg + 3052);
;             ab0 -= mq[0][0] * xy[24]; ab1 -= mq[0][1] * xy[25]; ab0 -= mq[0][2] * xy[26]; ab1 -= mq[0][3] * xy[27]; mq[0] = *(const LAS f32x4*)(Mg + 3072);
;             ab0 -= mq[1][0] * xy[28]; ab1 -= mq[1][1] * xy[29]; ab0 -= mq[1][2] * xy[30]; ab1 -= mq[1][3] * xy[31]; mq[1] = *(const LAS f32x4*)(Mg + 3076);
;             ab0 -= mq[2][0] * xy[32]; ab1 -= mq[2][1] * xy[33]; ab0 -= mq[2][2] * xy[34]; ab1 -= mq[2][3] * xy[35]; mq[2] = *(const LAS f32x4*)(Mg + 3080);
;             ab0 -= mq[3][0] * xy[36]; ab1 -= mq[3][1] * xy[37]; ab0 -= mq[3][2] * xy[38]; ab1 -= mq[3][3] * xy[39]; mq[3] = *(const LAS f32x4*)(Mg + 3084);
;             ab0 -= mq[4][0] * xy[40]; ab1 -= mq[4][1] * xy[41]; ab0 -= mq[4][2] * xy[42]; ab1 -= mq[4][3] * xy[43]; mq[4] = *(const LAS f32x4*)(Mg + 3088);
;             ab0 -= mq[5][0] * xy[44]; ab1 -= mq[5][1] * xy[45]; ab0 -= mq[5][2] * xy[46]; xy[47] = ab0 + ab1; up[6016] = xy[47][0]; wp[6016] = f2bf(-xy[47][1]); mq[5] = *(const LAS f32x4*)(Mg + 3092);
.Ls4_n46:
	v_lshlrev_b32_e32 v229, 16, v229
	v_mul_f32_e32 v232, v229, v223
	v_mul_f32_e32 v230, v232, v227
	v_mov_b32_e32 v231, 0
	ds_read_u16 v228, v7 offset:13056
	ds_read_b128 v[220:223], v8 offset:16848
	ds_read_b128 v[224:227], v8 offset:16592
	s_waitcnt lgkmcnt(8)
	v_fma_f32 v230, -v192, v84, v230
	v_fma_f32 v231, -v193, v85, v231
	v_fma_f32 v230, -v194, v86, v230
	v_fma_f32 v231, -v195, v87, v231
	ds_read_b128 v[192:195], v8 offset:12128
	s_waitcnt lgkmcnt(8)
	v_fma_f32 v230, -v196, v88, v230
	v_fma_f32 v231, -v197, v89, v231
	v_fma_f32 v230, -v198, v90, v230
	v_fma_f32 v231, -v199, v91, v231
	ds_read_b128 v[196:199], v8 offset:12144
	s_waitcnt lgkmcnt(8)
	v_fma_f32 v230, -v200, v92, v230
	v_fma_f32 v231, -v201, v93, v231
	v_fma_f32 v230, -v202, v94, v230
	v_fma_f32 v231, -v203, v95, v231
	ds_read_b128 v[200:203], v8 offset:12160
	s_waitcnt lgkmcnt(8)
	v_fma_f32 v230, -v204, v96, v230
	v_fma_f32 v231, -v205, v97, v231
	v_fma_f32 v230, -v206, v98, v230
	v_fma_f32 v231, -v207, v99, v231
	ds_read_b128 v[204:207], v8 offset:12176
	s_waitcnt lgkmcnt(8)
	v_fma_f32 v230, -v208, v100, v230
	v_fma_f32 v231, -v209, v101, v231
	v_fma_f32 v230, -v210, v102, v230
	v_fma_f32 v231, -v211, v103, v231
	ds_read_b128 v[208:211], v8 offset:12192
	s_waitcnt lgkmcnt(8)
	v_fma_f32 v230, -v212, v104, v230
	v_fma_f32 v231, -v213, v105, v231
	v_fma_f32 v230, -v214, v106, v230
	v_fma_f32 v231, -v215, v107, v231
	ds_read_b128 v[212:215], v8 offset:12208
	s_waitcnt lgkmcnt(5)
	v_fma_f32 v230, -v192, v108, v230
	v_fma_f32 v231, -v193, v109, v231
	v_fma_f32 v230, -v194, v110, v230
	v_fma_f32 v231, -v195, v111, v231
	ds_read_b128 v[192:195], v8 offset:12288
	s_waitcnt lgkmcnt(5)
	v_fma_f32 v230, -v196, v112, v230
	v_fma_f32 v231, -v197, v113, v231
	v_fma_f32 v230, -v198, v114, v230
	v_fma_f32 v231, -v199, v115, v231
	ds_read_b128 v[196:199], v8 offset:12304
	s_waitcnt lgkmcnt(5)
	v_fma_f32 v230, -v200, v116, v230
	v_fma_f32 v231, -v201, v117, v231
	v_fma_f32 v230, -v202, v118, v230
	v_fma_f32 v231, -v203, v119, v231
	ds_read_b128 v[200:203], v8 offset:12320
	s_waitcnt lgkmcnt(5)
	v_fma_f32 v230, -v204, v120, v230
	v_fma_f32 v231, -v205, v121, v231
	v_fma_f32 v230, -v206, v122, v230
	v_fma_f32 v231, -v207, v123, v231
	ds_read_b128 v[204:207], v8 offset:12336
	s_waitcnt lgkmcnt(5)
	v_fma_f32 v230, -v208, v124, v230
	v_fma_f32 v231, -v209, v125, v231
	v_fma_f32 v230, -v210, v126, v230
	v_fma_f32 v231, -v211, v127, v231
	ds_read_b128 v[208:211], v8 offset:12352
	s_waitcnt lgkmcnt(5)
	v_fma_f32 v230, -v212, v128, v230
	v_fma_f32 v231, -v213, v129, v231
	v_fma_f32 v230, -v214, v130, v230
	ds_read_b128 v[212:215], v8 offset:12368
	v_add_f32_e32 v131, v230, v231
	s_cbranch_vccz .Ls4_u47
	v_cvt_pk_bf16_f32 v233, -v131, v131
	global_store_short v6, v233, s[8:9] offset:3840
	s_branch .Ls4_n47
.Ls4_u47:
	global_store_dword v234, v131, s[8:9] offset:3584
.Ls4_n47:
	v_mul_f32_e32 v0, s16, v0
	v_mul_f32_e32 v1, s16, v1
	v_mul_f32_e32 v2, s16, v2
	v_mul_f32_e32 v3, s16, v3
	v_exp_f32_e32 v0, v0
	v_exp_f32_e32 v1, v1
	v_exp_f32_e32 v2, v2
	v_exp_f32_e32 v3, v3
	s_nop 0
	v_lshlrev_b32_e32 v228, 16, v228
	v_mul_f32_e32 v232, v228, v216
	v_mul_f32_e32 v230, v232, v0
	v_mov_b32_e32 v231, 0
	ds_read_u16 v229, v7 offset:13328
	s_waitcnt lgkmcnt(6)
	v_fma_f32 v230, -v192, v84, v230
	v_fma_f32 v231, -v193, v85, v231
	v_fma_f32 v230, -v194, v86, v230
	v_fma_f32 v231, -v195, v87, v231
	ds_read_b128 v[192:195], v8 offset:12384
	s_waitcnt lgkmcnt(6)
	v_fma_f32 v230, -v196, v88, v230
	v_fma_f32 v231, -v197, v89, v231
	v_fma_f32 v230, -v198, v90, v230
	v_fma_f32 v231, -v199, v91, v231
	ds_read_b128 v[196:199], v8 offset:12400
	s_waitcnt lgkmcnt(6)
	v_fma_f32 v230, -v200, v92, v230
	v_fma_f32 v231, -v201, v93, v231
	v_fma_f32 v230, -v202, v94, v230
	v_fma_f32 v231, -v203, v95, v231
	ds_read_b128 v[200:203], v8 offset:12416
	s_waitcnt lgkmcnt(6)
	v_fma_f32 v230, -v204, v96, v230
	v_fma_f32 v231, -v205, v97, v231
	v_fma_f32 v230, -v206, v98, v230
	v_fma_f32 v231, -v207, v99, v231
	ds_read_b128 v[204:207], v8 offset:12432
	s_waitcnt lgkmcnt(6)
	v_fma_f32 v230, -v208, v100, v230
	v_fma_f32 v231, -v209, v101, v231
	v_fma_f32 v230, -v210, v102, v230
	v_fma_f32 v231, -v211, v103, v231
	ds_read_b128 v[208:211], v8 offset:12448
	s_waitcnt lgkmcnt(6)
	v_fma_f32 v230, -v212, v104, v230
	v_fma_f32 v231, -v213, v105, v231
	v_fma_f32 v230, -v214, v106, v230
	v_fma_f32 v231, -v215, v107, v231
	ds_read_b128 v[212:215], v8 offset:12464
	s_waitcnt lgkmcnt(5)
	v_fma_f32 v230, -v192, v108, v230
	v_fma_f32 v231, -v193, v109, v231
	v_fma_f32 v230, -v194, v110, v230
	v_fma_f32 v231, -v195, v111, v231
	ds_read_b128 v[192:195], v8 offset:12544
	s_waitcnt lgkmcnt(5)
	v_fma_f32 v230, -v196, v112, v230
	v_fma_f32 v231, -v197, v113, v231
	v_fma_f32 v230, -v198, v114, v230
	v_fma_f32 v231, -v199, v115, v231
	ds_read_b128 v[196:199], v8 offset:12560
	s_waitcnt lgkmcnt(5)
	v_fma_f32 v230, -v200, v116, v230
	v_fma_f32 v231, -v201, v117, v231
	v_fma_f32 v230, -v202, v118, v230
	v_fma_f32 v231, -v203, v119, v231
	ds_read_b128 v[200:203], v8 offset:12576
	s_waitcnt lgkmcnt(5)
	v_fma_f32 v230, -v204, v120, v230
	v_fma_f32 v231, -v205, v121, v231
	v_fma_f32 v230, -v206, v122, v230
	v_fma_f32 v231, -v207, v123, v231
	ds_read_b128 v[204:207], v8 offset:12592
	s_waitcnt lgkmcnt(5)
	v_fma_f32 v230, -v208, v124, v230
	v_fma_f32 v231, -v209, v125, v231
	v_fma_f32 v230, -v210, v126, v230
	v_fma_f32 v231, -v211, v127, v231
	ds_read_b128 v[208:211], v8 offset:12608
	s_waitcnt lgkmcnt(5)
	v_fma_f32 v230, -v212, v128, v230
	v_fma_f32 v231, -v213, v129, v231
	v_fma_f32 v230, -v214, v130, v230
	v_fma_f32 v231, -v215, v131, v231
	ds_read_b128 v[212:215], v8 offset:12624
	v_add_f32_e32 v132, v230, v231
	s_cbranch_vccz .Ls4_u48
	s_add_u32 s8, s8, 0x1000
	s_addc_u32 s9, s9, 0
	v_cvt_pk_bf16_f32 v233, -v132, v132
	global_store_short v6, v233, s[8:9] offset:0
	s_branch .Ls4_n48
; __device__ __forceinline__ void chunk_prep_phase(const Params& p, int bid, int nblk, LAS unsigned char* lds0) {
;     ...
;             { const float br = betg[49]; ab0 = (f32x2){bf2f(*(const LAS bf16_t*)(lg + P5_VS + 13328 + c * 2)) * br, bf2f(*(const LAS bf16_t*)(lg + P5_KS + 13328 + c * 2)) * br * __expf(decg[49])}; ab1 = (f32x2){0.f, 0.f}; } ab0 -= mq[0][0] * xy[0]; ab1 -= mq[0][1] * xy[1]; ab0 -= mq[0][2] * xy[2]; ab1 -= mq[0][3] * xy[3]; mq[0] = *(const LAS f32x4*)(Mg + 3160);
;             ab0 -= mq[1][0] * xy[4]; ab1 -= mq[1][1] * xy[5]; ab0 -= mq[1][2] * xy[6]; ab1 -= mq[1][3] * xy[7]; mq[1] = *(const LAS f32x4*)(Mg + 3164);
;             ab0 -= mq[2][0] * xy[8]; ab1 -= mq[2][1] * xy[9]; ab0 -= mq[2][2] * xy[10]; ab1 -= mq[2][3] * xy[11]; mq[2] = *(const LAS f32x4*)(Mg + 3168);
;             ab0 -= mq[3][0] * xy[12]; ab1 -= mq[3][1] * xy[13]; ab0 -= mq[3][2] * xy[14]; ab1 -= mq[3][3] * xy[15]; mq[3] = *(const LAS f32x4*)(Mg + 3172);
;             ab0 -= mq[4][0] * xy[16]; ab1 -= mq[4][1] * xy[17]; ab0 -= mq[4][2] * xy[18]; ab1 -= mq[4][3] * xy[19]; mq[4] = *(const LAS f32x4*)(Mg + 3176);
;             ab0 -= mq[5][0] * xy[20]; ab1 -= mq[5][1] * xy[21]; ab0 -= mq[5][2] * xy[22]; ab1 -= mq[5][3] * xy[23]; mq[5] = *(const LAS f32x4*)(Mg + 3180);
;             ab0 -= mq[0][0] * xy[24]; ab1 -= mq[0][1] * xy[25]; ab0 -= mq[0][2] * xy[26]; ab1 -= mq[0][3] * xy[27]; mq[0] = *(const LAS f32x4*)(Mg + 3184);
;             ab0 -= mq[1][0] * xy[28]; ab1 -= mq[1][1] * xy[29]; ab0 -= mq[1][2] * xy[30]; ab1 -= mq[1][3] * xy[31]; mq[1] = *(const LAS f32x4*)(Mg + 3200);
;             ab0 -= mq[2][0] * xy[32]; ab1 -= mq[2][1] * xy[33]; ab0 -= mq[2][2] * xy[34]; ab1 -= mq[2][3] * xy[35]; mq[2] = *(const LAS f32x4*)(Mg + 3204);
;             ab0 -= mq[3][0] * xy[36]; ab1 -= mq[3][1] * xy[37]; ab0 -= mq[3][2] * xy[38]; ab1 -= mq[3][3] * xy[39]; mq[3] = *(const LAS f32x4*)(Mg + 3208);
;             ab0 -= mq[4][0] * xy[40]; ab1 -= mq[4][1] * xy[41]; ab0 -= mq[4][2] * xy[42]; ab1 -= mq[4][3] * xy[43]; mq[4] = *(const LAS f32x4*)(Mg + 3212);
;             ab0 -= mq[5][0] * xy[44]; ab1 -= mq[5][1] * xy[45]; ab0 -= mq[5][2] * xy[46]; ab1 -= mq[5][3] * xy[47]; mq[5] = *(const LAS f32x4*)(Mg + 3216);
;             ab0 -= mq[0][0] * xy[48]; xy[49] = ab0 + ab1; up[6272] = xy[49][0]; wp[6272] = f2bf(-xy[49][1]); mq[0] = *(const LAS f32x4*)(Mg + 3220);
.Ls4_u48:
	s_add_u32 s8, s8, 0x1000
	s_addc_u32 s9, s9, 0
	global_store_dword v234, v132, s[8:9] offset:0
.Ls4_n48:
	v_lshlrev_b32_e32 v229, 16, v229
	v_mul_f32_e32 v232, v229, v217
	v_mul_f32_e32 v230, v232, v1
	v_mov_b32_e32 v231, 0
	ds_read_u16 v228, v7 offset:13600
	s_waitcnt lgkmcnt(6)
	v_fma_f32 v230, -v192, v84, v230
	v_fma_f32 v231, -v193, v85, v231
	v_fma_f32 v230, -v194, v86, v230
	v_fma_f32 v231, -v195, v87, v231
	ds_read_b128 v[192:195], v8 offset:12640
	s_waitcnt lgkmcnt(6)
	v_fma_f32 v230, -v196, v88, v230
	v_fma_f32 v231, -v197, v89, v231
	v_fma_f32 v230, -v198, v90, v230
	v_fma_f32 v231, -v199, v91, v231
	ds_read_b128 v[196:199], v8 offset:12656
	s_waitcnt lgkmcnt(6)
	v_fma_f32 v230, -v200, v92, v230
	v_fma_f32 v231, -v201, v93, v231
	v_fma_f32 v230, -v202, v94, v230
	v_fma_f32 v231, -v203, v95, v231
	ds_read_b128 v[200:203], v8 offset:12672
	s_waitcnt lgkmcnt(6)
	v_fma_f32 v230, -v204, v96, v230
	v_fma_f32 v231, -v205, v97, v231
	v_fma_f32 v230, -v206, v98, v230
	v_fma_f32 v231, -v207, v99, v231
	ds_read_b128 v[204:207], v8 offset:12688
	s_waitcnt lgkmcnt(6)
	v_fma_f32 v230, -v208, v100, v230
	v_fma_f32 v231, -v209, v101, v231
	v_fma_f32 v230, -v210, v102, v230
	v_fma_f32 v231, -v211, v103, v231
	ds_read_b128 v[208:211], v8 offset:12704
	s_waitcnt lgkmcnt(6)
	v_fma_f32 v230, -v212, v104, v230
	v_fma_f32 v231, -v213, v105, v231
	v_fma_f32 v230, -v214, v106, v230
	v_fma_f32 v231, -v215, v107, v231
	ds_read_b128 v[212:215], v8 offset:12720
	s_waitcnt lgkmcnt(5)
	v_fma_f32 v230, -v192, v108, v230
	v_fma_f32 v231, -v193, v109, v231
	v_fma_f32 v230, -v194, v110, v230
	v_fma_f32 v231, -v195, v111, v231
	ds_read_b128 v[192:195], v8 offset:12736
	s_waitcnt lgkmcnt(5)
	v_fma_f32 v230, -v196, v112, v230
	v_fma_f32 v231, -v197, v113, v231
	v_fma_f32 v230, -v198, v114, v230
	v_fma_f32 v231, -v199, v115, v231
	ds_read_b128 v[196:199], v8 offset:12800
	s_waitcnt lgkmcnt(5)
	v_fma_f32 v230, -v200, v116, v230
	v_fma_f32 v231, -v201, v117, v231
	v_fma_f32 v230, -v202, v118, v230
	v_fma_f32 v231, -v203, v119, v231
	ds_read_b128 v[200:203], v8 offset:12816
	s_waitcnt lgkmcnt(5)
	v_fma_f32 v230, -v204, v120, v230
	v_fma_f32 v231, -v205, v121, v231
	v_fma_f32 v230, -v206, v122, v230
	v_fma_f32 v231, -v207, v123, v231
	ds_read_b128 v[204:207], v8 offset:12832
	s_waitcnt lgkmcnt(5)
	v_fma_f32 v230, -v208, v124, v230
	v_fma_f32 v231, -v209, v125, v231
	v_fma_f32 v230, -v210, v126, v230
	v_fma_f32 v231, -v211, v127, v231
	ds_read_b128 v[208:211], v8 offset:12848
	s_waitcnt lgkmcnt(5)
	v_fma_f32 v230, -v212, v128, v230
	v_fma_f32 v231, -v213, v129, v231
	v_fma_f32 v230, -v214, v130, v230
	v_fma_f32 v231, -v215, v131, v231
	ds_read_b128 v[212:215], v8 offset:12864
	s_waitcnt lgkmcnt(5)
	v_fma_f32 v230, -v192, v132, v230
	ds_read_b128 v[192:195], v8 offset:12880
	v_add_f32_e32 v133, v230, v231
	s_cbranch_vccz .Ls4_u49
	v_cvt_pk_bf16_f32 v233, -v133, v133
	global_store_short v6, v233, s[8:9] offset:256
	s_branch .Ls4_n49
.Ls4_u49:
	global_store_dword v234, v133, s[8:9] offset:512
.Ls4_n49:
	v_lshlrev_b32_e32 v228, 16, v228
	v_mul_f32_e32 v232, v228, v218
	v_mul_f32_e32 v230, v232, v2
	v_mov_b32_e32 v231, 0
	ds_read_u16 v229, v7 offset:13872
	s_waitcnt lgkmcnt(6)
	v_fma_f32 v230, -v196, v84, v230
	v_fma_f32 v231, -v197, v85, v231
	v_fma_f32 v230, -v198, v86, v230
	v_fma_f32 v231, -v199, v87, v231
	ds_read_b128 v[196:199], v8 offset:12896
	s_waitcnt lgkmcnt(6)
	v_fma_f32 v230, -v200, v88, v230
	v_fma_f32 v231, -v201, v89, v231
	v_fma_f32 v230, -v202, v90, v230
	v_fma_f32 v231, -v203, v91, v231
	ds_read_b128 v[200:203], v8 offset:12912
	s_waitcnt lgkmcnt(6)
	v_fma_f32 v230, -v204, v92, v230
	v_fma_f32 v231, -v205, v93, v231
	v_fma_f32 v230, -v206, v94, v230
	v_fma_f32 v231, -v207, v95, v231
	ds_read_b128 v[204:207], v8 offset:12928
	s_waitcnt lgkmcnt(6)
	v_fma_f32 v230, -v208, v96, v230
	v_fma_f32 v231, -v209, v97, v231
	v_fma_f32 v230, -v210, v98, v230
	v_fma_f32 v231, -v211, v99, v231
	ds_read_b128 v[208:211], v8 offset:12944
	s_waitcnt lgkmcnt(6)
	v_fma_f32 v230, -v212, v100, v230
	v_fma_f32 v231, -v213, v101, v231
	v_fma_f32 v230, -v214, v102, v230
	v_fma_f32 v231, -v215, v103, v231
	ds_read_b128 v[212:215], v8 offset:12960
	s_waitcnt lgkmcnt(6)
	v_fma_f32 v230, -v192, v104, v230
	v_fma_f32 v231, -v193, v105, v231
	v_fma_f32 v230, -v194, v106, v230
	v_fma_f32 v231, -v195, v107, v231
	ds_read_b128 v[192:195], v8 offset:12976
	s_waitcnt lgkmcnt(5)
	v_fma_f32 v230, -v196, v108, v230
	v_fma_f32 v231, -v197, v109, v231
	v_fma_f32 v230, -v198, v110, v230
	v_fma_f32 v231, -v199, v111, v231
	ds_read_b128 v[196:199], v8 offset:12992
	s_waitcnt lgkmcnt(5)
	v_fma_f32 v230, -v200, v112, v230
	v_fma_f32 v231, -v201, v113, v231
	v_fma_f32 v230, -v202, v114, v230
	v_fma_f32 v231, -v203, v115, v231
	ds_read_b128 v[200:203], v8 offset:13056
	s_waitcnt lgkmcnt(5)
	v_fma_f32 v230, -v204, v116, v230
	v_fma_f32 v231, -v205, v117, v231
	v_fma_f32 v230, -v206, v118, v230
	v_fma_f32 v231, -v207, v119, v231
	ds_read_b128 v[204:207], v8 offset:13072
	s_waitcnt lgkmcnt(5)
	v_fma_f32 v230, -v208, v120, v230
	v_fma_f32 v231, -v209, v121, v231
	v_fma_f32 v230, -v210, v122, v230
	v_fma_f32 v231, -v211, v123, v231
	ds_read_b128 v[208:211], v8 offset:13088
	s_waitcnt lgkmcnt(5)
	v_fma_f32 v230, -v212, v124, v230
	v_fma_f32 v231, -v213, v125, v231
	v_fma_f32 v230, -v214, v126, v230
	v_fma_f32 v231, -v215, v127, v231
	ds_read_b128 v[212:215], v8 offset:13104
	s_waitcnt lgkmcnt(5)
	v_fma_f32 v230, -v192, v128, v230
	v_fma_f32 v231, -v193, v129, v231
	v_fma_f32 v230, -v194, v130, v230
	v_fma_f32 v231, -v195, v131, v231
	ds_read_b128 v[192:195], v8 offset:13120
	s_waitcnt lgkmcnt(5)
	v_fma_f32 v230, -v196, v132, v230
	v_fma_f32 v231, -v197, v133, v231
	ds_read_b128 v[196:199], v8 offset:13136
	v_add_f32_e32 v134, v230, v231
	s_cbranch_vccz .Ls4_u50
	v_cvt_pk_bf16_f32 v233, -v134, v134
	global_store_short v6, v233, s[8:9] offset:512
	s_branch .Ls4_n50
; #define LAS __attribute__((address_space(3)))
; __device__ __forceinline__ float bf2f(unsigned short x) { return __uint_as_float(((unsigned)x) << 16); }
; __device__ __forceinline__ void chunk_prep_phase(const Params& p, int bid, int nblk, LAS unsigned char* lds0) {
;     ...
;             { const float br = betg[51]; ab0 = (f32x2){bf2f(*(const LAS bf16_t*)(lg + P5_VS + 13872 + c * 2)) * br, bf2f(*(const LAS bf16_t*)(lg + P5_KS + 13872 + c * 2)) * br * __expf(decg[51])}; ab1 = (f32x2){0.f, 0.f}; } ab0 -= mq[2][0] * xy[0]; ab1 -= mq[2][1] * xy[1]; ab0 -= mq[2][2] * xy[2]; ab1 -= mq[2][3] * xy[3]; mq[2] = *(const LAS f32x4*)(Mg + 3288);
;             ab0 -= mq[3][0] * xy[4]; ab1 -= mq[3][1] * xy[5]; ab0 -= mq[3][2] * xy[6]; ab1 -= mq[3][3] * xy[7]; mq[3] = *(const LAS f32x4*)(Mg + 3292);
;             ab0 -= mq[4][0] * xy[8]; ab1 -= mq[4][1] * xy[9]; ab0 -= mq[4][2] * xy[10]; ab1 -= mq[4][3] * xy[11]; mq[4] = *(const LAS f32x4*)(Mg + 3296);
;             ab0 -= mq[5][0] * xy[12]; ab1 -= mq[5][1] * xy[13]; ab0 -= mq[5][2] * xy[14]; ab1 -= mq[5][3] * xy[15]; mq[5] = *(const LAS f32x4*)(Mg + 3300);
;             ab0 -= mq[0][0] * xy[16]; ab1 -= mq[0][1] * xy[17]; ab0 -= mq[0][2] * xy[18]; ab1 -= mq[0][3] * xy[19]; mq[0] = *(const LAS f32x4*)(Mg + 3304);
;             ab0 -= mq[1][0] * xy[20]; ab1 -= mq[1][1] * xy[21]; ab0 -= mq[1][2] * xy[22]; ab1 -= mq[1][3] * xy[23]; mq[1] = *(const LAS f32x4*)(Mg + 3308);
;             ab0 -= mq[2][0] * xy[24]; ab1 -= mq[2][1] * xy[25]; ab0 -= mq[2][2] * xy[26]; ab1 -= mq[2][3] * xy[27]; mq[2] = *(const LAS f32x4*)(Mg + 3312);
;             ab0 -= mq[3][0] * xy[28]; ab1 -= mq[3][1] * xy[29]; ab0 -= mq[3][2] * xy[30]; ab1 -= mq[3][3] * xy[31]; mq[3] = *(const LAS f32x4*)(Mg + 3328);
;             ab0 -= mq[4][0] * xy[32]; ab1 -= mq[4][1] * xy[33]; ab0 -= mq[4][2] * xy[34]; ab1 -= mq[4][3] * xy[35]; mq[4] = *(const LAS f32x4*)(Mg + 3332);
;             ab0 -= mq[5][0] * xy[36]; ab1 -= mq[5][1] * xy[37]; ab0 -= mq[5][2] * xy[38]; ab1 -= mq[5][3] * xy[39]; mq[5] = *(const LAS f32x4*)(Mg + 3336);
;             ab0 -= mq[0][0] * xy[40]; ab1 -= mq[0][1] * xy[41]; ab0 -= mq[0][2] * xy[42]; ab1 -= mq[0][3] * xy[43]; mq[0] = *(const LAS f32x4*)(Mg + 3340);
;             ab0 -= mq[1][0] * xy[44]; ab1 -= mq[1][1] * xy[45]; ab0 -= mq[1][2] * xy[46]; ab1 -= mq[1][3] * xy[47]; mq[1] = *(const LAS f32x4*)(Mg + 3344);
.Ls4_u50:
	global_store_dword v234, v134, s[8:9] offset:1024
.Ls4_n50:
	v_lshlrev_b32_e32 v229, 16, v229
	v_mul_f32_e32 v232, v229, v219
	v_mul_f32_e32 v230, v232, v3
	v_mov_b32_e32 v231, 0
	ds_read_u16 v228, v7 offset:14144
	ds_read_b128 v[216:219], v8 offset:16864
	ds_read_b128 v[0:3], v8 offset:16608
	s_waitcnt lgkmcnt(8)
	v_fma_f32 v230, -v200, v84, v230
	v_fma_f32 v231, -v201, v85, v231
	v_fma_f32 v230, -v202, v86, v230
	v_fma_f32 v231, -v203, v87, v231
	ds_read_b128 v[200:203], v8 offset:13152
	s_waitcnt lgkmcnt(8)
	v_fma_f32 v230, -v204, v88, v230
	v_fma_f32 v231, -v205, v89, v231
	v_fma_f32 v230, -v206, v90, v230
	v_fma_f32 v231, -v207, v91, v231
	ds_read_b128 v[204:207], v8 offset:13168
	s_waitcnt lgkmcnt(8)
	v_fma_f32 v230, -v208, v92, v230
	v_fma_f32 v231, -v209, v93, v231
	v_fma_f32 v230, -v210, v94, v230
	v_fma_f32 v231, -v211, v95, v231
	ds_read_b128 v[208:211], v8 offset:13184
	s_waitcnt lgkmcnt(8)
	v_fma_f32 v230, -v212, v96, v230
	v_fma_f32 v231, -v213, v97, v231
	v_fma_f32 v230, -v214, v98, v230
	v_fma_f32 v231, -v215, v99, v231
	ds_read_b128 v[212:215], v8 offset:13200
	s_waitcnt lgkmcnt(8)
	v_fma_f32 v230, -v192, v100, v230
	v_fma_f32 v231, -v193, v101, v231
	v_fma_f32 v230, -v194, v102, v230
	v_fma_f32 v231, -v195, v103, v231
	ds_read_b128 v[192:195], v8 offset:13216
	s_waitcnt lgkmcnt(8)
	v_fma_f32 v230, -v196, v104, v230
	v_fma_f32 v231, -v197, v105, v231
	v_fma_f32 v230, -v198, v106, v230
	v_fma_f32 v231, -v199, v107, v231
	ds_read_b128 v[196:199], v8 offset:13232
	s_waitcnt lgkmcnt(5)
	v_fma_f32 v230, -v200, v108, v230
	v_fma_f32 v231, -v201, v109, v231
	v_fma_f32 v230, -v202, v110, v230
	v_fma_f32 v231, -v203, v111, v231
	ds_read_b128 v[200:203], v8 offset:13248
	s_waitcnt lgkmcnt(5)
	v_fma_f32 v230, -v204, v112, v230
	v_fma_f32 v231, -v205, v113, v231
	v_fma_f32 v230, -v206, v114, v230
	v_fma_f32 v231, -v207, v115, v231
	ds_read_b128 v[204:207], v8 offset:13312
	s_waitcnt lgkmcnt(5)
	v_fma_f32 v230, -v208, v116, v230
	v_fma_f32 v231, -v209, v117, v231
	v_fma_f32 v230, -v210, v118, v230
	v_fma_f32 v231, -v211, v119, v231
	ds_read_b128 v[208:211], v8 offset:13328
	s_waitcnt lgkmcnt(5)
	v_fma_f32 v230, -v212, v120, v230
	v_fma_f32 v231, -v213, v121, v231
	v_fma_f32 v230, -v214, v122, v230
	v_fma_f32 v231, -v215, v123, v231
	ds_read_b128 v[212:215], v8 offset:13344
	s_waitcnt lgkmcnt(5)
	v_fma_f32 v230, -v192, v124, v230
	v_fma_f32 v231, -v193, v125, v231
	v_fma_f32 v230, -v194, v126, v230
	v_fma_f32 v231, -v195, v127, v231
	ds_read_b128 v[192:195], v8 offset:13360
	s_waitcnt lgkmcnt(5)
	v_fma_f32 v230, -v196, v128, v230
	v_fma_f32 v231, -v197, v129, v231
	v_fma_f32 v230, -v198, v130, v230
	v_fma_f32 v231, -v199, v131, v231
	ds_read_b128 v[196:199], v8 offset:13376
	s_waitcnt lgkmcnt(5)
	v_fma_f32 v230, -v200, v132, v230
	v_fma_f32 v231, -v201, v133, v231
	v_fma_f32 v230, -v202, v134, v230
	ds_read_b128 v[200:203], v8 offset:13392
	v_add_f32_e32 v135, v230, v231
	s_cbranch_vccz .Ls4_u51
	v_cvt_pk_bf16_f32 v233, -v135, v135
	global_store_short v6, v233, s[8:9] offset:768
	s_branch .Ls4_n51
.Ls4_u51:
	global_store_dword v234, v135, s[8:9] offset:1536
.Ls4_n51:
	v_mul_f32_e32 v224, s16, v224
	v_mul_f32_e32 v225, s16, v225
	v_mul_f32_e32 v226, s16, v226
	v_mul_f32_e32 v227, s16, v227
	v_exp_f32_e32 v224, v224
	v_exp_f32_e32 v225, v225
	v_exp_f32_e32 v226, v226
	v_exp_f32_e32 v227, v227
	s_nop 0
	v_lshlrev_b32_e32 v228, 16, v228
	v_mul_f32_e32 v232, v228, v220
	v_mul_f32_e32 v230, v232, v224
	v_mov_b32_e32 v231, 0
	ds_read_u16 v229, v7 offset:14416
	s_waitcnt lgkmcnt(6)
	v_fma_f32 v230, -v204, v84, v230
	v_fma_f32 v231, -v205, v85, v231
	v_fma_f32 v230, -v206, v86, v230
	v_fma_f32 v231, -v207, v87, v231
	ds_read_b128 v[204:207], v8 offset:13408
	s_waitcnt lgkmcnt(6)
	v_fma_f32 v230, -v208, v88, v230
	v_fma_f32 v231, -v209, v89, v231
	v_fma_f32 v230, -v210, v90, v230
	v_fma_f32 v231, -v211, v91, v231
	ds_read_b128 v[208:211], v8 offset:13424
	s_waitcnt lgkmcnt(6)
	v_fma_f32 v230, -v212, v92, v230
	v_fma_f32 v231, -v213, v93, v231
	v_fma_f32 v230, -v214, v94, v230
	v_fma_f32 v231, -v215, v95, v231
	ds_read_b128 v[212:215], v8 offset:13440
	s_waitcnt lgkmcnt(6)
	v_fma_f32 v230, -v192, v96, v230
	v_fma_f32 v231, -v193, v97, v231
	v_fma_f32 v230, -v194, v98, v230
	v_fma_f32 v231, -v195, v99, v231
	ds_read_b128 v[192:195], v8 offset:13456
	s_waitcnt lgkmcnt(6)
	v_fma_f32 v230, -v196, v100, v230
	v_fma_f32 v231, -v197, v101, v231
	v_fma_f32 v230, -v198, v102, v230
	v_fma_f32 v231, -v199, v103, v231
	ds_read_b128 v[196:199], v8 offset:13472
	s_waitcnt lgkmcnt(6)
	v_fma_f32 v230, -v200, v104, v230
	v_fma_f32 v231, -v201, v105, v231
	v_fma_f32 v230, -v202, v106, v230
	v_fma_f32 v231, -v203, v107, v231
	ds_read_b128 v[200:203], v8 offset:13488
	s_waitcnt lgkmcnt(5)
	v_fma_f32 v230, -v204, v108, v230
	v_fma_f32 v231, -v205, v109, v231
	v_fma_f32 v230, -v206, v110, v230
	v_fma_f32 v231, -v207, v111, v231
	ds_read_b128 v[204:207], v8 offset:13504
	s_waitcnt lgkmcnt(5)
	v_fma_f32 v230, -v208, v112, v230
	v_fma_f32 v231, -v209, v113, v231
	v_fma_f32 v230, -v210, v114, v230
	v_fma_f32 v231, -v211, v115, v231
	ds_read_b128 v[208:211], v8 offset:13568
	s_waitcnt lgkmcnt(5)
	v_fma_f32 v230, -v212, v116, v230
	v_fma_f32 v231, -v213, v117, v231
	v_fma_f32 v230, -v214, v118, v230
	v_fma_f32 v231, -v215, v119, v231
	ds_read_b128 v[212:215], v8 offset:13584
	s_waitcnt lgkmcnt(5)
	v_fma_f32 v230, -v192, v120, v230
	v_fma_f32 v231, -v193, v121, v231
	v_fma_f32 v230, -v194, v122, v230
	v_fma_f32 v231, -v195, v123, v231
	ds_read_b128 v[192:195], v8 offset:13600
	s_waitcnt lgkmcnt(5)
	v_fma_f32 v230, -v196, v124, v230
	v_fma_f32 v231, -v197, v125, v231
	v_fma_f32 v230, -v198, v126, v230
	v_fma_f32 v231, -v199, v127, v231
	ds_read_b128 v[196:199], v8 offset:13616
	s_waitcnt lgkmcnt(5)
	v_fma_f32 v230, -v200, v128, v230
	v_fma_f32 v231, -v201, v129, v231
	v_fma_f32 v230, -v202, v130, v230
	v_fma_f32 v231, -v203, v131, v231
	ds_read_b128 v[200:203], v8 offset:13632
	s_waitcnt lgkmcnt(5)
	v_fma_f32 v230, -v204, v132, v230
	v_fma_f32 v231, -v205, v133, v231
	v_fma_f32 v230, -v206, v134, v230
	v_fma_f32 v231, -v207, v135, v231
	ds_read_b128 v[204:207], v8 offset:13648
	v_add_f32_e32 v136, v230, v231
	s_cbranch_vccz .Ls4_u52
	v_cvt_pk_bf16_f32 v233, -v136, v136
	global_store_short v6, v233, s[8:9] offset:1024
	s_branch .Ls4_n52
; __device__ __forceinline__ void chunk_prep_phase(const Params& p, int bid, int nblk, LAS unsigned char* lds0) {
;     ...
;             { const float br = betg[53]; ab0 = (f32x2){bf2f(*(const LAS bf16_t*)(lg + P5_VS + 14416 + c * 2)) * br, bf2f(*(const LAS bf16_t*)(lg + P5_KS + 14416 + c * 2)) * br * __expf(decg[53])}; ab1 = (f32x2){0.f, 0.f}; } ab0 -= mq[4][0] * xy[0]; ab1 -= mq[4][1] * xy[1]; ab0 -= mq[4][2] * xy[2]; ab1 -= mq[4][3] * xy[3]; mq[4] = *(const LAS f32x4*)(Mg + 3416);
;             ab0 -= mq[5][0] * xy[4]; ab1 -= mq[5][1] * xy[5]; ab0 -= mq[5][2] * xy[6]; ab1 -= mq[5][3] * xy[7]; mq[5] = *(const LAS f32x4*)(Mg + 3420);
;             ab0 -= mq[0][0] * xy[8]; ab1 -= mq[0][1] * xy[9]; ab0 -= mq[0][2] * xy[10]; ab1 -= mq[0][3] * xy[11]; mq[0] = *(const LAS f32x4*)(Mg + 3424);
;             ab0 -= mq[1][0] * xy[12]; ab1 -= mq[1][1] * xy[13]; ab0 -= mq[1][2] * xy[14]; ab1 -= mq[1][3] * xy[15]; mq[1] = *(const LAS f32x4*)(Mg + 3428);
;             ab0 -= mq[2][0] * xy[16]; ab1 -= mq[2][1] * xy[17]; ab0 -= mq[2][2] * xy[18]; ab1 -= mq[2][3] * xy[19]; mq[2] = *(const LAS f32x4*)(Mg + 3432);
;             ab0 -= mq[3][0] * xy[20]; ab1 -= mq[3][1] * xy[21]; ab0 -= mq[3][2] * xy[22]; ab1 -= mq[3][3] * xy[23]; mq[3] = *(const LAS f32x4*)(Mg + 3436);
;             ab0 -= mq[4][0] * xy[24]; ab1 -= mq[4][1] * xy[25]; ab0 -= mq[4][2] * xy[26]; ab1 -= mq[4][3] * xy[27]; mq[4] = *(const LAS f32x4*)(Mg + 3440);
;             ab0 -= mq[5][0] * xy[28]; ab1 -= mq[5][1] * xy[29]; ab0 -= mq[5][2] * xy[30]; ab1 -= mq[5][3] * xy[31]; mq[5] = *(const LAS f32x4*)(Mg + 3444);
;             ab0 -= mq[0][0] * xy[32]; ab1 -= mq[0][1] * xy[33]; ab0 -= mq[0][2] * xy[34]; ab1 -= mq[0][3] * xy[35]; mq[0] = *(const LAS f32x4*)(Mg + 3456);
;             ab0 -= mq[1][0] * xy[36]; ab1 -= mq[1][1] * xy[37]; ab0 -= mq[1][2] * xy[38]; ab1 -= mq[1][3] * xy[39]; mq[1] = *(const LAS f32x4*)(Mg + 3460);
;             ab0 -= mq[2][0] * xy[40]; ab1 -= mq[2][1] * xy[41]; ab0 -= mq[2][2] * xy[42]; ab1 -= mq[2][3] * xy[43]; mq[2] = *(const LAS f32x4*)(Mg + 3464);
;             ab0 -= mq[3][0] * xy[44]; ab1 -= mq[3][1] * xy[45]; ab0 -= mq[3][2] * xy[46]; ab1 -= mq[3][3] * xy[47]; mq[3] = *(const LAS f32x4*)(Mg + 3468);
;             ab0 -= mq[4][0] * xy[48]; ab1 -= mq[4][1] * xy[49]; ab0 -= mq[4][2] * xy[50]; ab1 -= mq[4][3] * xy[51]; mq[4] = *(const LAS f32x4*)(Mg + 3472);
.Ls4_u52:
	global_store_dword v234, v136, s[8:9] offset:2048
.Ls4_n52:
	v_lshlrev_b32_e32 v229, 16, v229
	v_mul_f32_e32 v232, v229, v221
	v_mul_f32_e32 v230, v232, v225
	v_mov_b32_e32 v231, 0
	ds_read_u16 v228, v7 offset:14688
	s_waitcnt lgkmcnt(6)
	v_fma_f32 v230, -v208, v84, v230
	v_fma_f32 v231, -v209, v85, v231
	v_fma_f32 v230, -v210, v86, v230
	v_fma_f32 v231, -v211, v87, v231
	ds_read_b128 v[208:211], v8 offset:13664
	s_waitcnt lgkmcnt(6)
	v_fma_f32 v230, -v212, v88, v230
	v_fma_f32 v231, -v213, v89, v231
	v_fma_f32 v230, -v214, v90, v230
	v_fma_f32 v231, -v215, v91, v231
	ds_read_b128 v[212:215], v8 offset:13680
	s_waitcnt lgkmcnt(6)
	v_fma_f32 v230, -v192, v92, v230
	v_fma_f32 v231, -v193, v93, v231
	v_fma_f32 v230, -v194, v94, v230
	v_fma_f32 v231, -v195, v95, v231
	ds_read_b128 v[192:195], v8 offset:13696
	s_waitcnt lgkmcnt(6)
	v_fma_f32 v230, -v196, v96, v230
	v_fma_f32 v231, -v197, v97, v231
	v_fma_f32 v230, -v198, v98, v230
	v_fma_f32 v231, -v199, v99, v231
	ds_read_b128 v[196:199], v8 offset:13712
	s_waitcnt lgkmcnt(6)
	v_fma_f32 v230, -v200, v100, v230
	v_fma_f32 v231, -v201, v101, v231
	v_fma_f32 v230, -v202, v102, v230
	v_fma_f32 v231, -v203, v103, v231
	ds_read_b128 v[200:203], v8 offset:13728
	s_waitcnt lgkmcnt(6)
	v_fma_f32 v230, -v204, v104, v230
	v_fma_f32 v231, -v205, v105, v231
	v_fma_f32 v230, -v206, v106, v230
	v_fma_f32 v231, -v207, v107, v231
	ds_read_b128 v[204:207], v8 offset:13744
	s_waitcnt lgkmcnt(5)
	v_fma_f32 v230, -v208, v108, v230
	v_fma_f32 v231, -v209, v109, v231
	v_fma_f32 v230, -v210, v110, v230
	v_fma_f32 v231, -v211, v111, v231
	ds_read_b128 v[208:211], v8 offset:13760
	s_waitcnt lgkmcnt(5)
	v_fma_f32 v230, -v212, v112, v230
	v_fma_f32 v231, -v213, v113, v231
	v_fma_f32 v230, -v214, v114, v230
	v_fma_f32 v231, -v215, v115, v231
	ds_read_b128 v[212:215], v8 offset:13776
	s_waitcnt lgkmcnt(5)
	v_fma_f32 v230, -v192, v116, v230
	v_fma_f32 v231, -v193, v117, v231
	v_fma_f32 v230, -v194, v118, v230
	v_fma_f32 v231, -v195, v119, v231
	ds_read_b128 v[192:195], v8 offset:13824
	s_waitcnt lgkmcnt(5)
	v_fma_f32 v230, -v196, v120, v230
	v_fma_f32 v231, -v197, v121, v231
	v_fma_f32 v230, -v198, v122, v230
	v_fma_f32 v231, -v199, v123, v231
	ds_read_b128 v[196:199], v8 offset:13840
	s_waitcnt lgkmcnt(5)
	v_fma_f32 v230, -v200, v124, v230
	v_fma_f32 v231, -v201, v125, v231
	v_fma_f32 v230, -v202, v126, v230
	v_fma_f32 v231, -v203, v127, v231
	ds_read_b128 v[200:203], v8 offset:13856
	s_waitcnt lgkmcnt(5)
	v_fma_f32 v230, -v204, v128, v230
	v_fma_f32 v231, -v205, v129, v231
	v_fma_f32 v230, -v206, v130, v230
	v_fma_f32 v231, -v207, v131, v231
	ds_read_b128 v[204:207], v8 offset:13872
	s_waitcnt lgkmcnt(5)
	v_fma_f32 v230, -v208, v132, v230
	v_fma_f32 v231, -v209, v133, v231
	v_fma_f32 v230, -v210, v134, v230
	v_fma_f32 v231, -v211, v135, v231
	ds_read_b128 v[208:211], v8 offset:13888
	s_waitcnt lgkmcnt(5)
	v_fma_f32 v230, -v212, v136, v230
	ds_read_b128 v[212:215], v8 offset:13904
	v_add_f32_e32 v137, v230, v231
	s_cbranch_vccz .Ls4_u53
	v_cvt_pk_bf16_f32 v233, -v137, v137
	global_store_short v6, v233, s[8:9] offset:1280
	s_branch .Ls4_n53
.Ls4_u53:
	global_store_dword v234, v137, s[8:9] offset:2560
.Ls4_n53:
	v_lshlrev_b32_e32 v228, 16, v228
	v_mul_f32_e32 v232, v228, v222
	v_mul_f32_e32 v230, v232, v226
	v_mov_b32_e32 v231, 0
	ds_read_u16 v229, v7 offset:14960
	s_waitcnt lgkmcnt(6)
	v_fma_f32 v230, -v192, v84, v230
	v_fma_f32 v231, -v193, v85, v231
	v_fma_f32 v230, -v194, v86, v230
	v_fma_f32 v231, -v195, v87, v231
	ds_read_b128 v[192:195], v8 offset:13920
	s_waitcnt lgkmcnt(6)
	v_fma_f32 v230, -v196, v88, v230
	v_fma_f32 v231, -v197, v89, v231
	v_fma_f32 v230, -v198, v90, v230
	v_fma_f32 v231, -v199, v91, v231
	ds_read_b128 v[196:199], v8 offset:13936
	s_waitcnt lgkmcnt(6)
	v_fma_f32 v230, -v200, v92, v230
	v_fma_f32 v231, -v201, v93, v231
	v_fma_f32 v230, -v202, v94, v230
	v_fma_f32 v231, -v203, v95, v231
	ds_read_b128 v[200:203], v8 offset:13952
	s_waitcnt lgkmcnt(6)
	v_fma_f32 v230, -v204, v96, v230
	v_fma_f32 v231, -v205, v97, v231
	v_fma_f32 v230, -v206, v98, v230
	v_fma_f32 v231, -v207, v99, v231
	ds_read_b128 v[204:207], v8 offset:13968
	s_waitcnt lgkmcnt(6)
	v_fma_f32 v230, -v208, v100, v230
	v_fma_f32 v231, -v209, v101, v231
	v_fma_f32 v230, -v210, v102, v230
	v_fma_f32 v231, -v211, v103, v231
	ds_read_b128 v[208:211], v8 offset:13984
	s_waitcnt lgkmcnt(6)
	v_fma_f32 v230, -v212, v104, v230
	v_fma_f32 v231, -v213, v105, v231
	v_fma_f32 v230, -v214, v106, v230
	v_fma_f32 v231, -v215, v107, v231
	ds_read_b128 v[212:215], v8 offset:14000
	s_waitcnt lgkmcnt(5)
	v_fma_f32 v230, -v192, v108, v230
	v_fma_f32 v231, -v193, v109, v231
	v_fma_f32 v230, -v194, v110, v230
	v_fma_f32 v231, -v195, v111, v231
	ds_read_b128 v[192:195], v8 offset:14016
	s_waitcnt lgkmcnt(5)
	v_fma_f32 v230, -v196, v112, v230
	v_fma_f32 v231, -v197, v113, v231
	v_fma_f32 v230, -v198, v114, v230
	v_fma_f32 v231, -v199, v115, v231
	ds_read_b128 v[196:199], v8 offset:14032
	s_waitcnt lgkmcnt(5)
	v_fma_f32 v230, -v200, v116, v230
	v_fma_f32 v231, -v201, v117, v231
	v_fma_f32 v230, -v202, v118, v230
	v_fma_f32 v231, -v203, v119, v231
	ds_read_b128 v[200:203], v8 offset:14080
	s_waitcnt lgkmcnt(5)
	v_fma_f32 v230, -v204, v120, v230
	v_fma_f32 v231, -v205, v121, v231
	v_fma_f32 v230, -v206, v122, v230
	v_fma_f32 v231, -v207, v123, v231
	ds_read_b128 v[204:207], v8 offset:14096
	s_waitcnt lgkmcnt(5)
	v_fma_f32 v230, -v208, v124, v230
	v_fma_f32 v231, -v209, v125, v231
	v_fma_f32 v230, -v210, v126, v230
	v_fma_f32 v231, -v211, v127, v231
	ds_read_b128 v[208:211], v8 offset:14112
	s_waitcnt lgkmcnt(5)
	v_fma_f32 v230, -v212, v128, v230
	v_fma_f32 v231, -v213, v129, v231
	v_fma_f32 v230, -v214, v130, v230
	v_fma_f32 v231, -v215, v131, v231
	ds_read_b128 v[212:215], v8 offset:14128
	s_waitcnt lgkmcnt(5)
	v_fma_f32 v230, -v192, v132, v230
	v_fma_f32 v231, -v193, v133, v231
	v_fma_f32 v230, -v194, v134, v230
	v_fma_f32 v231, -v195, v135, v231
	ds_read_b128 v[192:195], v8 offset:14144
	s_waitcnt lgkmcnt(5)
	v_fma_f32 v230, -v196, v136, v230
	v_fma_f32 v231, -v197, v137, v231
	ds_read_b128 v[196:199], v8 offset:14160
	v_add_f32_e32 v138, v230, v231
	s_cbranch_vccz .Ls4_u54
	v_cvt_pk_bf16_f32 v233, -v138, v138
	global_store_short v6, v233, s[8:9] offset:1536
	s_branch .Ls4_n54
; __device__ __forceinline__ void chunk_prep_phase(const Params& p, int bid, int nblk, LAS unsigned char* lds0) {
;     ...
;             { const float br = betg[55]; ab0 = (f32x2){bf2f(*(const LAS bf16_t*)(lg + P5_VS + 14960 + c * 2)) * br, bf2f(*(const LAS bf16_t*)(lg + P5_KS + 14960 + c * 2)) * br * __expf(decg[55])}; ab1 = (f32x2){0.f, 0.f}; } ab0 -= mq[2][0] * xy[0]; ab1 -= mq[2][1] * xy[1]; ab0 -= mq[2][2] * xy[2]; ab1 -= mq[2][3] * xy[3]; mq[2] = *(const LAS f32x4*)(Mg + 3544);
;             ab0 -= mq[3][0] * xy[4]; ab1 -= mq[3][1] * xy[5]; ab0 -= mq[3][2] * xy[6]; ab1 -= mq[3][3] * xy[7]; mq[3] = *(const LAS f32x4*)(Mg + 3548);
;             ab0 -= mq[4][0] * xy[8]; ab1 -= mq[4][1] * xy[9]; ab0 -= mq[4][2] * xy[10]; ab1 -= mq[4][3] * xy[11]; mq[4] = *(const LAS f32x4*)(Mg + 3552);
;             ab0 -= mq[5][0] * xy[12]; ab1 -= mq[5][1] * xy[13]; ab0 -= mq[5][2] * xy[14]; ab1 -= mq[5][3] * xy[15]; mq[5] = *(const LAS f32x4*)(Mg + 3556);
;             ab0 -= mq[0][0] * xy[16]; ab1 -= mq[0][1] * xy[17]; ab0 -= mq[0][2] * xy[18]; ab1 -= mq[0][3] * xy[19]; mq[0] = *(const LAS f32x4*)(Mg + 3560);
;             ab0 -= mq[1][0] * xy[20]; ab1 -= mq[1][1] * xy[21]; ab0 -= mq[1][2] * xy[22]; ab1 -= mq[1][3] * xy[23]; mq[1] = *(const LAS f32x4*)(Mg + 3564);
;             ab0 -= mq[2][0] * xy[24]; ab1 -= mq[2][1] * xy[25]; ab0 -= mq[2][2] * xy[26]; ab1 -= mq[2][3] * xy[27]; mq[2] = *(const LAS f32x4*)(Mg + 3568);
;             ab0 -= mq[3][0] * xy[28]; ab1 -= mq[3][1] * xy[29]; ab0 -= mq[3][2] * xy[30]; ab1 -= mq[3][3] * xy[31]; mq[3] = *(const LAS f32x4*)(Mg + 3572);
;             ab0 -= mq[4][0] * xy[32]; ab1 -= mq[4][1] * xy[33]; ab0 -= mq[4][2] * xy[34]; ab1 -= mq[4][3] * xy[35]; mq[4] = *(const LAS f32x4*)(Mg + 3584);
;             ab0 -= mq[5][0] * xy[36]; ab1 -= mq[5][1] * xy[37]; ab0 -= mq[5][2] * xy[38]; ab1 -= mq[5][3] * xy[39]; mq[5] = *(const LAS f32x4*)(Mg + 3588);
;             ab0 -= mq[0][0] * xy[40]; ab1 -= mq[0][1] * xy[41]; ab0 -= mq[0][2] * xy[42]; ab1 -= mq[0][3] * xy[43]; mq[0] = *(const LAS f32x4*)(Mg + 3592);
;             ab0 -= mq[1][0] * xy[44]; ab1 -= mq[1][1] * xy[45]; ab0 -= mq[1][2] * xy[46]; ab1 -= mq[1][3] * xy[47]; mq[1] = *(const LAS f32x4*)(Mg + 3596);
;             ab0 -= mq[2][0] * xy[48]; ab1 -= mq[2][1] * xy[49]; ab0 -= mq[2][2] * xy[50]; ab1 -= mq[2][3] * xy[51]; mq[2] = *(const LAS f32x4*)(Mg + 3600);
.Ls4_u54:
	global_store_dword v234, v138, s[8:9] offset:3072
.Ls4_n54:
	v_lshlrev_b32_e32 v229, 16, v229
	v_mul_f32_e32 v232, v229, v223
	v_mul_f32_e32 v230, v232, v227
	v_mov_b32_e32 v231, 0
	ds_read_u16 v228, v7 offset:15232
	ds_read_b128 v[220:223], v8 offset:16880
	ds_read_b128 v[224:227], v8 offset:16624
	s_waitcnt lgkmcnt(8)
	v_fma_f32 v230, -v200, v84, v230
	v_fma_f32 v231, -v201, v85, v231
	v_fma_f32 v230, -v202, v86, v230
	v_fma_f32 v231, -v203, v87, v231
	ds_read_b128 v[200:203], v8 offset:14176
	s_waitcnt lgkmcnt(8)
	v_fma_f32 v230, -v204, v88, v230
	v_fma_f32 v231, -v205, v89, v231
	v_fma_f32 v230, -v206, v90, v230
	v_fma_f32 v231, -v207, v91, v231
	ds_read_b128 v[204:207], v8 offset:14192
	s_waitcnt lgkmcnt(8)
	v_fma_f32 v230, -v208, v92, v230
	v_fma_f32 v231, -v209, v93, v231
	v_fma_f32 v230, -v210, v94, v230
	v_fma_f32 v231, -v211, v95, v231
	ds_read_b128 v[208:211], v8 offset:14208
	s_waitcnt lgkmcnt(8)
	v_fma_f32 v230, -v212, v96, v230
	v_fma_f32 v231, -v213, v97, v231
	v_fma_f32 v230, -v214, v98, v230
	v_fma_f32 v231, -v215, v99, v231
	ds_read_b128 v[212:215], v8 offset:14224
	s_waitcnt lgkmcnt(8)
	v_fma_f32 v230, -v192, v100, v230
	v_fma_f32 v231, -v193, v101, v231
	v_fma_f32 v230, -v194, v102, v230
	v_fma_f32 v231, -v195, v103, v231
	ds_read_b128 v[192:195], v8 offset:14240
	s_waitcnt lgkmcnt(8)
	v_fma_f32 v230, -v196, v104, v230
	v_fma_f32 v231, -v197, v105, v231
	v_fma_f32 v230, -v198, v106, v230
	v_fma_f32 v231, -v199, v107, v231
	ds_read_b128 v[196:199], v8 offset:14256
	s_waitcnt lgkmcnt(5)
	v_fma_f32 v230, -v200, v108, v230
	v_fma_f32 v231, -v201, v109, v231
	v_fma_f32 v230, -v202, v110, v230
	v_fma_f32 v231, -v203, v111, v231
	ds_read_b128 v[200:203], v8 offset:14272
	s_waitcnt lgkmcnt(5)
	v_fma_f32 v230, -v204, v112, v230
	v_fma_f32 v231, -v205, v113, v231
	v_fma_f32 v230, -v206, v114, v230
	v_fma_f32 v231, -v207, v115, v231
	ds_read_b128 v[204:207], v8 offset:14288
	s_waitcnt lgkmcnt(5)
	v_fma_f32 v230, -v208, v116, v230
	v_fma_f32 v231, -v209, v117, v231
	v_fma_f32 v230, -v210, v118, v230
	v_fma_f32 v231, -v211, v119, v231
	ds_read_b128 v[208:211], v8 offset:14336
	s_waitcnt lgkmcnt(5)
	v_fma_f32 v230, -v212, v120, v230
	v_fma_f32 v231, -v213, v121, v231
	v_fma_f32 v230, -v214, v122, v230
	v_fma_f32 v231, -v215, v123, v231
	ds_read_b128 v[212:215], v8 offset:14352
	s_waitcnt lgkmcnt(5)
	v_fma_f32 v230, -v192, v124, v230
	v_fma_f32 v231, -v193, v125, v231
	v_fma_f32 v230, -v194, v126, v230
	v_fma_f32 v231, -v195, v127, v231
	ds_read_b128 v[192:195], v8 offset:14368
	s_waitcnt lgkmcnt(5)
	v_fma_f32 v230, -v196, v128, v230
	v_fma_f32 v231, -v197, v129, v231
	v_fma_f32 v230, -v198, v130, v230
	v_fma_f32 v231, -v199, v131, v231
	ds_read_b128 v[196:199], v8 offset:14384
	s_waitcnt lgkmcnt(5)
	v_fma_f32 v230, -v200, v132, v230
	v_fma_f32 v231, -v201, v133, v231
	v_fma_f32 v230, -v202, v134, v230
	v_fma_f32 v231, -v203, v135, v231
	ds_read_b128 v[200:203], v8 offset:14400
	s_waitcnt lgkmcnt(5)
	v_fma_f32 v230, -v204, v136, v230
	v_fma_f32 v231, -v205, v137, v231
	v_fma_f32 v230, -v206, v138, v230
	ds_read_b128 v[204:207], v8 offset:14416
	v_add_f32_e32 v139, v230, v231
	s_cbranch_vccz .Ls4_u55
	v_cvt_pk_bf16_f32 v233, -v139, v139
	global_store_short v6, v233, s[8:9] offset:1792
	s_branch .Ls4_n55
.Ls4_u55:
	global_store_dword v234, v139, s[8:9] offset:3584
.Ls4_n55:
	v_mul_f32_e32 v0, s16, v0
	v_mul_f32_e32 v1, s16, v1
	v_mul_f32_e32 v2, s16, v2
	v_mul_f32_e32 v3, s16, v3
	v_exp_f32_e32 v0, v0
	v_exp_f32_e32 v1, v1
	v_exp_f32_e32 v2, v2
	v_exp_f32_e32 v3, v3
	s_nop 0
	v_lshlrev_b32_e32 v228, 16, v228
	v_mul_f32_e32 v232, v228, v216
	v_mul_f32_e32 v230, v232, v0
	v_mov_b32_e32 v231, 0
	ds_read_u16 v229, v7 offset:15504
	s_waitcnt lgkmcnt(6)
	v_fma_f32 v230, -v208, v84, v230
	v_fma_f32 v231, -v209, v85, v231
	v_fma_f32 v230, -v210, v86, v230
	v_fma_f32 v231, -v211, v87, v231
	ds_read_b128 v[208:211], v8 offset:14432
	s_waitcnt lgkmcnt(6)
	v_fma_f32 v230, -v212, v88, v230
	v_fma_f32 v231, -v213, v89, v231
	v_fma_f32 v230, -v214, v90, v230
	v_fma_f32 v231, -v215, v91, v231
	ds_read_b128 v[212:215], v8 offset:14448
	s_waitcnt lgkmcnt(6)
	v_fma_f32 v230, -v192, v92, v230
	v_fma_f32 v231, -v193, v93, v231
	v_fma_f32 v230, -v194, v94, v230
	v_fma_f32 v231, -v195, v95, v231
	ds_read_b128 v[192:195], v8 offset:14464
	s_waitcnt lgkmcnt(6)
	v_fma_f32 v230, -v196, v96, v230
	v_fma_f32 v231, -v197, v97, v231
	v_fma_f32 v230, -v198, v98, v230
	v_fma_f32 v231, -v199, v99, v231
	ds_read_b128 v[196:199], v8 offset:14480
	s_waitcnt lgkmcnt(6)
	v_fma_f32 v230, -v200, v100, v230
	v_fma_f32 v231, -v201, v101, v231
	v_fma_f32 v230, -v202, v102, v230
	v_fma_f32 v231, -v203, v103, v231
	ds_read_b128 v[200:203], v8 offset:14496
	s_waitcnt lgkmcnt(6)
	v_fma_f32 v230, -v204, v104, v230
	v_fma_f32 v231, -v205, v105, v231
	v_fma_f32 v230, -v206, v106, v230
	v_fma_f32 v231, -v207, v107, v231
	ds_read_b128 v[204:207], v8 offset:14512
	s_waitcnt lgkmcnt(5)
	v_fma_f32 v230, -v208, v108, v230
	v_fma_f32 v231, -v209, v109, v231
	v_fma_f32 v230, -v210, v110, v230
	v_fma_f32 v231, -v211, v111, v231
	ds_read_b128 v[208:211], v8 offset:14528
	s_waitcnt lgkmcnt(5)
	v_fma_f32 v230, -v212, v112, v230
	v_fma_f32 v231, -v213, v113, v231
	v_fma_f32 v230, -v214, v114, v230
	v_fma_f32 v231, -v215, v115, v231
	ds_read_b128 v[212:215], v8 offset:14544
	s_waitcnt lgkmcnt(5)
	v_fma_f32 v230, -v192, v116, v230
	v_fma_f32 v231, -v193, v117, v231
	v_fma_f32 v230, -v194, v118, v230
	v_fma_f32 v231, -v195, v119, v231
	ds_read_b128 v[192:195], v8 offset:14592
	s_waitcnt lgkmcnt(5)
	v_fma_f32 v230, -v196, v120, v230
	v_fma_f32 v231, -v197, v121, v231
	v_fma_f32 v230, -v198, v122, v230
	v_fma_f32 v231, -v199, v123, v231
	ds_read_b128 v[196:199], v8 offset:14608
	s_waitcnt lgkmcnt(5)
	v_fma_f32 v230, -v200, v124, v230
	v_fma_f32 v231, -v201, v125, v231
	v_fma_f32 v230, -v202, v126, v230
	v_fma_f32 v231, -v203, v127, v231
	ds_read_b128 v[200:203], v8 offset:14624
	s_waitcnt lgkmcnt(5)
	v_fma_f32 v230, -v204, v128, v230
	v_fma_f32 v231, -v205, v129, v231
	v_fma_f32 v230, -v206, v130, v230
	v_fma_f32 v231, -v207, v131, v231
	ds_read_b128 v[204:207], v8 offset:14640
	s_waitcnt lgkmcnt(5)
	v_fma_f32 v230, -v208, v132, v230
	v_fma_f32 v231, -v209, v133, v231
	v_fma_f32 v230, -v210, v134, v230
	v_fma_f32 v231, -v211, v135, v231
	ds_read_b128 v[208:211], v8 offset:14656
	s_waitcnt lgkmcnt(5)
	v_fma_f32 v230, -v212, v136, v230
	v_fma_f32 v231, -v213, v137, v231
	v_fma_f32 v230, -v214, v138, v230
	v_fma_f32 v231, -v215, v139, v231
	ds_read_b128 v[212:215], v8 offset:14672
	v_add_f32_e32 v140, v230, v231
	s_cbranch_vccz .Ls4_u56
	v_cvt_pk_bf16_f32 v233, -v140, v140
	global_store_short v6, v233, s[8:9] offset:2048
	s_branch .Ls4_n56
; __device__ __forceinline__ void chunk_prep_phase(const Params& p, int bid, int nblk, LAS unsigned char* lds0) {
;     ...
;             { const float br = betg[57]; ab0 = (f32x2){bf2f(*(const LAS bf16_t*)(lg + P5_VS + 15504 + c * 2)) * br, bf2f(*(const LAS bf16_t*)(lg + P5_KS + 15504 + c * 2)) * br * __expf(decg[57])}; ab1 = (f32x2){0.f, 0.f}; } ab0 -= mq[0][0] * xy[0]; ab1 -= mq[0][1] * xy[1]; ab0 -= mq[0][2] * xy[2]; ab1 -= mq[0][3] * xy[3]; mq[0] = *(const LAS f32x4*)(Mg + 3672);
;             ab0 -= mq[1][0] * xy[4]; ab1 -= mq[1][1] * xy[5]; ab0 -= mq[1][2] * xy[6]; ab1 -= mq[1][3] * xy[7]; mq[1] = *(const LAS f32x4*)(Mg + 3676);
;             ab0 -= mq[2][0] * xy[8]; ab1 -= mq[2][1] * xy[9]; ab0 -= mq[2][2] * xy[10]; ab1 -= mq[2][3] * xy[11]; mq[2] = *(const LAS f32x4*)(Mg + 3680);
;             ab0 -= mq[3][0] * xy[12]; ab1 -= mq[3][1] * xy[13]; ab0 -= mq[3][2] * xy[14]; ab1 -= mq[3][3] * xy[15]; mq[3] = *(const LAS f32x4*)(Mg + 3684);
;             ab0 -= mq[4][0] * xy[16]; ab1 -= mq[4][1] * xy[17]; ab0 -= mq[4][2] * xy[18]; ab1 -= mq[4][3] * xy[19]; mq[4] = *(const LAS f32x4*)(Mg + 3688);
;             ab0 -= mq[5][0] * xy[20]; ab1 -= mq[5][1] * xy[21]; ab0 -= mq[5][2] * xy[22]; ab1 -= mq[5][3] * xy[23]; mq[5] = *(const LAS f32x4*)(Mg + 3692);
;             ab0 -= mq[0][0] * xy[24]; ab1 -= mq[0][1] * xy[25]; ab0 -= mq[0][2] * xy[26]; ab1 -= mq[0][3] * xy[27]; mq[0] = *(const LAS f32x4*)(Mg + 3696);
;             ab0 -= mq[1][0] * xy[28]; ab1 -= mq[1][1] * xy[29]; ab0 -= mq[1][2] * xy[30]; ab1 -= mq[1][3] * xy[31]; mq[1] = *(const LAS f32x4*)(Mg + 3700);
;             ab0 -= mq[2][0] * xy[32]; ab1 -= mq[2][1] * xy[33]; ab0 -= mq[2][2] * xy[34]; ab1 -= mq[2][3] * xy[35]; mq[2] = *(const LAS f32x4*)(Mg + 3704);
;             ab0 -= mq[3][0] * xy[36]; ab1 -= mq[3][1] * xy[37]; ab0 -= mq[3][2] * xy[38]; ab1 -= mq[3][3] * xy[39]; mq[3] = *(const LAS f32x4*)(Mg + 3712);
;             ab0 -= mq[4][0] * xy[40]; ab1 -= mq[4][1] * xy[41]; ab0 -= mq[4][2] * xy[42]; ab1 -= mq[4][3] * xy[43]; mq[4] = *(const LAS f32x4*)(Mg + 3716);
;             ab0 -= mq[5][0] * xy[44]; ab1 -= mq[5][1] * xy[45]; ab0 -= mq[5][2] * xy[46]; ab1 -= mq[5][3] * xy[47]; mq[5] = *(const LAS f32x4*)(Mg + 3720);
;             ab0 -= mq[0][0] * xy[48]; ab1 -= mq[0][1] * xy[49]; ab0 -= mq[0][2] * xy[50]; ab1 -= mq[0][3] * xy[51]; mq[0] = *(const LAS f32x4*)(Mg + 3724);
.Ls4_u56:
	s_add_u32 s8, s8, 0x1000
	s_addc_u32 s9, s9, 0
	global_store_dword v234, v140, s[8:9] offset:0
.Ls4_n56:
	v_lshlrev_b32_e32 v229, 16, v229
	v_mul_f32_e32 v232, v229, v217
	v_mul_f32_e32 v230, v232, v1
	v_mov_b32_e32 v231, 0
	ds_read_u16 v228, v7 offset:15776
	s_waitcnt lgkmcnt(6)
	v_fma_f32 v230, -v192, v84, v230
	v_fma_f32 v231, -v193, v85, v231
	v_fma_f32 v230, -v194, v86, v230
	v_fma_f32 v231, -v195, v87, v231
	ds_read_b128 v[192:195], v8 offset:14688
	s_waitcnt lgkmcnt(6)
	v_fma_f32 v230, -v196, v88, v230
	v_fma_f32 v231, -v197, v89, v231
	v_fma_f32 v230, -v198, v90, v230
	v_fma_f32 v231, -v199, v91, v231
	ds_read_b128 v[196:199], v8 offset:14704
	s_waitcnt lgkmcnt(6)
	v_fma_f32 v230, -v200, v92, v230
	v_fma_f32 v231, -v201, v93, v231
	v_fma_f32 v230, -v202, v94, v230
	v_fma_f32 v231, -v203, v95, v231
	ds_read_b128 v[200:203], v8 offset:14720
	s_waitcnt lgkmcnt(6)
	v_fma_f32 v230, -v204, v96, v230
	v_fma_f32 v231, -v205, v97, v231
	v_fma_f32 v230, -v206, v98, v230
	v_fma_f32 v231, -v207, v99, v231
	ds_read_b128 v[204:207], v8 offset:14736
	s_waitcnt lgkmcnt(6)
	v_fma_f32 v230, -v208, v100, v230
	v_fma_f32 v231, -v209, v101, v231
	v_fma_f32 v230, -v210, v102, v230
	v_fma_f32 v231, -v211, v103, v231
	ds_read_b128 v[208:211], v8 offset:14752
	s_waitcnt lgkmcnt(6)
	v_fma_f32 v230, -v212, v104, v230
	v_fma_f32 v231, -v213, v105, v231
	v_fma_f32 v230, -v214, v106, v230
	v_fma_f32 v231, -v215, v107, v231
	ds_read_b128 v[212:215], v8 offset:14768
	s_waitcnt lgkmcnt(5)
	v_fma_f32 v230, -v192, v108, v230
	v_fma_f32 v231, -v193, v109, v231
	v_fma_f32 v230, -v194, v110, v230
	v_fma_f32 v231, -v195, v111, v231
	ds_read_b128 v[192:195], v8 offset:14784
	s_waitcnt lgkmcnt(5)
	v_fma_f32 v230, -v196, v112, v230
	v_fma_f32 v231, -v197, v113, v231
	v_fma_f32 v230, -v198, v114, v230
	v_fma_f32 v231, -v199, v115, v231
	ds_read_b128 v[196:199], v8 offset:14800
	s_waitcnt lgkmcnt(5)
	v_fma_f32 v230, -v200, v116, v230
	v_fma_f32 v231, -v201, v117, v231
	v_fma_f32 v230, -v202, v118, v230
	v_fma_f32 v231, -v203, v119, v231
	ds_read_b128 v[200:203], v8 offset:14816
	s_waitcnt lgkmcnt(5)
	v_fma_f32 v230, -v204, v120, v230
	v_fma_f32 v231, -v205, v121, v231
	v_fma_f32 v230, -v206, v122, v230
	v_fma_f32 v231, -v207, v123, v231
	ds_read_b128 v[204:207], v8 offset:14848
	s_waitcnt lgkmcnt(5)
	v_fma_f32 v230, -v208, v124, v230
	v_fma_f32 v231, -v209, v125, v231
	v_fma_f32 v230, -v210, v126, v230
	v_fma_f32 v231, -v211, v127, v231
	ds_read_b128 v[208:211], v8 offset:14864
	s_waitcnt lgkmcnt(5)
	v_fma_f32 v230, -v212, v128, v230
	v_fma_f32 v231, -v213, v129, v231
	v_fma_f32 v230, -v214, v130, v230
	v_fma_f32 v231, -v215, v131, v231
	ds_read_b128 v[212:215], v8 offset:14880
	s_waitcnt lgkmcnt(5)
	v_fma_f32 v230, -v192, v132, v230
	v_fma_f32 v231, -v193, v133, v231
	v_fma_f32 v230, -v194, v134, v230
	v_fma_f32 v231, -v195, v135, v231
	ds_read_b128 v[192:195], v8 offset:14896
	s_waitcnt lgkmcnt(5)
	v_fma_f32 v230, -v196, v136, v230
	v_fma_f32 v231, -v197, v137, v231
	v_fma_f32 v230, -v198, v138, v230
	v_fma_f32 v231, -v199, v139, v231
	ds_read_b128 v[196:199], v8 offset:14912
	s_waitcnt lgkmcnt(5)
	v_fma_f32 v230, -v200, v140, v230
	ds_read_b128 v[200:203], v8 offset:14928
	v_add_f32_e32 v141, v230, v231
	s_cbranch_vccz .Ls4_u57
	v_cvt_pk_bf16_f32 v233, -v141, v141
	global_store_short v6, v233, s[8:9] offset:2304
	s_branch .Ls4_n57
.Ls4_u57:
	global_store_dword v234, v141, s[8:9] offset:512
.Ls4_n57:
	v_lshlrev_b32_e32 v228, 16, v228
	v_mul_f32_e32 v232, v228, v218
	v_mul_f32_e32 v230, v232, v2
	v_mov_b32_e32 v231, 0
	ds_read_u16 v229, v7 offset:16048
	s_waitcnt lgkmcnt(6)
	v_fma_f32 v230, -v204, v84, v230
	v_fma_f32 v231, -v205, v85, v231
	v_fma_f32 v230, -v206, v86, v230
	v_fma_f32 v231, -v207, v87, v231
	ds_read_b128 v[204:207], v8 offset:14944
	s_waitcnt lgkmcnt(6)
	v_fma_f32 v230, -v208, v88, v230
	v_fma_f32 v231, -v209, v89, v231
	v_fma_f32 v230, -v210, v90, v230
	v_fma_f32 v231, -v211, v91, v231
	ds_read_b128 v[208:211], v8 offset:14960
	s_waitcnt lgkmcnt(6)
	v_fma_f32 v230, -v212, v92, v230
	v_fma_f32 v231, -v213, v93, v231
	v_fma_f32 v230, -v214, v94, v230
	v_fma_f32 v231, -v215, v95, v231
	ds_read_b128 v[212:215], v8 offset:14976
	s_waitcnt lgkmcnt(6)
	v_fma_f32 v230, -v192, v96, v230
	v_fma_f32 v231, -v193, v97, v231
	v_fma_f32 v230, -v194, v98, v230
	v_fma_f32 v231, -v195, v99, v231
	ds_read_b128 v[192:195], v8 offset:14992
	s_waitcnt lgkmcnt(6)
	v_fma_f32 v230, -v196, v100, v230
	v_fma_f32 v231, -v197, v101, v231
	v_fma_f32 v230, -v198, v102, v230
	v_fma_f32 v231, -v199, v103, v231
	ds_read_b128 v[196:199], v8 offset:15008
	s_waitcnt lgkmcnt(6)
	v_fma_f32 v230, -v200, v104, v230
	v_fma_f32 v231, -v201, v105, v231
	v_fma_f32 v230, -v202, v106, v230
	v_fma_f32 v231, -v203, v107, v231
	ds_read_b128 v[200:203], v8 offset:15024
	s_waitcnt lgkmcnt(5)
	v_fma_f32 v230, -v204, v108, v230
	v_fma_f32 v231, -v205, v109, v231
	v_fma_f32 v230, -v206, v110, v230
	v_fma_f32 v231, -v207, v111, v231
	ds_read_b128 v[204:207], v8 offset:15040
	s_waitcnt lgkmcnt(5)
	v_fma_f32 v230, -v208, v112, v230
	v_fma_f32 v231, -v209, v113, v231
	v_fma_f32 v230, -v210, v114, v230
	v_fma_f32 v231, -v211, v115, v231
	ds_read_b128 v[208:211], v8 offset:15056
	s_waitcnt lgkmcnt(5)
	v_fma_f32 v230, -v212, v116, v230
	v_fma_f32 v231, -v213, v117, v231
	v_fma_f32 v230, -v214, v118, v230
	v_fma_f32 v231, -v215, v119, v231
	ds_read_b128 v[212:215], v8 offset:15072
	s_waitcnt lgkmcnt(5)
	v_fma_f32 v230, -v192, v120, v230
	v_fma_f32 v231, -v193, v121, v231
	v_fma_f32 v230, -v194, v122, v230
	v_fma_f32 v231, -v195, v123, v231
	ds_read_b128 v[192:195], v8 offset:15104
	s_waitcnt lgkmcnt(5)
	v_fma_f32 v230, -v196, v124, v230
	v_fma_f32 v231, -v197, v125, v231
	v_fma_f32 v230, -v198, v126, v230
	v_fma_f32 v231, -v199, v127, v231
	ds_read_b128 v[196:199], v8 offset:15120
	s_waitcnt lgkmcnt(5)
	v_fma_f32 v230, -v200, v128, v230
	v_fma_f32 v231, -v201, v129, v231
	v_fma_f32 v230, -v202, v130, v230
	v_fma_f32 v231, -v203, v131, v231
	ds_read_b128 v[200:203], v8 offset:15136
	s_waitcnt lgkmcnt(5)
	v_fma_f32 v230, -v204, v132, v230
	v_fma_f32 v231, -v205, v133, v231
	v_fma_f32 v230, -v206, v134, v230
	v_fma_f32 v231, -v207, v135, v231
	ds_read_b128 v[204:207], v8 offset:15152
	s_waitcnt lgkmcnt(5)
	v_fma_f32 v230, -v208, v136, v230
	v_fma_f32 v231, -v209, v137, v231
	v_fma_f32 v230, -v210, v138, v230
	v_fma_f32 v231, -v211, v139, v231
	ds_read_b128 v[208:211], v8 offset:15168
	s_waitcnt lgkmcnt(5)
	v_fma_f32 v230, -v212, v140, v230
	v_fma_f32 v231, -v213, v141, v231
	ds_read_b128 v[212:215], v8 offset:15184
	v_add_f32_e32 v142, v230, v231
	s_cbranch_vccz .Ls4_u58
	v_cvt_pk_bf16_f32 v233, -v142, v142
	global_store_short v6, v233, s[8:9] offset:2560
	s_branch .Ls4_n58
; __device__ __forceinline__ void chunk_prep_phase(const Params& p, int bid, int nblk, LAS unsigned char* lds0) {
;     ...
;             { const float br = betg[59]; ab0 = (f32x2){bf2f(*(const LAS bf16_t*)(lg + P5_VS + 16048 + c * 2)) * br, bf2f(*(const LAS bf16_t*)(lg + P5_KS + 16048 + c * 2)) * br * __expf(decg[59])}; ab1 = (f32x2){0.f, 0.f}; } ab0 -= mq[0][0] * xy[0]; ab1 -= mq[0][1] * xy[1]; ab0 -= mq[0][2] * xy[2]; ab1 -= mq[0][3] * xy[3]; mq[0] = *(const LAS f32x4*)(Mg + 3800);
;             ab0 -= mq[1][0] * xy[4]; ab1 -= mq[1][1] * xy[5]; ab0 -= mq[1][2] * xy[6]; ab1 -= mq[1][3] * xy[7]; mq[1] = *(const LAS f32x4*)(Mg + 3804);
;             ab0 -= mq[2][0] * xy[8]; ab1 -= mq[2][1] * xy[9]; ab0 -= mq[2][2] * xy[10]; ab1 -= mq[2][3] * xy[11]; mq[2] = *(const LAS f32x4*)(Mg + 3808);
;             ab0 -= mq[3][0] * xy[12]; ab1 -= mq[3][1] * xy[13]; ab0 -= mq[3][2] * xy[14]; ab1 -= mq[3][3] * xy[15]; mq[3] = *(const LAS f32x4*)(Mg + 3812);
;             ab0 -= mq[4][0] * xy[16]; ab1 -= mq[4][1] * xy[17]; ab0 -= mq[4][2] * xy[18]; ab1 -= mq[4][3] * xy[19]; mq[4] = *(const LAS f32x4*)(Mg + 3816);
;             ab0 -= mq[5][0] * xy[20]; ab1 -= mq[5][1] * xy[21]; ab0 -= mq[5][2] * xy[22]; ab1 -= mq[5][3] * xy[23]; mq[5] = *(const LAS f32x4*)(Mg + 3820);
;             ab0 -= mq[0][0] * xy[24]; ab1 -= mq[0][1] * xy[25]; ab0 -= mq[0][2] * xy[26]; ab1 -= mq[0][3] * xy[27]; mq[0] = *(const LAS f32x4*)(Mg + 3824);
;             ab0 -= mq[1][0] * xy[28]; ab1 -= mq[1][1] * xy[29]; ab0 -= mq[1][2] * xy[30]; ab1 -= mq[1][3] * xy[31]; mq[1] = *(const LAS f32x4*)(Mg + 3828);
;             ab0 -= mq[2][0] * xy[32]; ab1 -= mq[2][1] * xy[33]; ab0 -= mq[2][2] * xy[34]; ab1 -= mq[2][3] * xy[35]; mq[2] = *(const LAS f32x4*)(Mg + 3832);
;             ab0 -= mq[3][0] * xy[36]; ab1 -= mq[3][1] * xy[37]; ab0 -= mq[3][2] * xy[38]; ab1 -= mq[3][3] * xy[39]; mq[3] = *(const LAS f32x4*)(Mg + 3840);
;             ab0 -= mq[4][0] * xy[40]; ab1 -= mq[4][1] * xy[41]; ab0 -= mq[4][2] * xy[42]; ab1 -= mq[4][3] * xy[43]; mq[4] = *(const LAS f32x4*)(Mg + 3844);
;             ab0 -= mq[5][0] * xy[44]; ab1 -= mq[5][1] * xy[45]; ab0 -= mq[5][2] * xy[46]; ab1 -= mq[5][3] * xy[47]; mq[5] = *(const LAS f32x4*)(Mg + 3848);
;             ab0 -= mq[0][0] * xy[48]; ab1 -= mq[0][1] * xy[49]; ab0 -= mq[0][2] * xy[50]; ab1 -= mq[0][3] * xy[51]; mq[0] = *(const LAS f32x4*)(Mg + 3852);
.Ls4_u58:
	global_store_dword v234, v142, s[8:9] offset:1024
.Ls4_n58:
	v_lshlrev_b32_e32 v229, 16, v229
	v_mul_f32_e32 v232, v229, v219
	v_mul_f32_e32 v230, v232, v3
	v_mov_b32_e32 v231, 0
	ds_read_u16 v228, v7 offset:16320
	s_waitcnt lgkmcnt(6)
	v_fma_f32 v230, -v192, v84, v230
	v_fma_f32 v231, -v193, v85, v231
	v_fma_f32 v230, -v194, v86, v230
	v_fma_f32 v231, -v195, v87, v231
	ds_read_b128 v[192:195], v8 offset:15200
	s_waitcnt lgkmcnt(6)
	v_fma_f32 v230, -v196, v88, v230
	v_fma_f32 v231, -v197, v89, v231
	v_fma_f32 v230, -v198, v90, v230
	v_fma_f32 v231, -v199, v91, v231
	ds_read_b128 v[196:199], v8 offset:15216
	s_waitcnt lgkmcnt(6)
	v_fma_f32 v230, -v200, v92, v230
	v_fma_f32 v231, -v201, v93, v231
	v_fma_f32 v230, -v202, v94, v230
	v_fma_f32 v231, -v203, v95, v231
	ds_read_b128 v[200:203], v8 offset:15232
	s_waitcnt lgkmcnt(6)
	v_fma_f32 v230, -v204, v96, v230
	v_fma_f32 v231, -v205, v97, v231
	v_fma_f32 v230, -v206, v98, v230
	v_fma_f32 v231, -v207, v99, v231
	ds_read_b128 v[204:207], v8 offset:15248
	s_waitcnt lgkmcnt(6)
	v_fma_f32 v230, -v208, v100, v230
	v_fma_f32 v231, -v209, v101, v231
	v_fma_f32 v230, -v210, v102, v230
	v_fma_f32 v231, -v211, v103, v231
	ds_read_b128 v[208:211], v8 offset:15264
	s_waitcnt lgkmcnt(6)
	v_fma_f32 v230, -v212, v104, v230
	v_fma_f32 v231, -v213, v105, v231
	v_fma_f32 v230, -v214, v106, v230
	v_fma_f32 v231, -v215, v107, v231
	ds_read_b128 v[212:215], v8 offset:15280
	s_waitcnt lgkmcnt(5)
	v_fma_f32 v230, -v192, v108, v230
	v_fma_f32 v231, -v193, v109, v231
	v_fma_f32 v230, -v194, v110, v230
	v_fma_f32 v231, -v195, v111, v231
	ds_read_b128 v[192:195], v8 offset:15296
	s_waitcnt lgkmcnt(5)
	v_fma_f32 v230, -v196, v112, v230
	v_fma_f32 v231, -v197, v113, v231
	v_fma_f32 v230, -v198, v114, v230
	v_fma_f32 v231, -v199, v115, v231
	ds_read_b128 v[196:199], v8 offset:15312
	s_waitcnt lgkmcnt(5)
	v_fma_f32 v230, -v200, v116, v230
	v_fma_f32 v231, -v201, v117, v231
	v_fma_f32 v230, -v202, v118, v230
	v_fma_f32 v231, -v203, v119, v231
	ds_read_b128 v[200:203], v8 offset:15328
	s_waitcnt lgkmcnt(5)
	v_fma_f32 v230, -v204, v120, v230
	v_fma_f32 v231, -v205, v121, v231
	v_fma_f32 v230, -v206, v122, v230
	v_fma_f32 v231, -v207, v123, v231
	ds_read_b128 v[204:207], v8 offset:15360
	s_waitcnt lgkmcnt(5)
	v_fma_f32 v230, -v208, v124, v230
	v_fma_f32 v231, -v209, v125, v231
	v_fma_f32 v230, -v210, v126, v230
	v_fma_f32 v231, -v211, v127, v231
	ds_read_b128 v[208:211], v8 offset:15376
	s_waitcnt lgkmcnt(5)
	v_fma_f32 v230, -v212, v128, v230
	v_fma_f32 v231, -v213, v129, v231
	v_fma_f32 v230, -v214, v130, v230
	v_fma_f32 v231, -v215, v131, v231
	ds_read_b128 v[212:215], v8 offset:15392
	s_waitcnt lgkmcnt(5)
	v_fma_f32 v230, -v192, v132, v230
	v_fma_f32 v231, -v193, v133, v231
	v_fma_f32 v230, -v194, v134, v230
	v_fma_f32 v231, -v195, v135, v231
	ds_read_b128 v[192:195], v8 offset:15408
	s_waitcnt lgkmcnt(5)
	v_fma_f32 v230, -v196, v136, v230
	v_fma_f32 v231, -v197, v137, v231
	v_fma_f32 v230, -v198, v138, v230
	v_fma_f32 v231, -v199, v139, v231
	ds_read_b128 v[196:199], v8 offset:15424
	s_waitcnt lgkmcnt(5)
	v_fma_f32 v230, -v200, v140, v230
	v_fma_f32 v231, -v201, v141, v231
	v_fma_f32 v230, -v202, v142, v230
	ds_read_b128 v[200:203], v8 offset:15440
	v_add_f32_e32 v143, v230, v231
	s_cbranch_vccz .Ls4_u59
	v_cvt_pk_bf16_f32 v233, -v143, v143
	global_store_short v6, v233, s[8:9] offset:2816
	s_branch .Ls4_n59
.Ls4_u59:
	global_store_dword v234, v143, s[8:9] offset:1536
.Ls4_n59:
	v_mul_f32_e32 v224, s16, v224
	v_mul_f32_e32 v225, s16, v225
	v_mul_f32_e32 v226, s16, v226
	v_mul_f32_e32 v227, s16, v227
	v_exp_f32_e32 v224, v224
	v_exp_f32_e32 v225, v225
	v_exp_f32_e32 v226, v226
	v_exp_f32_e32 v227, v227
	s_nop 0
	v_lshlrev_b32_e32 v228, 16, v228
	v_mul_f32_e32 v232, v228, v220
	v_mul_f32_e32 v230, v232, v224
	v_mov_b32_e32 v231, 0
	ds_read_u16 v229, v7 offset:16592
	s_waitcnt lgkmcnt(6)
	v_fma_f32 v230, -v204, v84, v230
	v_fma_f32 v231, -v205, v85, v231
	v_fma_f32 v230, -v206, v86, v230
	v_fma_f32 v231, -v207, v87, v231
	ds_read_b128 v[204:207], v8 offset:15456
	s_waitcnt lgkmcnt(6)
	v_fma_f32 v230, -v208, v88, v230
	v_fma_f32 v231, -v209, v89, v231
	v_fma_f32 v230, -v210, v90, v230
	v_fma_f32 v231, -v211, v91, v231
	ds_read_b128 v[208:211], v8 offset:15472
	s_waitcnt lgkmcnt(6)
	v_fma_f32 v230, -v212, v92, v230
	v_fma_f32 v231, -v213, v93, v231
	v_fma_f32 v230, -v214, v94, v230
	v_fma_f32 v231, -v215, v95, v231
	ds_read_b128 v[212:215], v8 offset:15488
	s_waitcnt lgkmcnt(6)
	v_fma_f32 v230, -v192, v96, v230
	v_fma_f32 v231, -v193, v97, v231
	v_fma_f32 v230, -v194, v98, v230
	v_fma_f32 v231, -v195, v99, v231
	ds_read_b128 v[192:195], v8 offset:15504
	s_waitcnt lgkmcnt(6)
	v_fma_f32 v230, -v196, v100, v230
	v_fma_f32 v231, -v197, v101, v231
	v_fma_f32 v230, -v198, v102, v230
	v_fma_f32 v231, -v199, v103, v231
	ds_read_b128 v[196:199], v8 offset:15520
	s_waitcnt lgkmcnt(6)
	v_fma_f32 v230, -v200, v104, v230
	v_fma_f32 v231, -v201, v105, v231
	v_fma_f32 v230, -v202, v106, v230
	v_fma_f32 v231, -v203, v107, v231
	ds_read_b128 v[200:203], v8 offset:15536
	s_waitcnt lgkmcnt(5)
	v_fma_f32 v230, -v204, v108, v230
	v_fma_f32 v231, -v205, v109, v231
	v_fma_f32 v230, -v206, v110, v230
	v_fma_f32 v231, -v207, v111, v231
	ds_read_b128 v[204:207], v8 offset:15552
	s_waitcnt lgkmcnt(5)
	v_fma_f32 v230, -v208, v112, v230
	v_fma_f32 v231, -v209, v113, v231
	v_fma_f32 v230, -v210, v114, v230
	v_fma_f32 v231, -v211, v115, v231
	ds_read_b128 v[208:211], v8 offset:15568
	s_waitcnt lgkmcnt(5)
	v_fma_f32 v230, -v212, v116, v230
	v_fma_f32 v231, -v213, v117, v231
	v_fma_f32 v230, -v214, v118, v230
	v_fma_f32 v231, -v215, v119, v231
	ds_read_b128 v[212:215], v8 offset:15584
	s_waitcnt lgkmcnt(5)
	v_fma_f32 v230, -v192, v120, v230
	v_fma_f32 v231, -v193, v121, v231
	v_fma_f32 v230, -v194, v122, v230
	v_fma_f32 v231, -v195, v123, v231
	ds_read_b128 v[192:195], v8 offset:15616
	s_waitcnt lgkmcnt(5)
	v_fma_f32 v230, -v196, v124, v230
	v_fma_f32 v231, -v197, v125, v231
	v_fma_f32 v230, -v198, v126, v230
	v_fma_f32 v231, -v199, v127, v231
	ds_read_b128 v[196:199], v8 offset:15632
	s_waitcnt lgkmcnt(5)
	v_fma_f32 v230, -v200, v128, v230
	v_fma_f32 v231, -v201, v129, v231
	v_fma_f32 v230, -v202, v130, v230
	v_fma_f32 v231, -v203, v131, v231
	ds_read_b128 v[200:203], v8 offset:15648
	s_waitcnt lgkmcnt(5)
	v_fma_f32 v230, -v204, v132, v230
	v_fma_f32 v231, -v205, v133, v231
	v_fma_f32 v230, -v206, v134, v230
	v_fma_f32 v231, -v207, v135, v231
	ds_read_b128 v[204:207], v8 offset:15664
	s_waitcnt lgkmcnt(5)
	v_fma_f32 v230, -v208, v136, v230
	v_fma_f32 v231, -v209, v137, v231
	v_fma_f32 v230, -v210, v138, v230
	v_fma_f32 v231, -v211, v139, v231
	ds_read_b128 v[208:211], v8 offset:15680
	s_waitcnt lgkmcnt(5)
	v_fma_f32 v230, -v212, v140, v230
	v_fma_f32 v231, -v213, v141, v231
	v_fma_f32 v230, -v214, v142, v230
	v_fma_f32 v231, -v215, v143, v231
	ds_read_b128 v[212:215], v8 offset:15696
	v_add_f32_e32 v144, v230, v231
	s_cbranch_vccz .Ls4_u60
; __device__ __forceinline__ void chunk_prep_phase(const Params& p, int bid, int nblk, LAS unsigned char* lds0) {
;     ...
;             { const float br = betg[61]; ab0 = (f32x2){bf2f(*(const LAS bf16_t*)(lg + P5_VS + 16592 + c * 2)) * br, bf2f(*(const LAS bf16_t*)(lg + P5_KS + 16592 + c * 2)) * br * __expf(decg[61])}; ab1 = (f32x2){0.f, 0.f}; } ab0 -= mq[0][0] * xy[0]; ab1 -= mq[0][1] * xy[1]; ab0 -= mq[0][2] * xy[2]; ab1 -= mq[0][3] * xy[3]; mq[0] = *(const LAS f32x4*)(Mg + 3928);
;             ab0 -= mq[1][0] * xy[4]; ab1 -= mq[1][1] * xy[5]; ab0 -= mq[1][2] * xy[6]; ab1 -= mq[1][3] * xy[7]; mq[1] = *(const LAS f32x4*)(Mg + 3932);
;             ab0 -= mq[2][0] * xy[8]; ab1 -= mq[2][1] * xy[9]; ab0 -= mq[2][2] * xy[10]; ab1 -= mq[2][3] * xy[11]; mq[2] = *(const LAS f32x4*)(Mg + 3936);
;             ab0 -= mq[3][0] * xy[12]; ab1 -= mq[3][1] * xy[13]; ab0 -= mq[3][2] * xy[14]; ab1 -= mq[3][3] * xy[15]; mq[3] = *(const LAS f32x4*)(Mg + 3940);
;             ab0 -= mq[4][0] * xy[16]; ab1 -= mq[4][1] * xy[17]; ab0 -= mq[4][2] * xy[18]; ab1 -= mq[4][3] * xy[19]; mq[4] = *(const LAS f32x4*)(Mg + 3944);
;             ab0 -= mq[5][0] * xy[20]; ab1 -= mq[5][1] * xy[21]; ab0 -= mq[5][2] * xy[22]; ab1 -= mq[5][3] * xy[23]; mq[5] = *(const LAS f32x4*)(Mg + 3948);
;             ab0 -= mq[0][0] * xy[24]; ab1 -= mq[0][1] * xy[25]; ab0 -= mq[0][2] * xy[26]; ab1 -= mq[0][3] * xy[27]; mq[0] = *(const LAS f32x4*)(Mg + 3952);
;             ab0 -= mq[1][0] * xy[28]; ab1 -= mq[1][1] * xy[29]; ab0 -= mq[1][2] * xy[30]; ab1 -= mq[1][3] * xy[31]; mq[1] = *(const LAS f32x4*)(Mg + 3956);
;             ab0 -= mq[2][0] * xy[32]; ab1 -= mq[2][1] * xy[33]; ab0 -= mq[2][2] * xy[34]; ab1 -= mq[2][3] * xy[35]; mq[2] = *(const LAS f32x4*)(Mg + 3960);
;             ab0 -= mq[3][0] * xy[36]; ab1 -= mq[3][1] * xy[37]; ab0 -= mq[3][2] * xy[38]; ab1 -= mq[3][3] * xy[39]; mq[3] = *(const LAS f32x4*)(Mg + 3964);
;             ab0 -= mq[4][0] * xy[40]; ab1 -= mq[4][1] * xy[41]; ab0 -= mq[4][2] * xy[42]; ab1 -= mq[4][3] * xy[43]; mq[4] = *(const LAS f32x4*)(Mg + 3968);
;             ab0 -= mq[5][0] * xy[44]; ab1 -= mq[5][1] * xy[45]; ab0 -= mq[5][2] * xy[46]; ab1 -= mq[5][3] * xy[47]; mq[5] = *(const LAS f32x4*)(Mg + 3972);
;             ab0 -= mq[0][0] * xy[48]; ab1 -= mq[0][1] * xy[49]; ab0 -= mq[0][2] * xy[50]; ab1 -= mq[0][3] * xy[51]; mq[0] = *(const LAS f32x4*)(Mg + 3976);
	v_cvt_pk_bf16_f32 v233, -v144, v144
	global_store_short v6, v233, s[8:9] offset:3072
	s_branch .Ls4_n60
.Ls4_u60:
	global_store_dword v234, v144, s[8:9] offset:2048
.Ls4_n60:
	v_lshlrev_b32_e32 v229, 16, v229
	v_mul_f32_e32 v232, v229, v221
	v_mul_f32_e32 v230, v232, v225
	v_mov_b32_e32 v231, 0
	ds_read_u16 v228, v7 offset:16864
	s_waitcnt lgkmcnt(6)
	v_fma_f32 v230, -v192, v84, v230
	v_fma_f32 v231, -v193, v85, v231
	v_fma_f32 v230, -v194, v86, v230
	v_fma_f32 v231, -v195, v87, v231
	ds_read_b128 v[192:195], v8 offset:15712
	s_waitcnt lgkmcnt(6)
	v_fma_f32 v230, -v196, v88, v230
	v_fma_f32 v231, -v197, v89, v231
	v_fma_f32 v230, -v198, v90, v230
	v_fma_f32 v231, -v199, v91, v231
	ds_read_b128 v[196:199], v8 offset:15728
	s_waitcnt lgkmcnt(6)
	v_fma_f32 v230, -v200, v92, v230
	v_fma_f32 v231, -v201, v93, v231
	v_fma_f32 v230, -v202, v94, v230
	v_fma_f32 v231, -v203, v95, v231
	ds_read_b128 v[200:203], v8 offset:15744
	s_waitcnt lgkmcnt(6)
	v_fma_f32 v230, -v204, v96, v230
	v_fma_f32 v231, -v205, v97, v231
	v_fma_f32 v230, -v206, v98, v230
	v_fma_f32 v231, -v207, v99, v231
	ds_read_b128 v[204:207], v8 offset:15760
	s_waitcnt lgkmcnt(6)
	v_fma_f32 v230, -v208, v100, v230
	v_fma_f32 v231, -v209, v101, v231
	v_fma_f32 v230, -v210, v102, v230
	v_fma_f32 v231, -v211, v103, v231
	ds_read_b128 v[208:211], v8 offset:15776
	s_waitcnt lgkmcnt(6)
	v_fma_f32 v230, -v212, v104, v230
	v_fma_f32 v231, -v213, v105, v231
	v_fma_f32 v230, -v214, v106, v230
	v_fma_f32 v231, -v215, v107, v231
	ds_read_b128 v[212:215], v8 offset:15792
	s_waitcnt lgkmcnt(5)
	v_fma_f32 v230, -v192, v108, v230
	v_fma_f32 v231, -v193, v109, v231
	v_fma_f32 v230, -v194, v110, v230
	v_fma_f32 v231, -v195, v111, v231
	ds_read_b128 v[192:195], v8 offset:15808
	s_waitcnt lgkmcnt(5)
	v_fma_f32 v230, -v196, v112, v230
	v_fma_f32 v231, -v197, v113, v231
	v_fma_f32 v230, -v198, v114, v230
	v_fma_f32 v231, -v199, v115, v231
	ds_read_b128 v[196:199], v8 offset:15824
	s_waitcnt lgkmcnt(5)
	v_fma_f32 v230, -v200, v116, v230
	v_fma_f32 v231, -v201, v117, v231
	v_fma_f32 v230, -v202, v118, v230
	v_fma_f32 v231, -v203, v119, v231
	ds_read_b128 v[200:203], v8 offset:15840
	s_waitcnt lgkmcnt(5)
	v_fma_f32 v230, -v204, v120, v230
	v_fma_f32 v231, -v205, v121, v231
	v_fma_f32 v230, -v206, v122, v230
	v_fma_f32 v231, -v207, v123, v231
	ds_read_b128 v[204:207], v8 offset:15856
	s_waitcnt lgkmcnt(5)
	v_fma_f32 v230, -v208, v124, v230
	v_fma_f32 v231, -v209, v125, v231
	v_fma_f32 v230, -v210, v126, v230
	v_fma_f32 v231, -v211, v127, v231
	ds_read_b128 v[208:211], v8 offset:15872
	s_waitcnt lgkmcnt(5)
	v_fma_f32 v230, -v212, v128, v230
	v_fma_f32 v231, -v213, v129, v231
	v_fma_f32 v230, -v214, v130, v230
	v_fma_f32 v231, -v215, v131, v231
	ds_read_b128 v[212:215], v8 offset:15888
	s_waitcnt lgkmcnt(5)
	v_fma_f32 v230, -v192, v132, v230
	v_fma_f32 v231, -v193, v133, v231
	v_fma_f32 v230, -v194, v134, v230
	v_fma_f32 v231, -v195, v135, v231
	ds_read_b128 v[192:195], v8 offset:15904
	s_waitcnt lgkmcnt(5)
	v_fma_f32 v230, -v196, v136, v230
	v_fma_f32 v231, -v197, v137, v231
	v_fma_f32 v230, -v198, v138, v230
	v_fma_f32 v231, -v199, v139, v231
	ds_read_b128 v[196:199], v8 offset:15920
	s_waitcnt lgkmcnt(5)
	v_fma_f32 v230, -v200, v140, v230
	v_fma_f32 v231, -v201, v141, v231
	v_fma_f32 v230, -v202, v142, v230
	v_fma_f32 v231, -v203, v143, v231
	ds_read_b128 v[200:203], v8 offset:15936
	s_waitcnt lgkmcnt(5)
	v_fma_f32 v230, -v204, v144, v230
	ds_read_b128 v[204:207], v8 offset:15952
	v_add_f32_e32 v145, v230, v231
	s_cbranch_vccz .Ls4_u61
	v_cvt_pk_bf16_f32 v233, -v145, v145
	global_store_short v6, v233, s[8:9] offset:3328
	s_branch .Ls4_n61
.Ls4_u61:
	global_store_dword v234, v145, s[8:9] offset:2560
.Ls4_n61:
	v_lshlrev_b32_e32 v228, 16, v228
	v_mul_f32_e32 v232, v228, v222
	v_mul_f32_e32 v230, v232, v226
	v_mov_b32_e32 v231, 0
	ds_read_u16 v229, v7 offset:17136
	s_waitcnt lgkmcnt(6)
	v_fma_f32 v230, -v208, v84, v230
	v_fma_f32 v231, -v209, v85, v231
	v_fma_f32 v230, -v210, v86, v230
	v_fma_f32 v231, -v211, v87, v231
	ds_read_b128 v[208:211], v8 offset:15968
	s_waitcnt lgkmcnt(6)
	v_fma_f32 v230, -v212, v88, v230
	v_fma_f32 v231, -v213, v89, v231
	v_fma_f32 v230, -v214, v90, v230
	v_fma_f32 v231, -v215, v91, v231
	ds_read_b128 v[212:215], v8 offset:15984
	s_waitcnt lgkmcnt(6)
	v_fma_f32 v230, -v192, v92, v230
	v_fma_f32 v231, -v193, v93, v231
	v_fma_f32 v230, -v194, v94, v230
	v_fma_f32 v231, -v195, v95, v231
	ds_read_b128 v[192:195], v8 offset:16000
	s_waitcnt lgkmcnt(6)
	v_fma_f32 v230, -v196, v96, v230
	v_fma_f32 v231, -v197, v97, v231
	v_fma_f32 v230, -v198, v98, v230
	v_fma_f32 v231, -v199, v99, v231
	ds_read_b128 v[196:199], v8 offset:16016
	s_waitcnt lgkmcnt(6)
	v_fma_f32 v230, -v200, v100, v230
	v_fma_f32 v231, -v201, v101, v231
	v_fma_f32 v230, -v202, v102, v230
	v_fma_f32 v231, -v203, v103, v231
	ds_read_b128 v[200:203], v8 offset:16032
	s_waitcnt lgkmcnt(6)
	v_fma_f32 v230, -v204, v104, v230
	v_fma_f32 v231, -v205, v105, v231
	v_fma_f32 v230, -v206, v106, v230
	v_fma_f32 v231, -v207, v107, v231
	ds_read_b128 v[204:207], v8 offset:16048
	s_waitcnt lgkmcnt(5)
	v_fma_f32 v230, -v208, v108, v230
	v_fma_f32 v231, -v209, v109, v231
	v_fma_f32 v230, -v210, v110, v230
	v_fma_f32 v231, -v211, v111, v231
	ds_read_b128 v[208:211], v8 offset:16064
	s_waitcnt lgkmcnt(5)
; __device__ __forceinline__ void chunk_prep_phase(const Params& p, int bid, int nblk, LAS unsigned char* lds0) {
;     ...
;             { const float br = betg[62]; ab0 = (f32x2){bf2f(*(const LAS bf16_t*)(lg + P5_VS + 16864 + c * 2)) * br, bf2f(*(const LAS bf16_t*)(lg + P5_KS + 16864 + c * 2)) * br * __expf(decg[62])}; ab1 = (f32x2){0.f, 0.f}; } ab0 -= mq[4][0] * xy[0]; ab1 -= mq[4][1] * xy[1]; ab0 -= mq[4][2] * xy[2]; ab1 -= mq[4][3] * xy[3]; mq[4] = *(const LAS f32x4*)(Mg + 3992);
;             ab0 -= mq[5][0] * xy[4]; ab1 -= mq[5][1] * xy[5]; ab0 -= mq[5][2] * xy[6]; ab1 -= mq[5][3] * xy[7]; mq[5] = *(const LAS f32x4*)(Mg + 3996);
;             ab0 -= mq[0][0] * xy[8]; ab1 -= mq[0][1] * xy[9]; ab0 -= mq[0][2] * xy[10]; ab1 -= mq[0][3] * xy[11]; mq[0] = *(const LAS f32x4*)(Mg + 4000);
;             ab0 -= mq[1][0] * xy[12]; ab1 -= mq[1][1] * xy[13]; ab0 -= mq[1][2] * xy[14]; ab1 -= mq[1][3] * xy[15]; mq[1] = *(const LAS f32x4*)(Mg + 4004);
;             ab0 -= mq[2][0] * xy[16]; ab1 -= mq[2][1] * xy[17]; ab0 -= mq[2][2] * xy[18]; ab1 -= mq[2][3] * xy[19]; mq[2] = *(const LAS f32x4*)(Mg + 4008);
;             ab0 -= mq[3][0] * xy[20]; ab1 -= mq[3][1] * xy[21]; ab0 -= mq[3][2] * xy[22]; ab1 -= mq[3][3] * xy[23]; mq[3] = *(const LAS f32x4*)(Mg + 4012);
;             ab0 -= mq[4][0] * xy[24]; ab1 -= mq[4][1] * xy[25]; ab0 -= mq[4][2] * xy[26]; ab1 -= mq[4][3] * xy[27]; mq[4] = *(const LAS f32x4*)(Mg + 4016);
;             ab0 -= mq[5][0] * xy[28]; ab1 -= mq[5][1] * xy[29]; ab0 -= mq[5][2] * xy[30]; ab1 -= mq[5][3] * xy[31]; mq[5] = *(const LAS f32x4*)(Mg + 4020);
;             ab0 -= mq[0][0] * xy[32]; ab1 -= mq[0][1] * xy[33]; ab0 -= mq[0][2] * xy[34]; ab1 -= mq[0][3] * xy[35]; mq[0] = *(const LAS f32x4*)(Mg + 4024);
;             ab0 -= mq[1][0] * xy[36]; ab1 -= mq[1][1] * xy[37]; ab0 -= mq[1][2] * xy[38]; ab1 -= mq[1][3] * xy[39]; mq[1] = *(const LAS f32x4*)(Mg + 4028);
;             ab0 -= mq[2][0] * xy[40]; ab1 -= mq[2][1] * xy[41]; ab0 -= mq[2][2] * xy[42]; ab1 -= mq[2][3] * xy[43]; mq[2] = *(const LAS f32x4*)(Mg + 4032);
;             ab0 -= mq[3][0] * xy[44]; ab1 -= mq[3][1] * xy[45]; ab0 -= mq[3][2] * xy[46]; ab1 -= mq[3][3] * xy[47]; mq[3] = *(const LAS f32x4*)(Mg + 4036);
;             ab0 -= mq[4][0] * xy[48]; ab1 -= mq[4][1] * xy[49]; ab0 -= mq[4][2] * xy[50]; ab1 -= mq[4][3] * xy[51]; mq[4] = *(const LAS f32x4*)(Mg + 4040);
	v_fma_f32 v230, -v212, v112, v230
	v_fma_f32 v231, -v213, v113, v231
	v_fma_f32 v230, -v214, v114, v230
	v_fma_f32 v231, -v215, v115, v231
	ds_read_b128 v[212:215], v8 offset:16080
	s_waitcnt lgkmcnt(5)
	v_fma_f32 v230, -v192, v116, v230
	v_fma_f32 v231, -v193, v117, v231
	v_fma_f32 v230, -v194, v118, v230
	v_fma_f32 v231, -v195, v119, v231
	ds_read_b128 v[192:195], v8 offset:16096
	s_waitcnt lgkmcnt(5)
	v_fma_f32 v230, -v196, v120, v230
	v_fma_f32 v231, -v197, v121, v231
	v_fma_f32 v230, -v198, v122, v230
	v_fma_f32 v231, -v199, v123, v231
	ds_read_b128 v[196:199], v8 offset:16112
	s_waitcnt lgkmcnt(5)
	v_fma_f32 v230, -v200, v124, v230
	v_fma_f32 v231, -v201, v125, v231
	v_fma_f32 v230, -v202, v126, v230
	v_fma_f32 v231, -v203, v127, v231
	ds_read_b128 v[200:203], v8 offset:16128
	s_waitcnt lgkmcnt(5)
	v_fma_f32 v230, -v204, v128, v230
	v_fma_f32 v231, -v205, v129, v231
	v_fma_f32 v230, -v206, v130, v230
	v_fma_f32 v231, -v207, v131, v231
	ds_read_b128 v[204:207], v8 offset:16144
	s_waitcnt lgkmcnt(5)
	v_fma_f32 v230, -v208, v132, v230
	v_fma_f32 v231, -v209, v133, v231
	v_fma_f32 v230, -v210, v134, v230
	v_fma_f32 v231, -v211, v135, v231
	ds_read_b128 v[208:211], v8 offset:16160
	s_waitcnt lgkmcnt(5)
	v_fma_f32 v230, -v212, v136, v230
	v_fma_f32 v231, -v213, v137, v231
	v_fma_f32 v230, -v214, v138, v230
	v_fma_f32 v231, -v215, v139, v231
	ds_read_b128 v[212:215], v8 offset:16176
	s_waitcnt lgkmcnt(5)
	v_fma_f32 v230, -v192, v140, v230
	v_fma_f32 v231, -v193, v141, v231
	v_fma_f32 v230, -v194, v142, v230
	v_fma_f32 v231, -v195, v143, v231
	ds_read_b128 v[192:195], v8 offset:16192
	s_waitcnt lgkmcnt(5)
	v_fma_f32 v230, -v196, v144, v230
	v_fma_f32 v231, -v197, v145, v231
	ds_read_b128 v[196:199], v8 offset:16208
	v_add_f32_e32 v146, v230, v231
	s_cbranch_vccz .Ls4_u62
	v_cvt_pk_bf16_f32 v233, -v146, v146
	global_store_short v6, v233, s[8:9] offset:3584
	s_branch .Ls4_n62
.Ls4_u62:
	global_store_dword v234, v146, s[8:9] offset:3072
.Ls4_n62:
	v_lshlrev_b32_e32 v229, 16, v229
	v_mul_f32_e32 v232, v229, v223
	v_mul_f32_e32 v230, v232, v227
	v_mov_b32_e32 v231, 0
	s_waitcnt lgkmcnt(5)
	v_fma_f32 v230, -v200, v84, v230
	v_fma_f32 v231, -v201, v85, v231
	v_fma_f32 v230, -v202, v86, v230
	v_fma_f32 v231, -v203, v87, v231
	ds_read_b128 v[200:203], v8 offset:16224
	s_waitcnt lgkmcnt(5)
	v_fma_f32 v230, -v204, v88, v230
	v_fma_f32 v231, -v205, v89, v231
	v_fma_f32 v230, -v206, v90, v230
	v_fma_f32 v231, -v207, v91, v231
	ds_read_b128 v[204:207], v8 offset:16240
	s_waitcnt lgkmcnt(5)
	v_fma_f32 v230, -v208, v92, v230
	v_fma_f32 v231, -v209, v93, v231
	v_fma_f32 v230, -v210, v94, v230
	v_fma_f32 v231, -v211, v95, v231
	ds_read_b128 v[208:211], v8 offset:16256
	s_waitcnt lgkmcnt(5)
	v_fma_f32 v230, -v212, v96, v230
	v_fma_f32 v231, -v213, v97, v231
	v_fma_f32 v230, -v214, v98, v230
	v_fma_f32 v231, -v215, v99, v231
	ds_read_b128 v[212:215], v8 offset:16272
	s_waitcnt lgkmcnt(5)
	v_fma_f32 v230, -v192, v100, v230
	v_fma_f32 v231, -v193, v101, v231
	v_fma_f32 v230, -v194, v102, v230
	v_fma_f32 v231, -v195, v103, v231
	ds_read_b128 v[192:195], v8 offset:16288
	s_waitcnt lgkmcnt(5)
	v_fma_f32 v230, -v196, v104, v230
	v_fma_f32 v231, -v197, v105, v231
	v_fma_f32 v230, -v198, v106, v230
	v_fma_f32 v231, -v199, v107, v231
	ds_read_b128 v[196:199], v8 offset:16304
	s_waitcnt lgkmcnt(5)
	v_fma_f32 v230, -v200, v108, v230
	v_fma_f32 v231, -v201, v109, v231
	v_fma_f32 v230, -v202, v110, v230
	v_fma_f32 v231, -v203, v111, v231
	ds_read_b128 v[200:203], v8 offset:16320
	s_waitcnt lgkmcnt(5)
	v_fma_f32 v230, -v204, v112, v230
	v_fma_f32 v231, -v205, v113, v231
	v_fma_f32 v230, -v206, v114, v230
	v_fma_f32 v231, -v207, v115, v231
	ds_read_b128 v[204:207], v8 offset:16336
	s_waitcnt lgkmcnt(5)
	v_fma_f32 v230, -v208, v116, v230
	v_fma_f32 v231, -v209, v117, v231
	v_fma_f32 v230, -v210, v118, v230
	v_fma_f32 v231, -v211, v119, v231
	ds_read_b128 v[208:211], v8 offset:16352
	s_waitcnt lgkmcnt(5)
	v_fma_f32 v230, -v212, v120, v230
	v_fma_f32 v231, -v213, v121, v231
	v_fma_f32 v230, -v214, v122, v230
	v_fma_f32 v231, -v215, v123, v231
	ds_read_b128 v[212:215], v8 offset:16368
	s_waitcnt lgkmcnt(5)
	v_fma_f32 v230, -v192, v124, v230
	v_fma_f32 v231, -v193, v125, v231
	v_fma_f32 v230, -v194, v126, v230
	v_fma_f32 v231, -v195, v127, v231
	s_waitcnt lgkmcnt(4)
	v_fma_f32 v230, -v196, v128, v230
	v_fma_f32 v231, -v197, v129, v231
	v_fma_f32 v230, -v198, v130, v230
	v_fma_f32 v231, -v199, v131, v231
	s_waitcnt lgkmcnt(3)
	v_fma_f32 v230, -v200, v132, v230
	v_fma_f32 v231, -v201, v133, v231
	v_fma_f32 v230, -v202, v134, v230
	v_fma_f32 v231, -v203, v135, v231
	s_waitcnt lgkmcnt(2)
	v_fma_f32 v230, -v204, v136, v230
	v_fma_f32 v231, -v205, v137, v231
	v_fma_f32 v230, -v206, v138, v230
	v_fma_f32 v231, -v207, v139, v231
	s_waitcnt lgkmcnt(1)
	v_fma_f32 v230, -v208, v140, v230
	v_fma_f32 v231, -v209, v141, v231
	v_fma_f32 v230, -v210, v142, v230
	v_fma_f32 v231, -v211, v143, v231
	s_waitcnt lgkmcnt(0)
	v_fma_f32 v230, -v212, v144, v230
	v_fma_f32 v231, -v213, v145, v231
	v_fma_f32 v230, -v214, v146, v230
	v_add_f32_e32 v147, v230, v231
	s_cbranch_vccz .Ls4_u63
	v_cvt_pk_bf16_f32 v233, -v147, v147
	global_store_short v6, v233, s[8:9] offset:3840
	s_branch .Ls4_n63
.Ls4_u63:
	global_store_dword v234, v147, s[8:9] offset:3584
.Ls4_n63:
	s_branch .LBB0_962
.LBB0_1009:
	v_readlane_b32 s82, v236, 4
	v_readlane_b32 s8, v236, 6
	v_readlane_b32 s83, v236, 5
	v_readlane_b32 s9, v236, 7
	s_waitcnt vmcnt(0) lgkmcnt(0)
	s_barrier

; #define PG8_STAGE(bufoff, gbase, voff) do { _Pragma("unroll") for (int _i = 0; _i < 2; ++_i) \
;         __builtin_amdgcn_global_load_lds((const unsigned*)((const char*)(gbase) + (voff)[_i]), (LAS unsigned*)(lds + (bufoff) + ldsw + _i * 8192), 16, 0, 0); } while (0)
; #define PG8_LDA(dst, b, h) do { _Pragma("unroll") for (int m = 0; m < 4; ++m) _Pragma("unroll") for (int k = 0; k < 2; ++k) dst[m][k] = *(const LAS bf16x8*)(lds + PG8_SA(b, h) + aoff + m * 2048 + k * 1024); } while (0)
; #define PG8_LDB(dst, b, h) do { _Pragma("unroll") for (int n = 0; n < 2; ++n) _Pragma("unroll") for (int k = 0; k < 2; ++k) dst[n][k] = *(const LAS bf16x8*)(lds + PG8_SB(b, h) + boff + n * 2048 + k * 1024); } while (0)
; #define PG8_MMA(ai, bj, At, Bt) do { __builtin_amdgcn_s_setprio(1); _Pragma("unroll") for (int m = 0; m < 4; ++m) _Pragma("unroll") for (int n = 0; n < 2; ++n) _Pragma("unroll") for (int k = 0; k < 2; ++k) \
;         acc[ai][bj][m][n] = __builtin_amdgcn_mfma_f32_16x16x32_bf16(Bt[n][k], At[m][k], acc[ai][bj][m][n], 0, 0, 0); __builtin_amdgcn_s_setprio(0); } while (0)
; #define PG8_WAIT_V(n) asm volatile("s_waitcnt vmcnt(" #n ")" ::: "memory")
; #define PG8_WAIT_L(n) asm volatile("s_waitcnt lgkmcnt(" #n ")" ::: "memory")
; #define PG8_BAR __builtin_amdgcn_s_barrier()
; #define PG8_SCHED __builtin_amdgcn_sched_barrier(0)
; template <class Epi, class Sched>
; __device__ __forceinline__ void gemm_phase(LAS unsigned char* lds, const Gemm g, const Sched& S, const Epi& E) {
;     ...
;             PG8_LDB(B0, 0, 0); PG8_SCHED; PG8_LDA(At, 0, 0); PG8_STAGE(PG8_SA(1, 1), a1 + hstepA, voffA);
;             PG8_WAIT_L(8); PG8_BAR; PG8_WAIT_L(0); PG8_MMA(0, 0, At, B0); PG8_BAR; PG8_SCHED;
;             PG8_LDB(B1, 0, 1); PG8_STAGE(PG8_SB(0, 0), b2, voffB);
;             PG8_BAR; PG8_WAIT_L(0); if constexpr (!Epi::DIAG) PG8_MMA(0, 1, At, B1); PG8_BAR;
;             PG8_LDA(At, 0, 1); PG8_STAGE(PG8_SA(0, 0), a2, voffA);
;             PG8_BAR; PG8_WAIT_L(0); if constexpr (!Epi::DIAG) PG8_MMA(1, 0, At, B0); PG8_BAR; PG8_SCHED;
;             PG8_STAGE(PG8_SB(0, 1), b2 + hstepB, voffB);
;             PG8_WAIT_V(6); PG8_BAR; PG8_MMA(1, 1, At, B1); PG8_BAR;
.LBB0_1174:
	s_add_u32 s48, s40, s29
	s_addc_u32 s49, s41, 0
	s_add_u32 s50, s48, 0x100
	s_addc_u32 s51, s49, 0
	s_and_b64 s[46:47], s[44:45], exec
	s_cselect_b32 s51, s31, s51
	s_cselect_b32 s50, s30, s50
	s_add_u32 s29, s38, s29
	s_addc_u32 s46, s39, 0
	s_add_u32 s29, s29, 0x100
	s_addc_u32 s46, s46, 0
	s_and_b64 s[44:45], s[44:45], exec
	s_cselect_b32 s53, s9, s46
	s_cselect_b32 s52, s27, s29
	s_add_u32 s54, s48, 0x40080
	s_addc_u32 s55, s49, 0
	s_add_i32 s80, s69, s56
	s_add_i32 m0, s37, 0xc000
	s_add_i32 s79, s37, 0xe000
	s_add_i32 s78, s80, 0x2000
	s_add_u32 s48, s52, 0x10000
	s_addc_u32 s49, s53, 0
	s_add_i32 s75, s70, s56
	ds_read_b128 v[142:145], v154
	ds_read_b128 v[146:149], v154 offset:1024
	ds_read_b128 v[162:165], v154 offset:2048
	ds_read_b128 v[168:171], v154 offset:3072
	s_add_i32 s74, s75, 0x2000
	s_add_i32 s73, 0, 0x18000
	s_add_u32 s46, s50, 0x40000
	s_addc_u32 s47, s51, 0
	s_add_i32 s72, s73, s56
	s_add_i32 s71, 0, 0x1c000
	s_add_i32 s29, s72, 0x2000
	s_add_u32 s44, s52, 0x10080
	s_addc_u32 s45, s53, 0
	s_add_i32 s77, s71, s56
	s_add_i32 s76, s77, 0x2000
	v_lshl_add_u64 v[158:159], s[54:55], 0, v[130:131]
	ds_read_b128 v[172:175], v155
	ds_read_b128 v[176:179], v155 offset:1024
	ds_read_b128 v[180:183], v155 offset:2048
	ds_read_b128 v[186:189], v155 offset:3072
	ds_read_b128 v[190:193], v155 offset:4096
	ds_read_b128 v[194:197], v155 offset:5120
	ds_read_b128 v[198:201], v155 offset:6144
	ds_read_b128 v[202:205], v155 offset:7168
	global_load_lds_dwordx4 v[158:159], off
	v_lshl_add_u64 v[158:159], s[54:55], 0, v[134:135]
	s_mov_b32 m0, s79
	s_nop 0
	global_load_lds_dwordx4 v[158:159], off
	s_waitcnt lgkmcnt(8)
	s_barrier
	s_waitcnt lgkmcnt(0)
	s_setprio 1
	s_waitcnt lgkmcnt(0)
	v_mfma_f32_16x16x32_bf16 v[124:127], v[142:145], v[172:175], v[124:127]
	v_mfma_f32_16x16x32_bf16 v[120:123], v[162:165], v[172:175], v[120:123]
	v_mfma_f32_16x16x32_bf16 v[108:111], v[142:145], v[180:183], v[108:111]
	v_mfma_f32_16x16x32_bf16 v[104:107], v[162:165], v[180:183], v[104:107]
	v_mfma_f32_16x16x32_bf16 v[92:95], v[142:145], v[190:193], v[92:95]
	v_mfma_f32_16x16x32_bf16 v[88:91], v[162:165], v[190:193], v[88:91]
	v_mfma_f32_16x16x32_bf16 v[76:79], v[142:145], v[198:201], v[76:79]
	v_mfma_f32_16x16x32_bf16 v[72:75], v[162:165], v[198:201], v[72:75]
	v_mfma_f32_16x16x32_bf16 v[124:127], v[146:149], v[176:179], v[124:127]
	v_mfma_f32_16x16x32_bf16 v[120:123], v[168:171], v[176:179], v[120:123]
	v_mfma_f32_16x16x32_bf16 v[108:111], v[146:149], v[186:189], v[108:111]
	v_mfma_f32_16x16x32_bf16 v[104:107], v[168:171], v[186:189], v[104:107]
	v_mfma_f32_16x16x32_bf16 v[92:95], v[146:149], v[194:197], v[92:95]
	v_mfma_f32_16x16x32_bf16 v[88:91], v[168:171], v[194:197], v[88:91]
	v_mfma_f32_16x16x32_bf16 v[76:79], v[146:149], v[202:205], v[76:79]
	v_mfma_f32_16x16x32_bf16 v[72:75], v[168:171], v[202:205], v[72:75]
	s_setprio 0
	s_barrier
	s_mov_b32 m0, s80
	v_lshl_add_u64 v[158:159], s[52:53], 0, v[132:133]
	ds_read_b128 v[206:209], v156
	ds_read_b128 v[210:213], v156 offset:1024
	ds_read_b128 v[214:217], v156 offset:2048
	ds_read_b128 v[218:221], v156 offset:3072
	global_load_lds_dwordx4 v[158:159], off
	v_lshl_add_u64 v[222:223], s[52:53], 0, v[136:137]
	s_mov_b32 m0, s78
	s_nop 0
	global_load_lds_dwordx4 v[222:223], off
	s_barrier
	s_waitcnt lgkmcnt(0)
	s_setprio 1
	s_waitcnt lgkmcnt(0)
	v_mfma_f32_16x16x32_bf16 v[116:119], v[206:209], v[172:175], v[116:119]
	v_mfma_f32_16x16x32_bf16 v[112:115], v[214:217], v[172:175], v[112:115]
	v_mfma_f32_16x16x32_bf16 v[100:103], v[206:209], v[180:183], v[100:103]
	v_mfma_f32_16x16x32_bf16 v[96:99], v[214:217], v[180:183], v[96:99]
	v_mfma_f32_16x16x32_bf16 v[84:87], v[206:209], v[190:193], v[84:87]
	v_mfma_f32_16x16x32_bf16 v[80:83], v[214:217], v[190:193], v[80:83]
	v_mfma_f32_16x16x32_bf16 v[68:71], v[206:209], v[198:201], v[68:71]
	v_mfma_f32_16x16x32_bf16 v[64:67], v[214:217], v[198:201], v[64:67]
	v_mfma_f32_16x16x32_bf16 v[116:119], v[210:213], v[176:179], v[116:119]
	v_mfma_f32_16x16x32_bf16 v[112:115], v[218:221], v[176:179], v[112:115]
	v_mfma_f32_16x16x32_bf16 v[100:103], v[210:213], v[186:189], v[100:103]
	v_mfma_f32_16x16x32_bf16 v[96:99], v[218:221], v[186:189], v[96:99]
	v_mfma_f32_16x16x32_bf16 v[84:87], v[210:213], v[194:197], v[84:87]
	v_mfma_f32_16x16x32_bf16 v[80:83], v[218:221], v[194:197], v[80:83]
	v_mfma_f32_16x16x32_bf16 v[68:71], v[210:213], v[202:205], v[68:71]
	v_mfma_f32_16x16x32_bf16 v[64:67], v[218:221], v[202:205], v[64:67]
	s_setprio 0
	s_mov_b32 m0, s37
	v_lshl_add_u64 v[224:225], s[50:51], 0, v[130:131]
	s_barrier
	ds_read_b128 v[172:175], v155 offset:16384
	ds_read_b128 v[176:179], v155 offset:17408
	ds_read_b128 v[180:183], v155 offset:18432
	ds_read_b128 v[186:189], v155 offset:19456
	ds_read_b128 v[190:193], v155 offset:20480
	ds_read_b128 v[194:197], v155 offset:21504
	ds_read_b128 v[198:201], v155 offset:22528
	ds_read_b128 v[202:205], v155 offset:23552
	global_load_lds_dwordx4 v[224:225], off
	v_lshl_add_u64 v[226:227], s[50:51], 0, v[134:135]
	s_mov_b32 m0, s61
	s_nop 0
	global_load_lds_dwordx4 v[226:227], off
	s_barrier
; #define PG8_STAGE(bufoff, gbase, voff) do { _Pragma("unroll") for (int _i = 0; _i < 2; ++_i) \
;         __builtin_amdgcn_global_load_lds((const unsigned*)((const char*)(gbase) + (voff)[_i]), (LAS unsigned*)(lds + (bufoff) + ldsw + _i * 8192), 16, 0, 0); } while (0)
; #define PG8_LDA(dst, b, h) do { _Pragma("unroll") for (int m = 0; m < 4; ++m) _Pragma("unroll") for (int k = 0; k < 2; ++k) dst[m][k] = *(const LAS bf16x8*)(lds + PG8_SA(b, h) + aoff + m * 2048 + k * 1024); } while (0)
; #define PG8_LDB(dst, b, h) do { _Pragma("unroll") for (int n = 0; n < 2; ++n) _Pragma("unroll") for (int k = 0; k < 2; ++k) dst[n][k] = *(const LAS bf16x8*)(lds + PG8_SB(b, h) + boff + n * 2048 + k * 1024); } while (0)
; #define PG8_MMA(ai, bj, At, Bt) do { __builtin_amdgcn_s_setprio(1); _Pragma("unroll") for (int m = 0; m < 4; ++m) _Pragma("unroll") for (int n = 0; n < 2; ++n) _Pragma("unroll") for (int k = 0; k < 2; ++k) \
;         acc[ai][bj][m][n] = __builtin_amdgcn_mfma_f32_16x16x32_bf16(Bt[n][k], At[m][k], acc[ai][bj][m][n], 0, 0, 0); __builtin_amdgcn_s_setprio(0); } while (0)
; #define PG8_WAIT_V(n) asm volatile("s_waitcnt vmcnt(" #n ")" ::: "memory")
; #define PG8_WAIT_L(n) asm volatile("s_waitcnt lgkmcnt(" #n ")" ::: "memory")
; #define PG8_BAR __builtin_amdgcn_s_barrier()
; #define PG8_SCHED __builtin_amdgcn_sched_barrier(0)
; template <class Epi, class Sched>
; __device__ __forceinline__ void gemm_phase(LAS unsigned char* lds, const Gemm g, const Sched& S, const Epi& E) {
;     ...
;             PG8_WAIT_V(6); PG8_BAR; PG8_MMA(1, 1, At, B1); PG8_BAR;
;             PG8_LDB(B0, 1, 0); PG8_SCHED; PG8_LDA(At, 1, 0); PG8_STAGE(PG8_SA(0, 1), a2 + hstepA, voffA);
;             PG8_WAIT_L(8); PG8_BAR; PG8_WAIT_L(0); PG8_MMA(0, 0, At, B0); PG8_BAR; PG8_SCHED;
;             PG8_LDB(B1, 1, 1); PG8_STAGE(PG8_SB(1, 0), b3, voffB);
;             PG8_BAR; PG8_WAIT_L(0); if constexpr (!Epi::DIAG) PG8_MMA(0, 1, At, B1); PG8_BAR;
;             PG8_LDA(At, 1, 1); PG8_STAGE(PG8_SA(1, 0), a3, voffA);
;             PG8_BAR; PG8_WAIT_L(0); if constexpr (!Epi::DIAG) PG8_MMA(1, 0, At, B0); PG8_BAR; PG8_SCHED;
	s_waitcnt lgkmcnt(0)
	s_setprio 1
	s_waitcnt lgkmcnt(0)
	v_mfma_f32_16x16x32_bf16 v[60:63], v[142:145], v[172:175], v[60:63]
	v_mfma_f32_16x16x32_bf16 v[56:59], v[162:165], v[172:175], v[56:59]
	v_mfma_f32_16x16x32_bf16 v[44:47], v[142:145], v[180:183], v[44:47]
	v_mfma_f32_16x16x32_bf16 v[40:43], v[162:165], v[180:183], v[40:43]
	v_mfma_f32_16x16x32_bf16 v[28:31], v[142:145], v[190:193], v[28:31]
	v_mfma_f32_16x16x32_bf16 v[24:27], v[162:165], v[190:193], v[24:27]
	v_mfma_f32_16x16x32_bf16 v[12:15], v[142:145], v[198:201], v[12:15]
	v_mfma_f32_16x16x32_bf16 v[8:11], v[162:165], v[198:201], v[8:11]
	v_mfma_f32_16x16x32_bf16 v[60:63], v[146:149], v[176:179], v[60:63]
	v_mfma_f32_16x16x32_bf16 v[56:59], v[168:171], v[176:179], v[56:59]
	v_mfma_f32_16x16x32_bf16 v[44:47], v[146:149], v[186:189], v[44:47]
	v_mfma_f32_16x16x32_bf16 v[40:43], v[168:171], v[186:189], v[40:43]
	v_mfma_f32_16x16x32_bf16 v[28:31], v[146:149], v[194:197], v[28:31]
	v_mfma_f32_16x16x32_bf16 v[24:27], v[168:171], v[194:197], v[24:27]
	v_mfma_f32_16x16x32_bf16 v[12:15], v[146:149], v[202:205], v[12:15]
	v_mfma_f32_16x16x32_bf16 v[8:11], v[168:171], v[202:205], v[8:11]
	s_setprio 0
	s_barrier
	s_mov_b32 m0, s75
	v_lshl_add_u64 v[142:143], s[48:49], 0, v[132:133]
	global_load_lds_dwordx4 v[142:143], off
	v_lshl_add_u64 v[142:143], s[48:49], 0, v[136:137]
	s_mov_b32 m0, s74
	s_nop 0
	global_load_lds_dwordx4 v[142:143], off
	s_waitcnt vmcnt(6)
	s_barrier
	s_setprio 1
	v_mfma_f32_16x16x32_bf16 v[52:55], v[206:209], v[172:175], v[52:55]
	v_mfma_f32_16x16x32_bf16 v[48:51], v[214:217], v[172:175], v[48:51]
	v_mfma_f32_16x16x32_bf16 v[36:39], v[206:209], v[180:183], v[36:39]
	v_mfma_f32_16x16x32_bf16 v[32:35], v[214:217], v[180:183], v[32:35]
	v_mfma_f32_16x16x32_bf16 v[20:23], v[206:209], v[190:193], v[20:23]
	v_mfma_f32_16x16x32_bf16 v[16:19], v[214:217], v[190:193], v[16:19]
	v_mfma_f32_16x16x32_bf16 v[4:7], v[206:209], v[198:201], v[4:7]
	v_mfma_f32_16x16x32_bf16 v[0:3], v[214:217], v[198:201], v[0:3]
	v_mfma_f32_16x16x32_bf16 v[52:55], v[210:213], v[176:179], v[52:55]
	v_mfma_f32_16x16x32_bf16 v[48:51], v[218:221], v[176:179], v[48:51]
	v_mfma_f32_16x16x32_bf16 v[36:39], v[210:213], v[186:189], v[36:39]
	v_mfma_f32_16x16x32_bf16 v[32:35], v[218:221], v[186:189], v[32:35]
	v_mfma_f32_16x16x32_bf16 v[20:23], v[210:213], v[194:197], v[20:23]
	v_mfma_f32_16x16x32_bf16 v[16:19], v[218:221], v[194:197], v[16:19]
	v_mfma_f32_16x16x32_bf16 v[4:7], v[210:213], v[202:205], v[4:7]
	v_mfma_f32_16x16x32_bf16 v[0:3], v[218:221], v[202:205], v[0:3]
	s_setprio 0
	v_add_u32_e32 v157, s73, v152
	s_barrier
	ds_read_b128 v[142:145], v157
	ds_read_b128 v[146:149], v157 offset:1024
	ds_read_b128 v[162:165], v157 offset:2048
	ds_read_b128 v[168:171], v157 offset:3072
	s_mov_b32 m0, s62
	v_lshl_add_u64 v[206:207], s[46:47], 0, v[130:131]
	ds_read_b128 v[172:175], v155 offset:32768
	ds_read_b128 v[176:179], v155 offset:33792
	ds_read_b128 v[180:183], v155 offset:34816
	ds_read_b128 v[186:189], v155 offset:35840
	ds_read_b128 v[190:193], v155 offset:36864
	ds_read_b128 v[194:197], v155 offset:37888
	ds_read_b128 v[198:201], v155 offset:38912
	ds_read_b128 v[202:205], v155 offset:39936
	global_load_lds_dwordx4 v[206:207], off
	v_lshl_add_u64 v[206:207], s[46:47], 0, v[134:135]
	s_mov_b32 m0, s63
	s_nop 0
	global_load_lds_dwordx4 v[206:207], off
	s_waitcnt lgkmcnt(8)
	s_barrier
	s_waitcnt lgkmcnt(0)
	s_setprio 1
	s_waitcnt lgkmcnt(0)
	v_mfma_f32_16x16x32_bf16 v[124:127], v[142:145], v[172:175], v[124:127]
	v_mfma_f32_16x16x32_bf16 v[120:123], v[162:165], v[172:175], v[120:123]
	v_mfma_f32_16x16x32_bf16 v[108:111], v[142:145], v[180:183], v[108:111]
	v_mfma_f32_16x16x32_bf16 v[104:107], v[162:165], v[180:183], v[104:107]
	v_mfma_f32_16x16x32_bf16 v[92:95], v[142:145], v[190:193], v[92:95]
	v_mfma_f32_16x16x32_bf16 v[88:91], v[162:165], v[190:193], v[88:91]
	v_mfma_f32_16x16x32_bf16 v[76:79], v[142:145], v[198:201], v[76:79]
	v_mfma_f32_16x16x32_bf16 v[72:75], v[162:165], v[198:201], v[72:75]
	v_mfma_f32_16x16x32_bf16 v[124:127], v[146:149], v[176:179], v[124:127]
	v_mfma_f32_16x16x32_bf16 v[120:123], v[168:171], v[176:179], v[120:123]
	v_mfma_f32_16x16x32_bf16 v[108:111], v[146:149], v[186:189], v[108:111]
	v_mfma_f32_16x16x32_bf16 v[104:107], v[168:171], v[186:189], v[104:107]
	v_mfma_f32_16x16x32_bf16 v[92:95], v[146:149], v[194:197], v[92:95]
	v_mfma_f32_16x16x32_bf16 v[88:91], v[168:171], v[194:197], v[88:91]
	v_mfma_f32_16x16x32_bf16 v[76:79], v[146:149], v[202:205], v[76:79]
	v_mfma_f32_16x16x32_bf16 v[72:75], v[168:171], v[202:205], v[72:75]
	s_setprio 0
	s_barrier
	s_mov_b32 m0, s72
	v_add_u32_e32 v157, s71, v152
	v_lshl_add_u64 v[158:159], v[158:159], 0, s[16:17]
	ds_read_b128 v[206:209], v157
	ds_read_b128 v[210:213], v157 offset:1024
	ds_read_b128 v[214:217], v157 offset:2048
	ds_read_b128 v[218:221], v157 offset:3072
	global_load_lds_dwordx4 v[158:159], off
	v_lshl_add_u64 v[158:159], v[222:223], 0, s[16:17]
	s_mov_b32 m0, s29
	s_nop 0
	global_load_lds_dwordx4 v[158:159], off
	s_barrier
; __device__ __forceinline__ unsigned pk2(float lo, float hi) { const f32x2 v = {lo, hi}; const bf16x2_hw b = __builtin_convertvector(v, bf16x2_hw); return __builtin_bit_cast(unsigned, b); }
; #define PG8_STAGE(bufoff, gbase, voff) do { _Pragma("unroll") for (int _i = 0; _i < 2; ++_i) \
;         __builtin_amdgcn_global_load_lds((const unsigned*)((const char*)(gbase) + (voff)[_i]), (LAS unsigned*)(lds + (bufoff) + ldsw + _i * 8192), 16, 0, 0); } while (0)
; #define PG8_LDA(dst, b, h) do { _Pragma("unroll") for (int m = 0; m < 4; ++m) _Pragma("unroll") for (int k = 0; k < 2; ++k) dst[m][k] = *(const LAS bf16x8*)(lds + PG8_SA(b, h) + aoff + m * 2048 + k * 1024); } while (0)
; #define PG8_BAR __builtin_amdgcn_s_barrier()
; template <class Epi, class Sched>
; __device__ __forceinline__ void gemm_phase(LAS unsigned char* lds, const Gemm g, const Sched& S, const Epi& E) {
;     ...
;             PG8_WAIT_V(6); PG8_BAR; PG8_MMA(1, 1, At, B1); PG8_BAR;
;             PG8_LDB(B0, 1, 0); PG8_SCHED; PG8_LDA(At, 1, 0); PG8_STAGE(PG8_SA(0, 1), a2 + hstepA, voffA);
;             PG8_WAIT_L(8); PG8_BAR; PG8_WAIT_L(0); PG8_MMA(0, 0, At, B0); PG8_BAR; PG8_SCHED;
;             PG8_LDB(B1, 1, 1); PG8_STAGE(PG8_SB(1, 0), b3, voffB);
;             PG8_BAR; PG8_WAIT_L(0); if constexpr (!Epi::DIAG) PG8_MMA(0, 1, At, B1); PG8_BAR;
;             PG8_LDA(At, 1, 1); PG8_STAGE(PG8_SA(1, 0), a3, voffA);
;             PG8_BAR; PG8_WAIT_L(0); if constexpr (!Epi::DIAG) PG8_MMA(1, 0, At, B0); PG8_BAR; PG8_SCHED;
;             PG8_STAGE(PG8_SB(1, 1), b3 + hstepB, voffB);
;             PG8_WAIT_V(6); PG8_BAR; PG8_MMA(1, 1, At, B1); PG8_BAR;
;     __device__ __forceinline__ void operator()(const Acc& acc, const Unit& u, int wr, int wc, int fr, int fq) const {
;     ...
;             for (int m = 0; m < 4; ++m) { bf16_t* rowp = O + (size_t)(row0 + ai * HALF + m * 16) * ldc + col_off + col0;
; #pragma unroll
;                 for (int bj = 0; bj < 2; ++bj) { f32x4 v0 = acc[ai][bj][m][0], v1 = acc[ai][bj][m][1];
;                     if (scale) { v0 *= *(const f32x4*)(scale + col0 + bj * HALF); v1 *= *(const f32x4*)(scale + col0 + bj * HALF + 4); }
;                     u32x4 w; w.x = pk2(v0[0], v0[1]); w.y = pk2(v0[2], v0[3]); w.z = pk2(v1[0], v1[1]); w.w = pk2(v1[2], v1[3]);
;                     *(u32x4*)(rowp + bj * HALF) = w; }
;                 if (scale) asm volatile("" ::: "memory"); }
	s_waitcnt lgkmcnt(0)
	s_setprio 1
	s_waitcnt lgkmcnt(0)
	v_mfma_f32_16x16x32_bf16 v[116:119], v[206:209], v[172:175], v[116:119]
	v_mfma_f32_16x16x32_bf16 v[112:115], v[214:217], v[172:175], v[112:115]
	v_mfma_f32_16x16x32_bf16 v[100:103], v[206:209], v[180:183], v[100:103]
	v_mfma_f32_16x16x32_bf16 v[96:99], v[214:217], v[180:183], v[96:99]
	v_mfma_f32_16x16x32_bf16 v[84:87], v[206:209], v[190:193], v[84:87]
	v_mfma_f32_16x16x32_bf16 v[80:83], v[214:217], v[190:193], v[80:83]
	v_mfma_f32_16x16x32_bf16 v[68:71], v[206:209], v[198:201], v[68:71]
	v_mfma_f32_16x16x32_bf16 v[64:67], v[214:217], v[198:201], v[64:67]
	v_mfma_f32_16x16x32_bf16 v[116:119], v[210:213], v[176:179], v[116:119]
	v_mfma_f32_16x16x32_bf16 v[112:115], v[218:221], v[176:179], v[112:115]
	v_mfma_f32_16x16x32_bf16 v[100:103], v[210:213], v[186:189], v[100:103]
	v_mfma_f32_16x16x32_bf16 v[96:99], v[218:221], v[186:189], v[96:99]
	v_mfma_f32_16x16x32_bf16 v[84:87], v[210:213], v[194:197], v[84:87]
	v_mfma_f32_16x16x32_bf16 v[80:83], v[218:221], v[194:197], v[80:83]
	v_mfma_f32_16x16x32_bf16 v[68:71], v[210:213], v[202:205], v[68:71]
	v_mfma_f32_16x16x32_bf16 v[64:67], v[218:221], v[202:205], v[64:67]
	s_setprio 0
	s_mov_b32 m0, s67
	v_lshl_add_u64 v[158:159], v[224:225], 0, s[16:17]
	s_barrier
	ds_read_b128 v[172:175], v155 offset:49152
	ds_read_b128 v[176:179], v155 offset:50176
	ds_read_b128 v[180:183], v155 offset:51200
	ds_read_b128 v[186:189], v155 offset:52224
	ds_read_b128 v[190:193], v155 offset:53248
	ds_read_b128 v[194:197], v155 offset:54272
	ds_read_b128 v[198:201], v155 offset:55296
	ds_read_b128 v[202:205], v155 offset:56320
	global_load_lds_dwordx4 v[158:159], off
	v_lshl_add_u64 v[158:159], v[226:227], 0, s[16:17]
	s_mov_b32 m0, s68
	s_nop 0
	global_load_lds_dwordx4 v[158:159], off
	s_barrier
	s_waitcnt lgkmcnt(0)
	s_setprio 1
	s_waitcnt lgkmcnt(0)
	v_mfma_f32_16x16x32_bf16 v[60:63], v[142:145], v[172:175], v[60:63]
	v_mfma_f32_16x16x32_bf16 v[56:59], v[162:165], v[172:175], v[56:59]
	v_mfma_f32_16x16x32_bf16 v[44:47], v[142:145], v[180:183], v[44:47]
	v_mfma_f32_16x16x32_bf16 v[40:43], v[162:165], v[180:183], v[40:43]
	v_mfma_f32_16x16x32_bf16 v[28:31], v[142:145], v[190:193], v[28:31]
	v_mfma_f32_16x16x32_bf16 v[24:27], v[162:165], v[190:193], v[24:27]
	v_mfma_f32_16x16x32_bf16 v[12:15], v[142:145], v[198:201], v[12:15]
	v_mfma_f32_16x16x32_bf16 v[8:11], v[162:165], v[198:201], v[8:11]
	v_mfma_f32_16x16x32_bf16 v[60:63], v[146:149], v[176:179], v[60:63]
	v_mfma_f32_16x16x32_bf16 v[56:59], v[168:171], v[176:179], v[56:59]
	v_mfma_f32_16x16x32_bf16 v[44:47], v[146:149], v[186:189], v[44:47]
	v_mfma_f32_16x16x32_bf16 v[40:43], v[168:171], v[186:189], v[40:43]
	v_mfma_f32_16x16x32_bf16 v[28:31], v[146:149], v[194:197], v[28:31]
	v_mfma_f32_16x16x32_bf16 v[24:27], v[168:171], v[194:197], v[24:27]
	v_mfma_f32_16x16x32_bf16 v[12:15], v[146:149], v[202:205], v[12:15]
	v_mfma_f32_16x16x32_bf16 v[8:11], v[168:171], v[202:205], v[8:11]
	s_setprio 0
	s_barrier
	s_mov_b32 m0, s77
	v_lshl_add_u64 v[142:143], s[44:45], 0, v[132:133]
	global_load_lds_dwordx4 v[142:143], off
	v_lshl_add_u64 v[142:143], s[44:45], 0, v[136:137]
	s_mov_b32 m0, s76
	s_nop 0
	global_load_lds_dwordx4 v[142:143], off
	s_waitcnt vmcnt(6)
	s_barrier
	s_setprio 1
	v_mfma_f32_16x16x32_bf16 v[52:55], v[206:209], v[172:175], v[52:55]
	v_mfma_f32_16x16x32_bf16 v[48:51], v[214:217], v[172:175], v[48:51]
	v_mfma_f32_16x16x32_bf16 v[36:39], v[206:209], v[180:183], v[36:39]
	v_mfma_f32_16x16x32_bf16 v[32:35], v[214:217], v[180:183], v[32:35]
	v_mfma_f32_16x16x32_bf16 v[20:23], v[206:209], v[190:193], v[20:23]
	v_mfma_f32_16x16x32_bf16 v[16:19], v[214:217], v[190:193], v[16:19]
	v_mfma_f32_16x16x32_bf16 v[4:7], v[206:209], v[198:201], v[4:7]
	v_mfma_f32_16x16x32_bf16 v[0:3], v[214:217], v[198:201], v[0:3]
	v_mfma_f32_16x16x32_bf16 v[52:55], v[210:213], v[176:179], v[52:55]
	v_mfma_f32_16x16x32_bf16 v[48:51], v[218:221], v[176:179], v[48:51]
	v_mfma_f32_16x16x32_bf16 v[36:39], v[210:213], v[186:189], v[36:39]
	v_mfma_f32_16x16x32_bf16 v[32:35], v[218:221], v[186:189], v[32:35]
	v_mfma_f32_16x16x32_bf16 v[20:23], v[210:213], v[194:197], v[20:23]
	v_mfma_f32_16x16x32_bf16 v[16:19], v[218:221], v[194:197], v[16:19]
	v_mfma_f32_16x16x32_bf16 v[4:7], v[210:213], v[202:205], v[4:7]
	v_mfma_f32_16x16x32_bf16 v[0:3], v[218:221], v[202:205], v[0:3]
	s_setprio 0
	s_movk_i32 s29, 0x100
	s_andn2_b64 vcc, exec, s[42:43]
	s_mov_b64 s[44:45], -1
	s_mov_b64 s[42:43], 0
	s_barrier
	s_cbranch_vccz .LBB0_1174
	v_lshl_or_b32 v144, s8, 8, v153
	v_ashrrev_i32_e32 v145, 31, v144
	v_cndmask_b32_e64 v142, 0, 1, s[14:15]
	v_cmp_ne_u32_e64 s[8:9], 1, v142
	s_andn2_b64 vcc, exec, s[14:15]
	v_lshl_add_u64 v[142:143], v[144:145], 2, s[10:11]
	s_cbranch_vccnz .LBB0_1177
	global_load_dwordx4 v[186:189], v[142:143], off
	global_load_dwordx4 v[190:193], v[142:143], off offset:16
	global_load_dwordx4 v[194:197], v[142:143], off offset:512
	global_load_dwordx4 v[198:201], v[142:143], off offset:528
	s_waitcnt vmcnt(0)
	s_nop 1
	v_mov_b32_e32 v146, v186
	v_mov_b32_e32 v147, v187
	v_mov_b32_e32 v148, v188
	v_mov_b32_e32 v149, v189
	s_nop 1
	v_mov_b32_e32 v162, v190
	v_mov_b32_e32 v163, v191
	v_mov_b32_e32 v164, v192
	v_mov_b32_e32 v165, v193
	v_pk_mul_f32 v[126:127], v[126:127], v[148:149]
	v_pk_mul_f32 v[124:125], v[124:125], v[146:147]
	v_pk_mul_f32 v[122:123], v[122:123], v[164:165]
	v_pk_mul_f32 v[120:121], v[120:121], v[162:163]
.LBB0_1177:
	v_lshl_add_u32 v146, s36, 8, v151
	v_ashrrev_i32_e32 v147, 31, v146
	v_lshlrev_b64 v[148:149], 12, v[146:147]
	v_lshl_add_u64 v[148:149], s[12:13], 0, v[148:149]
	v_lshl_add_u64 v[148:149], v[144:145], 1, v[148:149]
	v_cvt_pk_bf16_f32 v124, v124, v125
	v_cvt_pk_bf16_f32 v125, v126, v127
	v_cvt_pk_bf16_f32 v126, v120, v121
	v_cvt_pk_bf16_f32 v127, v122, v123
	s_and_b64 vcc, exec, s[8:9]
	global_store_dwordx4 v[148:149], v[124:127], off offset:2048
	s_cbranch_vccnz .LBB0_1179
	s_nop 1
	v_mov_b32_e32 v120, v194
	v_mov_b32_e32 v121, v195
	v_mov_b32_e32 v122, v196
	v_mov_b32_e32 v123, v197
	s_nop 1
	v_mov_b32_e32 v124, v198
	v_mov_b32_e32 v125, v199
	v_mov_b32_e32 v126, v200
	v_mov_b32_e32 v127, v201
	v_pk_mul_f32 v[118:119], v[118:119], v[122:123]
	v_pk_mul_f32 v[116:117], v[116:117], v[120:121]
	v_pk_mul_f32 v[114:115], v[114:115], v[126:127]
	v_pk_mul_f32 v[112:113], v[112:113], v[124:125]

; __device__ __forceinline__ unsigned pk2(float lo, float hi) { const f32x2 v = {lo, hi}; const bf16x2_hw b = __builtin_convertvector(v, bf16x2_hw); return __builtin_bit_cast(unsigned, b); }
;     __device__ __forceinline__ void operator()(const Acc& acc, const Unit& u, int wr, int wc, int fr, int fq) const {
;     ...
;             for (int m = 0; m < 4; ++m) { bf16_t* rowp = O + (size_t)(row0 + ai * HALF + m * 16) * ldc + col_off + col0;
; #pragma unroll
;                 for (int bj = 0; bj < 2; ++bj) { f32x4 v0 = acc[ai][bj][m][0], v1 = acc[ai][bj][m][1];
;                     if (scale) { v0 *= *(const f32x4*)(scale + col0 + bj * HALF); v1 *= *(const f32x4*)(scale + col0 + bj * HALF + 4); }
;                     u32x4 w; w.x = pk2(v0[0], v0[1]); w.y = pk2(v0[2], v0[3]); w.z = pk2(v1[0], v1[1]); w.w = pk2(v1[2], v1[3]);
;                     *(u32x4*)(rowp + bj * HALF) = w; }
;                 if (scale) asm volatile("" ::: "memory"); }
.LBB0_1181:
	s_and_b64 vcc, exec, s[8:9]
	s_cbranch_vccnz .LBB0_1183
	s_nop 1
	v_mov_b32_e32 v112, v186
	v_mov_b32_e32 v113, v187
	v_mov_b32_e32 v114, v188
	v_mov_b32_e32 v115, v189
	s_nop 1
	v_mov_b32_e32 v116, v190
	v_mov_b32_e32 v117, v191
	v_mov_b32_e32 v118, v192
	v_mov_b32_e32 v119, v193
	v_pk_mul_f32 v[110:111], v[110:111], v[114:115]
	v_pk_mul_f32 v[108:109], v[108:109], v[112:113]
	v_pk_mul_f32 v[106:107], v[106:107], v[118:119]
	v_pk_mul_f32 v[104:105], v[104:105], v[116:117]
.LBB0_1183:
	v_or_b32_e32 v112, 16, v146
	v_ashrrev_i32_e32 v113, 31, v112
	v_lshlrev_b64 v[112:113], 12, v[112:113]
	v_lshl_add_u64 v[112:113], s[12:13], 0, v[112:113]
	v_lshl_add_u64 v[112:113], v[144:145], 1, v[112:113]
	v_cvt_pk_bf16_f32 v108, v108, v109
	v_cvt_pk_bf16_f32 v109, v110, v111
	v_cvt_pk_bf16_f32 v110, v104, v105
	v_cvt_pk_bf16_f32 v111, v106, v107
	s_and_b64 vcc, exec, s[8:9]
	global_store_dwordx4 v[112:113], v[108:111], off offset:2048
	s_cbranch_vccnz .LBB0_1185
	s_nop 1
	v_mov_b32_e32 v104, v194
	v_mov_b32_e32 v105, v195
	v_mov_b32_e32 v106, v196
	v_mov_b32_e32 v107, v197
	s_nop 1
	v_mov_b32_e32 v108, v198
	v_mov_b32_e32 v109, v199
	v_mov_b32_e32 v110, v200
	v_mov_b32_e32 v111, v201
	v_pk_mul_f32 v[102:103], v[102:103], v[106:107]
	v_pk_mul_f32 v[100:101], v[100:101], v[104:105]
	v_pk_mul_f32 v[98:99], v[98:99], v[110:111]
	v_pk_mul_f32 v[96:97], v[96:97], v[108:109]

; __device__ __forceinline__ unsigned pk2(float lo, float hi) { const f32x2 v = {lo, hi}; const bf16x2_hw b = __builtin_convertvector(v, bf16x2_hw); return __builtin_bit_cast(unsigned, b); }
;     __device__ __forceinline__ void operator()(const Acc& acc, const Unit& u, int wr, int wc, int fr, int fq) const {
;     ...
;             for (int m = 0; m < 4; ++m) { bf16_t* rowp = O + (size_t)(row0 + ai * HALF + m * 16) * ldc + col_off + col0;
; #pragma unroll
;                 for (int bj = 0; bj < 2; ++bj) { f32x4 v0 = acc[ai][bj][m][0], v1 = acc[ai][bj][m][1];
;                     if (scale) { v0 *= *(const f32x4*)(scale + col0 + bj * HALF); v1 *= *(const f32x4*)(scale + col0 + bj * HALF + 4); }
;                     u32x4 w; w.x = pk2(v0[0], v0[1]); w.y = pk2(v0[2], v0[3]); w.z = pk2(v1[0], v1[1]); w.w = pk2(v1[2], v1[3]);
;                     *(u32x4*)(rowp + bj * HALF) = w; }
;                 if (scale) asm volatile("" ::: "memory"); }
.LBB0_1187:
	s_and_b64 vcc, exec, s[8:9]
	s_cbranch_vccnz .LBB0_1189
	s_nop 1
	v_mov_b32_e32 v96, v186
	v_mov_b32_e32 v97, v187
	v_mov_b32_e32 v98, v188
	v_mov_b32_e32 v99, v189
	s_nop 1
	v_mov_b32_e32 v100, v190
	v_mov_b32_e32 v101, v191
	v_mov_b32_e32 v102, v192
	v_mov_b32_e32 v103, v193
	v_pk_mul_f32 v[94:95], v[94:95], v[98:99]
	v_pk_mul_f32 v[92:93], v[92:93], v[96:97]
	v_pk_mul_f32 v[90:91], v[90:91], v[102:103]
	v_pk_mul_f32 v[88:89], v[88:89], v[100:101]
.LBB0_1189:
	v_or_b32_e32 v96, 32, v146
	v_ashrrev_i32_e32 v97, 31, v96
	v_lshlrev_b64 v[96:97], 12, v[96:97]
	v_lshl_add_u64 v[96:97], s[12:13], 0, v[96:97]
	v_lshl_add_u64 v[96:97], v[144:145], 1, v[96:97]
	v_cvt_pk_bf16_f32 v92, v92, v93
	v_cvt_pk_bf16_f32 v93, v94, v95
	v_cvt_pk_bf16_f32 v94, v88, v89
	v_cvt_pk_bf16_f32 v95, v90, v91
	s_and_b64 vcc, exec, s[8:9]
	global_store_dwordx4 v[96:97], v[92:95], off offset:2048
	s_cbranch_vccnz .LBB0_1191
	s_nop 1
	v_mov_b32_e32 v88, v194
	v_mov_b32_e32 v89, v195
	v_mov_b32_e32 v90, v196
	v_mov_b32_e32 v91, v197
	s_nop 1
	v_mov_b32_e32 v92, v198
	v_mov_b32_e32 v93, v199
	v_mov_b32_e32 v94, v200
	v_mov_b32_e32 v95, v201
	v_pk_mul_f32 v[86:87], v[86:87], v[90:91]
	v_pk_mul_f32 v[84:85], v[84:85], v[88:89]
	v_pk_mul_f32 v[82:83], v[82:83], v[94:95]
	v_pk_mul_f32 v[80:81], v[80:81], v[92:93]

; __device__ __forceinline__ unsigned pk2(float lo, float hi) { const f32x2 v = {lo, hi}; const bf16x2_hw b = __builtin_convertvector(v, bf16x2_hw); return __builtin_bit_cast(unsigned, b); }
;     __device__ __forceinline__ void operator()(const Acc& acc, const Unit& u, int wr, int wc, int fr, int fq) const {
;     ...
;             for (int m = 0; m < 4; ++m) { bf16_t* rowp = O + (size_t)(row0 + ai * HALF + m * 16) * ldc + col_off + col0;
; #pragma unroll
;                 for (int bj = 0; bj < 2; ++bj) { f32x4 v0 = acc[ai][bj][m][0], v1 = acc[ai][bj][m][1];
;                     if (scale) { v0 *= *(const f32x4*)(scale + col0 + bj * HALF); v1 *= *(const f32x4*)(scale + col0 + bj * HALF + 4); }
;                     u32x4 w; w.x = pk2(v0[0], v0[1]); w.y = pk2(v0[2], v0[3]); w.z = pk2(v1[0], v1[1]); w.w = pk2(v1[2], v1[3]);
;                     *(u32x4*)(rowp + bj * HALF) = w; }
;                 if (scale) asm volatile("" ::: "memory"); }
.LBB0_1193:
	s_and_b64 vcc, exec, s[8:9]
	s_cbranch_vccnz .LBB0_1195
	s_nop 1
	v_mov_b32_e32 v80, v186
	v_mov_b32_e32 v81, v187
	v_mov_b32_e32 v82, v188
	v_mov_b32_e32 v83, v189
	s_nop 1
	v_mov_b32_e32 v84, v190
	v_mov_b32_e32 v85, v191
	v_mov_b32_e32 v86, v192
	v_mov_b32_e32 v87, v193
	v_pk_mul_f32 v[78:79], v[78:79], v[82:83]
	v_pk_mul_f32 v[76:77], v[76:77], v[80:81]
	v_pk_mul_f32 v[74:75], v[74:75], v[86:87]
	v_pk_mul_f32 v[72:73], v[72:73], v[84:85]
.LBB0_1195:
	v_or_b32_e32 v80, 48, v146
	v_ashrrev_i32_e32 v81, 31, v80
	v_lshlrev_b64 v[80:81], 12, v[80:81]
	v_lshl_add_u64 v[80:81], s[12:13], 0, v[80:81]
	v_lshl_add_u64 v[80:81], v[144:145], 1, v[80:81]
	v_cvt_pk_bf16_f32 v76, v76, v77
	v_cvt_pk_bf16_f32 v77, v78, v79
	v_cvt_pk_bf16_f32 v78, v72, v73
	v_cvt_pk_bf16_f32 v79, v74, v75
	s_and_b64 vcc, exec, s[8:9]
	global_store_dwordx4 v[80:81], v[76:79], off offset:2048
	s_cbranch_vccnz .LBB0_1197
	s_nop 1
	v_mov_b32_e32 v72, v194
	v_mov_b32_e32 v73, v195
	v_mov_b32_e32 v74, v196
	v_mov_b32_e32 v75, v197
	s_nop 1
	v_mov_b32_e32 v76, v198
	v_mov_b32_e32 v77, v199
	v_mov_b32_e32 v78, v200
	v_mov_b32_e32 v79, v201
	v_pk_mul_f32 v[70:71], v[70:71], v[74:75]
	v_pk_mul_f32 v[68:69], v[68:69], v[72:73]
	v_pk_mul_f32 v[66:67], v[66:67], v[78:79]
	v_pk_mul_f32 v[64:65], v[64:65], v[76:77]

; __device__ __forceinline__ unsigned pk2(float lo, float hi) { const f32x2 v = {lo, hi}; const bf16x2_hw b = __builtin_convertvector(v, bf16x2_hw); return __builtin_bit_cast(unsigned, b); }
;     __device__ __forceinline__ void operator()(const Acc& acc, const Unit& u, int wr, int wc, int fr, int fq) const {
;     ...
;             for (int m = 0; m < 4; ++m) { bf16_t* rowp = O + (size_t)(row0 + ai * HALF + m * 16) * ldc + col_off + col0;
; #pragma unroll
;                 for (int bj = 0; bj < 2; ++bj) { f32x4 v0 = acc[ai][bj][m][0], v1 = acc[ai][bj][m][1];
;                     if (scale) { v0 *= *(const f32x4*)(scale + col0 + bj * HALF); v1 *= *(const f32x4*)(scale + col0 + bj * HALF + 4); }
;                     u32x4 w; w.x = pk2(v0[0], v0[1]); w.y = pk2(v0[2], v0[3]); w.z = pk2(v1[0], v1[1]); w.w = pk2(v1[2], v1[3]);
;                     *(u32x4*)(rowp + bj * HALF) = w; }
;                 if (scale) asm volatile("" ::: "memory"); }
.LBB0_1199:
	s_and_b64 vcc, exec, s[8:9]
	s_cbranch_vccnz .LBB0_1201
	s_nop 1
	v_mov_b32_e32 v64, v186
	v_mov_b32_e32 v65, v187
	v_mov_b32_e32 v66, v188
	v_mov_b32_e32 v67, v189
	s_nop 1
	v_mov_b32_e32 v68, v190
	v_mov_b32_e32 v69, v191
	v_mov_b32_e32 v70, v192
	v_mov_b32_e32 v71, v193
	v_pk_mul_f32 v[62:63], v[62:63], v[66:67]
	v_pk_mul_f32 v[60:61], v[60:61], v[64:65]
	v_pk_mul_f32 v[58:59], v[58:59], v[70:71]
	v_pk_mul_f32 v[56:57], v[56:57], v[68:69]
.LBB0_1201:
	v_lshlrev_b64 v[64:65], 12, v[146:147]
	v_lshl_add_u64 v[64:65], s[12:13], 0, v[64:65]
	v_lshl_add_u64 v[64:65], v[144:145], 1, v[64:65]
	v_lshl_add_u64 v[64:65], v[64:65], 0, s[18:19]
	v_cvt_pk_bf16_f32 v60, v60, v61
	v_cvt_pk_bf16_f32 v61, v62, v63
	v_cvt_pk_bf16_f32 v62, v56, v57
	v_cvt_pk_bf16_f32 v63, v58, v59
	s_and_b64 vcc, exec, s[8:9]
	global_store_dwordx4 v[64:65], v[60:63], off offset:2048
	s_cbranch_vccnz .LBB0_1203
	s_nop 1
	v_mov_b32_e32 v56, v194
	v_mov_b32_e32 v57, v195
	v_mov_b32_e32 v58, v196
	v_mov_b32_e32 v59, v197
	s_nop 1
	v_mov_b32_e32 v60, v198
	v_mov_b32_e32 v61, v199
	v_mov_b32_e32 v62, v200
	v_mov_b32_e32 v63, v201
	v_pk_mul_f32 v[54:55], v[54:55], v[58:59]
	v_pk_mul_f32 v[52:53], v[52:53], v[56:57]
	v_pk_mul_f32 v[50:51], v[50:51], v[62:63]
	v_pk_mul_f32 v[48:49], v[48:49], v[60:61]

; __device__ __forceinline__ unsigned pk2(float lo, float hi) { const f32x2 v = {lo, hi}; const bf16x2_hw b = __builtin_convertvector(v, bf16x2_hw); return __builtin_bit_cast(unsigned, b); }
;     __device__ __forceinline__ void operator()(const Acc& acc, const Unit& u, int wr, int wc, int fr, int fq) const {
;     ...
;             for (int m = 0; m < 4; ++m) { bf16_t* rowp = O + (size_t)(row0 + ai * HALF + m * 16) * ldc + col_off + col0;
; #pragma unroll
;                 for (int bj = 0; bj < 2; ++bj) { f32x4 v0 = acc[ai][bj][m][0], v1 = acc[ai][bj][m][1];
;                     if (scale) { v0 *= *(const f32x4*)(scale + col0 + bj * HALF); v1 *= *(const f32x4*)(scale + col0 + bj * HALF + 4); }
;                     u32x4 w; w.x = pk2(v0[0], v0[1]); w.y = pk2(v0[2], v0[3]); w.z = pk2(v1[0], v1[1]); w.w = pk2(v1[2], v1[3]);
;                     *(u32x4*)(rowp + bj * HALF) = w; }
;                 if (scale) asm volatile("" ::: "memory"); }
.LBB0_1205:
	s_and_b64 vcc, exec, s[8:9]
	s_cbranch_vccnz .LBB0_1207
	s_nop 1
	v_mov_b32_e32 v48, v186
	v_mov_b32_e32 v49, v187
	v_mov_b32_e32 v50, v188
	v_mov_b32_e32 v51, v189
	s_nop 1
	v_mov_b32_e32 v52, v190
	v_mov_b32_e32 v53, v191
	v_mov_b32_e32 v54, v192
	v_mov_b32_e32 v55, v193
	v_pk_mul_f32 v[46:47], v[46:47], v[50:51]
	v_pk_mul_f32 v[44:45], v[44:45], v[48:49]
	v_pk_mul_f32 v[42:43], v[42:43], v[54:55]
	v_pk_mul_f32 v[40:41], v[40:41], v[52:53]
.LBB0_1207:
	v_lshlrev_b64 v[48:49], 12, v[146:147]
	v_lshl_add_u64 v[48:49], s[12:13], 0, v[48:49]
	v_lshl_add_u64 v[48:49], v[144:145], 1, v[48:49]
	v_lshl_add_u64 v[48:49], v[48:49], 0, s[20:21]
	v_cvt_pk_bf16_f32 v44, v44, v45
	v_cvt_pk_bf16_f32 v45, v46, v47
	v_cvt_pk_bf16_f32 v46, v40, v41
	v_cvt_pk_bf16_f32 v47, v42, v43
	s_and_b64 vcc, exec, s[8:9]
	global_store_dwordx4 v[48:49], v[44:47], off offset:2048
	s_cbranch_vccnz .LBB0_1209
	s_nop 1
	v_mov_b32_e32 v40, v194
	v_mov_b32_e32 v41, v195
	v_mov_b32_e32 v42, v196
	v_mov_b32_e32 v43, v197
	s_nop 1
	v_mov_b32_e32 v44, v198
	v_mov_b32_e32 v45, v199
	v_mov_b32_e32 v46, v200
	v_mov_b32_e32 v47, v201
	v_pk_mul_f32 v[38:39], v[38:39], v[42:43]
	v_pk_mul_f32 v[36:37], v[36:37], v[40:41]
	v_pk_mul_f32 v[34:35], v[34:35], v[46:47]
	v_pk_mul_f32 v[32:33], v[32:33], v[44:45]

; __device__ __forceinline__ unsigned pk2(float lo, float hi) { const f32x2 v = {lo, hi}; const bf16x2_hw b = __builtin_convertvector(v, bf16x2_hw); return __builtin_bit_cast(unsigned, b); }
;     __device__ __forceinline__ void operator()(const Acc& acc, const Unit& u, int wr, int wc, int fr, int fq) const {
;     ...
;             for (int m = 0; m < 4; ++m) { bf16_t* rowp = O + (size_t)(row0 + ai * HALF + m * 16) * ldc + col_off + col0;
; #pragma unroll
;                 for (int bj = 0; bj < 2; ++bj) { f32x4 v0 = acc[ai][bj][m][0], v1 = acc[ai][bj][m][1];
;                     if (scale) { v0 *= *(const f32x4*)(scale + col0 + bj * HALF); v1 *= *(const f32x4*)(scale + col0 + bj * HALF + 4); }
;                     u32x4 w; w.x = pk2(v0[0], v0[1]); w.y = pk2(v0[2], v0[3]); w.z = pk2(v1[0], v1[1]); w.w = pk2(v1[2], v1[3]);
;                     *(u32x4*)(rowp + bj * HALF) = w; }
;                 if (scale) asm volatile("" ::: "memory"); }
.LBB0_1211:
	s_and_b64 vcc, exec, s[8:9]
	s_cbranch_vccnz .LBB0_1213
	s_nop 1
	v_mov_b32_e32 v32, v186
	v_mov_b32_e32 v33, v187
	v_mov_b32_e32 v34, v188
	v_mov_b32_e32 v35, v189
	s_nop 1
	v_mov_b32_e32 v36, v190
	v_mov_b32_e32 v37, v191
	v_mov_b32_e32 v38, v192
	v_mov_b32_e32 v39, v193
	v_pk_mul_f32 v[30:31], v[30:31], v[34:35]
	v_pk_mul_f32 v[28:29], v[28:29], v[32:33]
	v_pk_mul_f32 v[26:27], v[26:27], v[38:39]
	v_pk_mul_f32 v[24:25], v[24:25], v[36:37]
.LBB0_1213:
	v_lshlrev_b64 v[32:33], 12, v[146:147]
	v_lshl_add_u64 v[32:33], s[12:13], 0, v[32:33]
	v_lshl_add_u64 v[32:33], v[144:145], 1, v[32:33]
	v_lshl_add_u64 v[32:33], v[32:33], 0, s[22:23]
	v_cvt_pk_bf16_f32 v28, v28, v29
	v_cvt_pk_bf16_f32 v29, v30, v31
	v_cvt_pk_bf16_f32 v30, v24, v25
	v_cvt_pk_bf16_f32 v31, v26, v27
	s_and_b64 vcc, exec, s[8:9]
	global_store_dwordx4 v[32:33], v[28:31], off offset:2048
	s_cbranch_vccnz .LBB0_1215
	s_nop 1
	v_mov_b32_e32 v24, v194
	v_mov_b32_e32 v25, v195
	v_mov_b32_e32 v26, v196
	v_mov_b32_e32 v27, v197
	s_nop 1
	v_mov_b32_e32 v28, v198
	v_mov_b32_e32 v29, v199
	v_mov_b32_e32 v30, v200
	v_mov_b32_e32 v31, v201
	v_pk_mul_f32 v[22:23], v[22:23], v[26:27]
	v_pk_mul_f32 v[20:21], v[20:21], v[24:25]
	v_pk_mul_f32 v[18:19], v[18:19], v[30:31]
	v_pk_mul_f32 v[16:17], v[16:17], v[28:29]

; __device__ __forceinline__ unsigned pk2(float lo, float hi) { const f32x2 v = {lo, hi}; const bf16x2_hw b = __builtin_convertvector(v, bf16x2_hw); return __builtin_bit_cast(unsigned, b); }
;     __device__ __forceinline__ void operator()(const Acc& acc, const Unit& u, int wr, int wc, int fr, int fq) const {
;     ...
;             for (int m = 0; m < 4; ++m) { bf16_t* rowp = O + (size_t)(row0 + ai * HALF + m * 16) * ldc + col_off + col0;
; #pragma unroll
;                 for (int bj = 0; bj < 2; ++bj) { f32x4 v0 = acc[ai][bj][m][0], v1 = acc[ai][bj][m][1];
;                     if (scale) { v0 *= *(const f32x4*)(scale + col0 + bj * HALF); v1 *= *(const f32x4*)(scale + col0 + bj * HALF + 4); }
;                     u32x4 w; w.x = pk2(v0[0], v0[1]); w.y = pk2(v0[2], v0[3]); w.z = pk2(v1[0], v1[1]); w.w = pk2(v1[2], v1[3]);
;                     *(u32x4*)(rowp + bj * HALF) = w; }
;                 if (scale) asm volatile("" ::: "memory"); }
.LBB0_1217:
	s_and_b64 vcc, exec, s[8:9]
	s_cbranch_vccnz .LBB0_1219
	s_nop 1
	v_mov_b32_e32 v16, v186
	v_mov_b32_e32 v17, v187
	v_mov_b32_e32 v18, v188
	v_mov_b32_e32 v19, v189
	s_nop 1
	v_mov_b32_e32 v20, v190
	v_mov_b32_e32 v21, v191
	v_mov_b32_e32 v22, v192
	v_mov_b32_e32 v23, v193
	v_pk_mul_f32 v[14:15], v[14:15], v[18:19]
	v_pk_mul_f32 v[12:13], v[12:13], v[16:17]
	v_pk_mul_f32 v[10:11], v[10:11], v[22:23]
	v_pk_mul_f32 v[8:9], v[8:9], v[20:21]
.LBB0_1219:
	v_lshlrev_b64 v[16:17], 12, v[146:147]
	v_lshl_add_u64 v[16:17], s[12:13], 0, v[16:17]
	v_lshl_add_u64 v[16:17], v[144:145], 1, v[16:17]
	v_lshl_add_u64 v[16:17], v[16:17], 0, s[24:25]
	v_cvt_pk_bf16_f32 v12, v12, v13
	v_cvt_pk_bf16_f32 v13, v14, v15
	v_cvt_pk_bf16_f32 v14, v8, v9
	v_cvt_pk_bf16_f32 v15, v10, v11
	s_and_b64 vcc, exec, s[8:9]
	global_store_dwordx4 v[16:17], v[12:15], off offset:2048
	s_cbranch_vccnz .LBB0_1221
	s_nop 1
	v_mov_b32_e32 v8, v194
	v_mov_b32_e32 v9, v195
	v_mov_b32_e32 v10, v196
	v_mov_b32_e32 v11, v197
	s_nop 1
	v_mov_b32_e32 v12, v198
	v_mov_b32_e32 v13, v199
	v_mov_b32_e32 v14, v200
	v_mov_b32_e32 v15, v201
	v_pk_mul_f32 v[6:7], v[6:7], v[10:11]
	v_pk_mul_f32 v[4:5], v[4:5], v[8:9]
	v_pk_mul_f32 v[2:3], v[2:3], v[14:15]
	v_pk_mul_f32 v[0:1], v[0:1], v[12:13]
